# v17 with the mid-block s_setprio 0/1 flip pairs removed from the GEMM MFMA blocks (timing-only experiment)
# baseline (speedup 1.0000x reference)
; #define PG8_STAGE(bufoff, gbase, voff) do { _Pragma("unroll") for (int _i = 0; _i < 2; ++_i) \
;         __builtin_amdgcn_global_load_lds((const unsigned*)((const char*)(gbase) + (voff)[_i]), (PG8_LAS unsigned*)(lds + (bufoff) + ldsw + _i * 8192), 16, 0, 0); } while (0)
; #define PG8_LDA(dst, b, h) do { _Pragma("unroll") for (int m = 0; m < 4; ++m) _Pragma("unroll") for (int k = 0; k < 2; ++k) dst[m][k] = *(const PG8_LAS bf16x8*)(lds + PG8_SA(b, h) + aoff + m * 2048 + k * 1024); } while (0)
; #define PG8_LDB(dst, b, h) do { _Pragma("unroll") for (int n = 0; n < 2; ++n) _Pragma("unroll") for (int k = 0; k < 2; ++k) dst[n][k] = *(const PG8_LAS bf16x8*)(lds + PG8_SB(b, h) + boff + n * 2048 + k * 1024); } while (0)
; #define PG8_WAIT_V(n) asm volatile("s_waitcnt vmcnt(" #n ")" ::: "memory")
; #define PG8_WAIT_L(n) asm volatile("s_waitcnt lgkmcnt(" #n ")" ::: "memory")
; #define PG8_BAR __builtin_amdgcn_s_barrier()
; #define PG8_SCHED __builtin_amdgcn_sched_barrier(0)
; template <class Epi, class Sched, bool ALIGN_EPI = false, bool SP2 = false>
; __device__ __forceinline__ void gemm_phase(PG8_LAS unsigned char* lds, const Gemm g, const Sched& S, const Epi& E) {
;     ...
;         const bool has_next = S.next(ui + 1, nxt);
;         const char* nA = has_next ? (const char*)g.A + (size_t)nxt.pm * tstep : cA; const char* nB = has_next ? (const char*)g.Bt + (size_t)nxt.pn * tstep : cB;
;         for (int t = 0; t < nt; t += 2) {
;             const bool last = (t == nt - 2);
;             const char* a1 = cA + (size_t)(t + 1) * kstep;
;             const char* a2 = last ? nA : cA + (size_t)(t + 2) * kstep; const char* b2 = last ? nB : cB + (size_t)(t + 2) * kstep;
;             const char* a3 = a2 + kstep; const char* b3 = b2 + kstep;
;             if (last && has_next) S.a_ready(nxt);
;             if constexpr (SP2) {
;             PG8_LDB(B0, 0, 0); PG8_LDB(B1, 0, 1); PG8_SCHED; PG8_LDA(At, 0, 0); PG8_STAGE(PG8_SA(1, 1), a1 + hstep, voffA);
;             PG8_WAIT_V(8); PG8_WAIT_L(0); PG8_BAR; PG8_MMA(0, 0, At, B0); PG8_MMA(0, 1, At, B1); PG8_BAR; PG8_SCHED;
;             PG8_LDA(At, 0, 1); PG8_STAGE(PG8_SB(0, 0), b2, voffB); PG8_STAGE(PG8_SB(0, 1), b2 + hstep, voffB); PG8_STAGE(PG8_SA(0, 0), a2, voffA);
;             PG8_WAIT_V(8); PG8_WAIT_L(0); PG8_BAR; PG8_MMA(1, 0, At, B0); PG8_MMA(1, 1, At, B1); PG8_BAR; PG8_SCHED;
.LBB0_41:
	s_ashr_i32 s17, s16, 31
	s_lshl_b64 s[18:19], s[16:17], s28
	s_add_u32 s18, s26, s18
	s_addc_u32 s19, s27, s19
	s_and_b64 s[20:21], s[6:7], exec
	s_cselect_b32 s17, s19, s23
	s_cselect_b32 s42, s18, s22
	s_ashr_i32 s15, s14, 31
	s_lshl_b64 s[20:21], s[14:15], s28
	v_readlane_b32 s44, v251, 2
	v_readlane_b32 s45, v251, 3
	s_add_u32 s20, s44, s20
	s_addc_u32 s21, s45, s21
	s_and_b64 s[44:45], s[6:7], exec
	s_cselect_b32 s15, s21, s25
	s_cselect_b32 s43, s20, s24
	s_add_u32 s22, s22, 0x80
	s_addc_u32 s23, s23, 0
	s_add_u32 s44, s24, 0x100
	s_addc_u32 s45, s25, 0
	s_mov_b32 s24, 0
	s_waitcnt lgkmcnt(0)
	s_add_i32 s46, s24, 2
	s_add_u32 s47, s22, 0x80
	s_addc_u32 s25, s23, 0
	s_add_i32 s50, 0, 0x10000
	s_cmp_eq_u32 s37, s24
	s_cselect_b32 s25, s17, s25
	s_cselect_b32 s24, s42, s47
	s_cselect_b32 s49, s15, s45
	s_cselect_b32 s48, s43, s44
	s_add_i32 s47, 0, 0x14000
	v_add_u32_e32 v142, s50, v165
	v_add_u32_e32 v182, s47, v165
	ds_read_b128 v[130:133], v142
	ds_read_b128 v[134:137], v142 offset:1024
	ds_read_b128 v[138:141], v142 offset:2048
	ds_read_b128 v[142:145], v142 offset:3072
	ds_read_b128 v[146:149], v182
	ds_read_b128 v[150:153], v182 offset:1024
	ds_read_b128 v[154:157], v182 offset:2048
	ds_read_b128 v[182:185], v182 offset:3072
	v_lshl_add_u64 v[198:199], s[22:23], 0, v[178:179]
	s_add_i32 m0, s29, 0xc000
	ds_read_b128 v[186:189], v214
	ds_read_b128 v[190:193], v214 offset:1024
	ds_read_b128 v[194:197], v214 offset:2048
	ds_read_b128 v[216:219], v214 offset:3072
	ds_read_b128 v[220:223], v214 offset:4096
	ds_read_b128 v[224:227], v214 offset:5120
	ds_read_b128 v[228:231], v214 offset:6144
	ds_read_b128 v[232:235], v214 offset:7168
	global_load_lds_dwordx4 v[198:199], off
	v_lshl_add_u64 v[198:199], s[22:23], 0, v[180:181]
	s_add_i32 m0, s29, 0xe000
	s_nop 0
	global_load_lds_dwordx4 v[198:199], off
	s_waitcnt vmcnt(8)
	s_waitcnt lgkmcnt(0)
	s_barrier
	s_setprio 1
	s_waitcnt lgkmcnt(0)
	v_mfma_f32_16x16x32_bf16 v[126:129], v[130:133], v[186:189], 0
	v_mfma_f32_16x16x32_bf16 v[122:125], v[138:141], v[186:189], 0
	v_mfma_f32_16x16x32_bf16 v[110:113], v[130:133], v[194:197], 0
	v_mfma_f32_16x16x32_bf16 v[106:109], v[138:141], v[194:197], 0
	v_mfma_f32_16x16x32_bf16 v[94:97], v[130:133], v[220:223], 0
	v_mfma_f32_16x16x32_bf16 v[90:93], v[138:141], v[220:223], 0
	v_mfma_f32_16x16x32_bf16 v[78:81], v[130:133], v[228:231], 0
	v_mfma_f32_16x16x32_bf16 v[74:77], v[138:141], v[228:231], 0
	v_mfma_f32_16x16x32_bf16 v[126:129], v[134:137], v[190:193], v[126:129]
	v_mfma_f32_16x16x32_bf16 v[122:125], v[142:145], v[190:193], v[122:125]
	v_mfma_f32_16x16x32_bf16 v[110:113], v[134:137], v[216:219], v[110:113]
	v_mfma_f32_16x16x32_bf16 v[106:109], v[142:145], v[216:219], v[106:109]
	v_mfma_f32_16x16x32_bf16 v[94:97], v[134:137], v[224:227], v[94:97]
	v_mfma_f32_16x16x32_bf16 v[90:93], v[142:145], v[224:227], v[90:93]
	v_mfma_f32_16x16x32_bf16 v[78:81], v[134:137], v[232:235], v[78:81]
	v_mfma_f32_16x16x32_bf16 v[74:77], v[142:145], v[232:235], v[74:77]
	v_mfma_f32_16x16x32_bf16 v[118:121], v[146:149], v[186:189], 0
	v_mfma_f32_16x16x32_bf16 v[114:117], v[154:157], v[186:189], 0
	v_mfma_f32_16x16x32_bf16 v[102:105], v[146:149], v[194:197], 0
	v_mfma_f32_16x16x32_bf16 v[98:101], v[154:157], v[194:197], 0
	v_mfma_f32_16x16x32_bf16 v[86:89], v[146:149], v[220:223], 0
	v_mfma_f32_16x16x32_bf16 v[82:85], v[154:157], v[220:223], 0
	v_mfma_f32_16x16x32_bf16 v[70:73], v[146:149], v[228:231], 0
	v_mfma_f32_16x16x32_bf16 v[66:69], v[154:157], v[228:231], 0
	v_mfma_f32_16x16x32_bf16 v[118:121], v[150:153], v[190:193], v[118:121]
	v_mfma_f32_16x16x32_bf16 v[114:117], v[182:185], v[190:193], v[114:117]
	v_mfma_f32_16x16x32_bf16 v[102:105], v[150:153], v[216:219], v[102:105]
	v_mfma_f32_16x16x32_bf16 v[98:101], v[182:185], v[216:219], v[98:101]
	v_mfma_f32_16x16x32_bf16 v[86:89], v[150:153], v[224:227], v[86:89]
	v_mfma_f32_16x16x32_bf16 v[82:85], v[182:185], v[224:227], v[82:85]
	v_mfma_f32_16x16x32_bf16 v[70:73], v[150:153], v[232:235], v[70:73]
	v_mfma_f32_16x16x32_bf16 v[66:69], v[182:185], v[232:235], v[66:69]
	s_setprio 0
	s_barrier
	s_add_i32 s50, s50, s2
	v_lshl_add_u64 v[198:199], s[48:49], 0, v[0:1]
	s_mov_b32 m0, s50
	ds_read_b128 v[186:189], v214 offset:16384
	ds_read_b128 v[190:193], v214 offset:17408
	ds_read_b128 v[194:197], v214 offset:18432
	ds_read_b128 v[216:219], v214 offset:19456
	ds_read_b128 v[220:223], v214 offset:20480
	ds_read_b128 v[224:227], v214 offset:21504
	ds_read_b128 v[228:231], v214 offset:22528
	ds_read_b128 v[232:235], v214 offset:23552
	global_load_lds_dwordx4 v[198:199], off
	s_add_i32 m0, s50, 0x2000
	v_lshl_add_u64 v[236:237], s[48:49], 0, v[172:173]
	s_add_u32 s48, s48, s8
	s_addc_u32 s49, s49, 0
	s_add_i32 s47, s47, s2
	global_load_lds_dwordx4 v[236:237], off
	v_lshl_add_u64 v[238:239], s[48:49], 0, v[0:1]
	s_mov_b32 m0, s47
	v_lshl_add_u64 v[240:241], s[48:49], 0, v[172:173]
	global_load_lds_dwordx4 v[238:239], off
	s_add_i32 m0, s47, 0x2000
	v_lshl_add_u64 v[242:243], s[24:25], 0, v[176:177]
	global_load_lds_dwordx4 v[240:241], off
	s_mov_b32 m0, s29
	v_lshl_add_u64 v[244:245], s[24:25], 0, v[174:175]
	global_load_lds_dwordx4 v[242:243], off
	s_mov_b32 m0, s30
	s_nop 0
	global_load_lds_dwordx4 v[244:245], off
	s_waitcnt vmcnt(8)
	s_waitcnt lgkmcnt(0)
	s_barrier
; #define PG8_STAGE(bufoff, gbase, voff) do { _Pragma("unroll") for (int _i = 0; _i < 2; ++_i) \
;         __builtin_amdgcn_global_load_lds((const unsigned*)((const char*)(gbase) + (voff)[_i]), (PG8_LAS unsigned*)(lds + (bufoff) + ldsw + _i * 8192), 16, 0, 0); } while (0)
; #define PG8_LDA(dst, b, h) do { _Pragma("unroll") for (int m = 0; m < 4; ++m) _Pragma("unroll") for (int k = 0; k < 2; ++k) dst[m][k] = *(const PG8_LAS bf16x8*)(lds + PG8_SA(b, h) + aoff + m * 2048 + k * 1024); } while (0)
; #define PG8_LDB(dst, b, h) do { _Pragma("unroll") for (int n = 0; n < 2; ++n) _Pragma("unroll") for (int k = 0; k < 2; ++k) dst[n][k] = *(const PG8_LAS bf16x8*)(lds + PG8_SB(b, h) + boff + n * 2048 + k * 1024); } while (0)
; #define PG8_MMA(ai, bj, At, Bt) do { __builtin_amdgcn_s_setprio(1); _Pragma("unroll") for (int m = 0; m < 4; ++m) _Pragma("unroll") for (int n = 0; n < 2; ++n) _Pragma("unroll") for (int k = 0; k < 2; ++k) \
;         acc[ai][bj][m][n] = __builtin_amdgcn_mfma_f32_16x16x32_bf16(Bt[n][k], At[m][k], acc[ai][bj][m][n], 0, 0, 0); __builtin_amdgcn_s_setprio(0); } while (0)
; #define PG8_WAIT_V(n) asm volatile("s_waitcnt vmcnt(" #n ")" ::: "memory")
; #define PG8_WAIT_L(n) asm volatile("s_waitcnt lgkmcnt(" #n ")" ::: "memory")
; #define PG8_BAR __builtin_amdgcn_s_barrier()
; #define PG8_SCHED __builtin_amdgcn_sched_barrier(0)
; template <class Epi, class Sched, bool ALIGN_EPI = false, bool SP2 = false>
; __device__ __forceinline__ void gemm_phase(PG8_LAS unsigned char* lds, const Gemm g, const Sched& S, const Epi& E) {
;     ...
;             PG8_WAIT_V(8); PG8_WAIT_L(0); PG8_BAR; PG8_MMA(1, 0, At, B0); PG8_MMA(1, 1, At, B1); PG8_BAR; PG8_SCHED;
;             PG8_LDB(B0, 1, 0); PG8_LDB(B1, 1, 1); PG8_SCHED; PG8_LDA(At, 1, 0); PG8_STAGE(PG8_SA(0, 1), a2 + hstep, voffA);
;             PG8_WAIT_V(8); PG8_WAIT_L(0); PG8_BAR; PG8_MMA(0, 0, At, B0); PG8_MMA(0, 1, At, B1); PG8_BAR; PG8_SCHED;
	s_setprio 1
	s_waitcnt lgkmcnt(0)
	v_mfma_f32_16x16x32_bf16 v[62:65], v[130:133], v[186:189], 0
	v_mfma_f32_16x16x32_bf16 v[58:61], v[138:141], v[186:189], 0
	v_mfma_f32_16x16x32_bf16 v[46:49], v[130:133], v[194:197], 0
	v_mfma_f32_16x16x32_bf16 v[42:45], v[138:141], v[194:197], 0
	v_mfma_f32_16x16x32_bf16 v[30:33], v[130:133], v[220:223], 0
	v_mfma_f32_16x16x32_bf16 v[26:29], v[138:141], v[220:223], 0
	v_mfma_f32_16x16x32_bf16 v[14:17], v[130:133], v[228:231], 0
	v_mfma_f32_16x16x32_bf16 v[10:13], v[138:141], v[228:231], 0
	v_mfma_f32_16x16x32_bf16 v[62:65], v[134:137], v[190:193], v[62:65]
	v_mfma_f32_16x16x32_bf16 v[58:61], v[142:145], v[190:193], v[58:61]
	v_mfma_f32_16x16x32_bf16 v[46:49], v[134:137], v[216:219], v[46:49]
	v_mfma_f32_16x16x32_bf16 v[42:45], v[142:145], v[216:219], v[42:45]
	v_mfma_f32_16x16x32_bf16 v[30:33], v[134:137], v[224:227], v[30:33]
	v_mfma_f32_16x16x32_bf16 v[26:29], v[142:145], v[224:227], v[26:29]
	v_mfma_f32_16x16x32_bf16 v[14:17], v[134:137], v[232:235], v[14:17]
	v_mfma_f32_16x16x32_bf16 v[10:13], v[142:145], v[232:235], v[10:13]
	v_mfma_f32_16x16x32_bf16 v[54:57], v[146:149], v[186:189], 0
	v_mfma_f32_16x16x32_bf16 v[50:53], v[154:157], v[186:189], 0
	v_mfma_f32_16x16x32_bf16 v[38:41], v[146:149], v[194:197], 0
	v_mfma_f32_16x16x32_bf16 v[34:37], v[154:157], v[194:197], 0
	v_mfma_f32_16x16x32_bf16 v[22:25], v[146:149], v[220:223], 0
	v_mfma_f32_16x16x32_bf16 v[18:21], v[154:157], v[220:223], 0
	v_mfma_f32_16x16x32_bf16 v[6:9], v[146:149], v[228:231], 0
	v_mfma_f32_16x16x32_bf16 v[2:5], v[154:157], v[228:231], 0
	v_mfma_f32_16x16x32_bf16 v[54:57], v[150:153], v[190:193], v[54:57]
	v_mfma_f32_16x16x32_bf16 v[50:53], v[182:185], v[190:193], v[50:53]
	v_mfma_f32_16x16x32_bf16 v[38:41], v[150:153], v[216:219], v[38:41]
	v_mfma_f32_16x16x32_bf16 v[34:37], v[182:185], v[216:219], v[34:37]
	v_mfma_f32_16x16x32_bf16 v[22:25], v[150:153], v[224:227], v[22:25]
	v_mfma_f32_16x16x32_bf16 v[18:21], v[182:185], v[224:227], v[18:21]
	v_mfma_f32_16x16x32_bf16 v[6:9], v[150:153], v[232:235], v[6:9]
	v_mfma_f32_16x16x32_bf16 v[2:5], v[182:185], v[232:235], v[2:5]
	s_setprio 0
	s_barrier
	s_add_i32 s47, 0, 0x18000
	s_add_i32 s48, 0, 0x1c000
	v_add_u32_e32 v142, s47, v165
	v_add_u32_e32 v182, s48, v165
	ds_read_b128 v[130:133], v142
	ds_read_b128 v[134:137], v142 offset:1024
	ds_read_b128 v[138:141], v142 offset:2048
	ds_read_b128 v[142:145], v142 offset:3072
	ds_read_b128 v[146:149], v182
	ds_read_b128 v[150:153], v182 offset:1024
	ds_read_b128 v[154:157], v182 offset:2048
	ds_read_b128 v[182:185], v182 offset:3072
	s_add_u32 s24, s24, s8
	s_addc_u32 s25, s25, 0
	s_mov_b32 m0, s31
	v_lshl_add_u64 v[246:247], s[24:25], 0, v[176:177]
	ds_read_b128 v[186:189], v214 offset:32768
	ds_read_b128 v[190:193], v214 offset:33792
	ds_read_b128 v[194:197], v214 offset:34816
	ds_read_b128 v[216:219], v214 offset:35840
	ds_read_b128 v[220:223], v214 offset:36864
	ds_read_b128 v[224:227], v214 offset:37888
	ds_read_b128 v[228:231], v214 offset:38912
	ds_read_b128 v[232:235], v214 offset:39936
	global_load_lds_dwordx4 v[246:247], off
	v_lshl_add_u64 v[246:247], s[24:25], 0, v[174:175]
	s_mov_b32 m0, s34
	s_nop 0
	global_load_lds_dwordx4 v[246:247], off
	s_waitcnt vmcnt(8)
	s_waitcnt lgkmcnt(0)
	s_barrier
	s_setprio 1
	s_waitcnt lgkmcnt(0)
	v_mfma_f32_16x16x32_bf16 v[126:129], v[130:133], v[186:189], v[126:129]
	v_mfma_f32_16x16x32_bf16 v[122:125], v[138:141], v[186:189], v[122:125]
	v_mfma_f32_16x16x32_bf16 v[110:113], v[130:133], v[194:197], v[110:113]
	v_mfma_f32_16x16x32_bf16 v[106:109], v[138:141], v[194:197], v[106:109]
	v_mfma_f32_16x16x32_bf16 v[94:97], v[130:133], v[220:223], v[94:97]
	v_mfma_f32_16x16x32_bf16 v[90:93], v[138:141], v[220:223], v[90:93]
	v_mfma_f32_16x16x32_bf16 v[78:81], v[130:133], v[228:231], v[78:81]
	v_mfma_f32_16x16x32_bf16 v[74:77], v[138:141], v[228:231], v[74:77]
	v_mfma_f32_16x16x32_bf16 v[126:129], v[134:137], v[190:193], v[126:129]
	v_mfma_f32_16x16x32_bf16 v[122:125], v[142:145], v[190:193], v[122:125]
	v_mfma_f32_16x16x32_bf16 v[110:113], v[134:137], v[216:219], v[110:113]
	v_mfma_f32_16x16x32_bf16 v[106:109], v[142:145], v[216:219], v[106:109]
	v_mfma_f32_16x16x32_bf16 v[94:97], v[134:137], v[224:227], v[94:97]
	v_mfma_f32_16x16x32_bf16 v[90:93], v[142:145], v[224:227], v[90:93]
	v_mfma_f32_16x16x32_bf16 v[78:81], v[134:137], v[232:235], v[78:81]
	v_mfma_f32_16x16x32_bf16 v[74:77], v[142:145], v[232:235], v[74:77]
	v_mfma_f32_16x16x32_bf16 v[118:121], v[146:149], v[186:189], v[118:121]
	v_mfma_f32_16x16x32_bf16 v[114:117], v[154:157], v[186:189], v[114:117]
	v_mfma_f32_16x16x32_bf16 v[102:105], v[146:149], v[194:197], v[102:105]
	v_mfma_f32_16x16x32_bf16 v[98:101], v[154:157], v[194:197], v[98:101]
	v_mfma_f32_16x16x32_bf16 v[86:89], v[146:149], v[220:223], v[86:89]
	v_mfma_f32_16x16x32_bf16 v[82:85], v[154:157], v[220:223], v[82:85]
	v_mfma_f32_16x16x32_bf16 v[70:73], v[146:149], v[228:231], v[70:73]
	v_mfma_f32_16x16x32_bf16 v[66:69], v[154:157], v[228:231], v[66:69]
	v_mfma_f32_16x16x32_bf16 v[118:121], v[150:153], v[190:193], v[118:121]
	v_mfma_f32_16x16x32_bf16 v[114:117], v[182:185], v[190:193], v[114:117]
	v_mfma_f32_16x16x32_bf16 v[102:105], v[150:153], v[216:219], v[102:105]
	v_mfma_f32_16x16x32_bf16 v[98:101], v[182:185], v[216:219], v[98:101]
	v_mfma_f32_16x16x32_bf16 v[86:89], v[150:153], v[224:227], v[86:89]
	v_mfma_f32_16x16x32_bf16 v[82:85], v[182:185], v[224:227], v[82:85]
	v_mfma_f32_16x16x32_bf16 v[70:73], v[150:153], v[232:235], v[70:73]
	v_mfma_f32_16x16x32_bf16 v[66:69], v[182:185], v[232:235], v[66:69]
	s_setprio 0
	s_barrier
; #define PG8_STAGE(bufoff, gbase, voff) do { _Pragma("unroll") for (int _i = 0; _i < 2; ++_i) \
;         __builtin_amdgcn_global_load_lds((const unsigned*)((const char*)(gbase) + (voff)[_i]), (PG8_LAS unsigned*)(lds + (bufoff) + ldsw + _i * 8192), 16, 0, 0); } while (0)
; #define PG8_LDA(dst, b, h) do { _Pragma("unroll") for (int m = 0; m < 4; ++m) _Pragma("unroll") for (int k = 0; k < 2; ++k) dst[m][k] = *(const PG8_LAS bf16x8*)(lds + PG8_SA(b, h) + aoff + m * 2048 + k * 1024); } while (0)
; #define PG8_LDB(dst, b, h) do { _Pragma("unroll") for (int n = 0; n < 2; ++n) _Pragma("unroll") for (int k = 0; k < 2; ++k) dst[n][k] = *(const PG8_LAS bf16x8*)(lds + PG8_SB(b, h) + boff + n * 2048 + k * 1024); } while (0)
; template <class Epi, class Sched, bool ALIGN_EPI = false, bool SP2 = false>
; __device__ __forceinline__ void gemm_phase(PG8_LAS unsigned char* lds, const Gemm g, const Sched& S, const Epi& E) {
;     ...
;         for (int t = 0; t < nt; t += 2) {
;             const bool last = (t == nt - 2);
;             const char* a1 = cA + (size_t)(t + 1) * kstep;
;             const char* a2 = last ? nA : cA + (size_t)(t + 2) * kstep; const char* b2 = last ? nB : cB + (size_t)(t + 2) * kstep;
;             const char* a3 = a2 + kstep; const char* b3 = b2 + kstep;
;             if (last && has_next) S.a_ready(nxt);
;             if constexpr (SP2) {
;             PG8_LDB(B0, 0, 0); PG8_LDB(B1, 0, 1); PG8_SCHED; PG8_LDA(At, 0, 0); PG8_STAGE(PG8_SA(1, 1), a1 + hstep, voffA);
;             PG8_WAIT_V(8); PG8_WAIT_L(0); PG8_BAR; PG8_MMA(0, 0, At, B0); PG8_MMA(0, 1, At, B1); PG8_BAR; PG8_SCHED;
;             PG8_LDA(At, 0, 1); PG8_STAGE(PG8_SB(0, 0), b2, voffB); PG8_STAGE(PG8_SB(0, 1), b2 + hstep, voffB); PG8_STAGE(PG8_SA(0, 0), a2, voffA);
;             PG8_WAIT_V(8); PG8_WAIT_L(0); PG8_BAR; PG8_MMA(1, 0, At, B0); PG8_MMA(1, 1, At, B1); PG8_BAR; PG8_SCHED;
;             PG8_LDB(B0, 1, 0); PG8_LDB(B1, 1, 1); PG8_SCHED; PG8_LDA(At, 1, 0); PG8_STAGE(PG8_SA(0, 1), a2 + hstep, voffA);
;             PG8_WAIT_V(8); PG8_WAIT_L(0); PG8_BAR; PG8_MMA(0, 0, At, B0); PG8_MMA(0, 1, At, B1); PG8_BAR; PG8_SCHED;
;             PG8_LDA(At, 1, 1); PG8_STAGE(PG8_SB(1, 0), b3, voffB); PG8_STAGE(PG8_SB(1, 1), b3 + hstep, voffB); PG8_STAGE(PG8_SA(1, 0), a3, voffA);
;             PG8_WAIT_V(8); PG8_WAIT_L(0); PG8_BAR; PG8_MMA(1, 0, At, B0); PG8_MMA(1, 1, At, B1); PG8_BAR; PG8_SCHED;
	s_add_i32 s24, s47, s2
	v_lshl_add_u64 v[198:199], v[198:199], 0, s[90:91]
	s_mov_b32 m0, s24
	ds_read_b128 v[186:189], v214 offset:49152
	ds_read_b128 v[190:193], v214 offset:50176
	ds_read_b128 v[194:197], v214 offset:51200
	ds_read_b128 v[216:219], v214 offset:52224
	ds_read_b128 v[220:223], v214 offset:53248
	ds_read_b128 v[224:227], v214 offset:54272
	ds_read_b128 v[228:231], v214 offset:55296
	ds_read_b128 v[232:235], v214 offset:56320
	global_load_lds_dwordx4 v[198:199], off
	v_lshl_add_u64 v[198:199], v[236:237], 0, s[90:91]
	s_add_i32 m0, s24, 0x2000
	s_add_i32 s24, s48, s2
	global_load_lds_dwordx4 v[198:199], off
	v_lshl_add_u64 v[198:199], v[238:239], 0, s[90:91]
	s_mov_b32 m0, s24
	s_nop 0
	global_load_lds_dwordx4 v[198:199], off
	v_lshl_add_u64 v[198:199], v[240:241], 0, s[90:91]
	s_add_i32 m0, s24, 0x2000
	s_nop 0
	global_load_lds_dwordx4 v[198:199], off
	v_lshl_add_u64 v[198:199], v[242:243], 0, s[90:91]
	s_mov_b32 m0, s38
	s_nop 0
	global_load_lds_dwordx4 v[198:199], off
	v_lshl_add_u64 v[198:199], v[244:245], 0, s[90:91]
	s_mov_b32 m0, s39
	s_nop 0
	global_load_lds_dwordx4 v[198:199], off
	s_waitcnt vmcnt(8)
	s_waitcnt lgkmcnt(0)
	s_barrier
	s_setprio 1
	s_waitcnt lgkmcnt(0)
	v_mfma_f32_16x16x32_bf16 v[62:65], v[130:133], v[186:189], v[62:65]
	v_mfma_f32_16x16x32_bf16 v[58:61], v[138:141], v[186:189], v[58:61]
	v_mfma_f32_16x16x32_bf16 v[46:49], v[130:133], v[194:197], v[46:49]
	v_mfma_f32_16x16x32_bf16 v[42:45], v[138:141], v[194:197], v[42:45]
	v_mfma_f32_16x16x32_bf16 v[30:33], v[130:133], v[220:223], v[30:33]
	v_mfma_f32_16x16x32_bf16 v[26:29], v[138:141], v[220:223], v[26:29]
	v_mfma_f32_16x16x32_bf16 v[14:17], v[130:133], v[228:231], v[14:17]
	v_mfma_f32_16x16x32_bf16 v[10:13], v[138:141], v[228:231], v[10:13]
	v_mfma_f32_16x16x32_bf16 v[62:65], v[134:137], v[190:193], v[62:65]
	v_mfma_f32_16x16x32_bf16 v[58:61], v[142:145], v[190:193], v[58:61]
	v_mfma_f32_16x16x32_bf16 v[46:49], v[134:137], v[216:219], v[46:49]
	v_mfma_f32_16x16x32_bf16 v[42:45], v[142:145], v[216:219], v[42:45]
	v_mfma_f32_16x16x32_bf16 v[30:33], v[134:137], v[224:227], v[30:33]
	v_mfma_f32_16x16x32_bf16 v[26:29], v[142:145], v[224:227], v[26:29]
	v_mfma_f32_16x16x32_bf16 v[14:17], v[134:137], v[232:235], v[14:17]
	v_mfma_f32_16x16x32_bf16 v[10:13], v[142:145], v[232:235], v[10:13]
	v_mfma_f32_16x16x32_bf16 v[54:57], v[146:149], v[186:189], v[54:57]
	v_mfma_f32_16x16x32_bf16 v[50:53], v[154:157], v[186:189], v[50:53]
	v_mfma_f32_16x16x32_bf16 v[38:41], v[146:149], v[194:197], v[38:41]
	v_mfma_f32_16x16x32_bf16 v[34:37], v[154:157], v[194:197], v[34:37]
	v_mfma_f32_16x16x32_bf16 v[22:25], v[146:149], v[220:223], v[22:25]
	v_mfma_f32_16x16x32_bf16 v[18:21], v[154:157], v[220:223], v[18:21]
	v_mfma_f32_16x16x32_bf16 v[6:9], v[146:149], v[228:231], v[6:9]
	v_mfma_f32_16x16x32_bf16 v[2:5], v[154:157], v[228:231], v[2:5]
	v_mfma_f32_16x16x32_bf16 v[54:57], v[150:153], v[190:193], v[54:57]
	v_mfma_f32_16x16x32_bf16 v[50:53], v[182:185], v[190:193], v[50:53]
	v_mfma_f32_16x16x32_bf16 v[38:41], v[150:153], v[216:219], v[38:41]
	v_mfma_f32_16x16x32_bf16 v[34:37], v[182:185], v[216:219], v[34:37]
	v_mfma_f32_16x16x32_bf16 v[22:25], v[150:153], v[224:227], v[22:25]
	v_mfma_f32_16x16x32_bf16 v[18:21], v[182:185], v[224:227], v[18:21]
	v_mfma_f32_16x16x32_bf16 v[6:9], v[150:153], v[232:235], v[6:9]
	v_mfma_f32_16x16x32_bf16 v[2:5], v[182:185], v[232:235], v[2:5]
	s_setprio 0
	s_barrier
	s_add_u32 s22, s22, 0x100
	s_addc_u32 s23, s23, 0
	s_add_u32 s44, s44, 0x100
	s_addc_u32 s45, s45, 0
	s_mov_b32 s24, s46
.LBB0_42:
	s_add_i32 s46, s24, 2
	s_add_u32 s47, s22, 0x80
	s_addc_u32 s25, s23, 0
	s_add_i32 s50, 0, 0x10000
	s_cmp_eq_u32 s37, s24
	s_cselect_b32 s25, s17, s25
	s_cselect_b32 s24, s42, s47
	s_cselect_b32 s49, s15, s45
	s_cselect_b32 s48, s43, s44
	s_add_i32 s47, 0, 0x14000
	v_add_u32_e32 v142, s50, v165
	v_add_u32_e32 v182, s47, v165
	ds_read_b128 v[130:133], v142
	ds_read_b128 v[134:137], v142 offset:1024
	ds_read_b128 v[138:141], v142 offset:2048
	ds_read_b128 v[142:145], v142 offset:3072
	ds_read_b128 v[146:149], v182
	ds_read_b128 v[150:153], v182 offset:1024
	ds_read_b128 v[154:157], v182 offset:2048
	ds_read_b128 v[182:185], v182 offset:3072
	v_lshl_add_u64 v[198:199], s[22:23], 0, v[178:179]
	s_add_i32 m0, s29, 0xc000
	ds_read_b128 v[186:189], v214
	ds_read_b128 v[190:193], v214 offset:1024
	ds_read_b128 v[194:197], v214 offset:2048
	ds_read_b128 v[216:219], v214 offset:3072
	ds_read_b128 v[220:223], v214 offset:4096
	ds_read_b128 v[224:227], v214 offset:5120
	ds_read_b128 v[228:231], v214 offset:6144
	ds_read_b128 v[232:235], v214 offset:7168
	global_load_lds_dwordx4 v[198:199], off
	v_lshl_add_u64 v[198:199], s[22:23], 0, v[180:181]
	s_add_i32 m0, s29, 0xe000
	s_nop 0
	global_load_lds_dwordx4 v[198:199], off
	s_waitcnt vmcnt(8)
	s_waitcnt lgkmcnt(0)
	s_barrier
; #define PG8_STAGE(bufoff, gbase, voff) do { _Pragma("unroll") for (int _i = 0; _i < 2; ++_i) \
;         __builtin_amdgcn_global_load_lds((const unsigned*)((const char*)(gbase) + (voff)[_i]), (PG8_LAS unsigned*)(lds + (bufoff) + ldsw + _i * 8192), 16, 0, 0); } while (0)
; #define PG8_LDA(dst, b, h) do { _Pragma("unroll") for (int m = 0; m < 4; ++m) _Pragma("unroll") for (int k = 0; k < 2; ++k) dst[m][k] = *(const PG8_LAS bf16x8*)(lds + PG8_SA(b, h) + aoff + m * 2048 + k * 1024); } while (0)
; #define PG8_MMA(ai, bj, At, Bt) do { __builtin_amdgcn_s_setprio(1); _Pragma("unroll") for (int m = 0; m < 4; ++m) _Pragma("unroll") for (int n = 0; n < 2; ++n) _Pragma("unroll") for (int k = 0; k < 2; ++k) \
;         acc[ai][bj][m][n] = __builtin_amdgcn_mfma_f32_16x16x32_bf16(Bt[n][k], At[m][k], acc[ai][bj][m][n], 0, 0, 0); __builtin_amdgcn_s_setprio(0); } while (0)
; #define PG8_WAIT_V(n) asm volatile("s_waitcnt vmcnt(" #n ")" ::: "memory")
; #define PG8_WAIT_L(n) asm volatile("s_waitcnt lgkmcnt(" #n ")" ::: "memory")
; #define PG8_BAR __builtin_amdgcn_s_barrier()
; #define PG8_SCHED __builtin_amdgcn_sched_barrier(0)
; template <class Epi, class Sched, bool ALIGN_EPI = false, bool SP2 = false>
; __device__ __forceinline__ void gemm_phase(PG8_LAS unsigned char* lds, const Gemm g, const Sched& S, const Epi& E) {
;     ...
;             PG8_WAIT_V(8); PG8_WAIT_L(0); PG8_BAR; PG8_MMA(0, 0, At, B0); PG8_MMA(0, 1, At, B1); PG8_BAR; PG8_SCHED;
;             PG8_LDA(At, 0, 1); PG8_STAGE(PG8_SB(0, 0), b2, voffB); PG8_STAGE(PG8_SB(0, 1), b2 + hstep, voffB); PG8_STAGE(PG8_SA(0, 0), a2, voffA);
;             PG8_WAIT_V(8); PG8_WAIT_L(0); PG8_BAR; PG8_MMA(1, 0, At, B0); PG8_MMA(1, 1, At, B1); PG8_BAR; PG8_SCHED;
	s_setprio 1
	s_waitcnt lgkmcnt(0)
	v_mfma_f32_16x16x32_bf16 v[126:129], v[130:133], v[186:189], v[126:129]
	v_mfma_f32_16x16x32_bf16 v[122:125], v[138:141], v[186:189], v[122:125]
	v_mfma_f32_16x16x32_bf16 v[110:113], v[130:133], v[194:197], v[110:113]
	v_mfma_f32_16x16x32_bf16 v[106:109], v[138:141], v[194:197], v[106:109]
	v_mfma_f32_16x16x32_bf16 v[94:97], v[130:133], v[220:223], v[94:97]
	v_mfma_f32_16x16x32_bf16 v[90:93], v[138:141], v[220:223], v[90:93]
	v_mfma_f32_16x16x32_bf16 v[78:81], v[130:133], v[228:231], v[78:81]
	v_mfma_f32_16x16x32_bf16 v[74:77], v[138:141], v[228:231], v[74:77]
	v_mfma_f32_16x16x32_bf16 v[126:129], v[134:137], v[190:193], v[126:129]
	v_mfma_f32_16x16x32_bf16 v[122:125], v[142:145], v[190:193], v[122:125]
	v_mfma_f32_16x16x32_bf16 v[110:113], v[134:137], v[216:219], v[110:113]
	v_mfma_f32_16x16x32_bf16 v[106:109], v[142:145], v[216:219], v[106:109]
	v_mfma_f32_16x16x32_bf16 v[94:97], v[134:137], v[224:227], v[94:97]
	v_mfma_f32_16x16x32_bf16 v[90:93], v[142:145], v[224:227], v[90:93]
	v_mfma_f32_16x16x32_bf16 v[78:81], v[134:137], v[232:235], v[78:81]
	v_mfma_f32_16x16x32_bf16 v[74:77], v[142:145], v[232:235], v[74:77]
	v_mfma_f32_16x16x32_bf16 v[118:121], v[146:149], v[186:189], v[118:121]
	v_mfma_f32_16x16x32_bf16 v[114:117], v[154:157], v[186:189], v[114:117]
	v_mfma_f32_16x16x32_bf16 v[102:105], v[146:149], v[194:197], v[102:105]
	v_mfma_f32_16x16x32_bf16 v[98:101], v[154:157], v[194:197], v[98:101]
	v_mfma_f32_16x16x32_bf16 v[86:89], v[146:149], v[220:223], v[86:89]
	v_mfma_f32_16x16x32_bf16 v[82:85], v[154:157], v[220:223], v[82:85]
	v_mfma_f32_16x16x32_bf16 v[70:73], v[146:149], v[228:231], v[70:73]
	v_mfma_f32_16x16x32_bf16 v[66:69], v[154:157], v[228:231], v[66:69]
	v_mfma_f32_16x16x32_bf16 v[118:121], v[150:153], v[190:193], v[118:121]
	v_mfma_f32_16x16x32_bf16 v[114:117], v[182:185], v[190:193], v[114:117]
	v_mfma_f32_16x16x32_bf16 v[102:105], v[150:153], v[216:219], v[102:105]
	v_mfma_f32_16x16x32_bf16 v[98:101], v[182:185], v[216:219], v[98:101]
	v_mfma_f32_16x16x32_bf16 v[86:89], v[150:153], v[224:227], v[86:89]
	v_mfma_f32_16x16x32_bf16 v[82:85], v[182:185], v[224:227], v[82:85]
	v_mfma_f32_16x16x32_bf16 v[70:73], v[150:153], v[232:235], v[70:73]
	v_mfma_f32_16x16x32_bf16 v[66:69], v[182:185], v[232:235], v[66:69]
	s_setprio 0
	s_barrier
	s_add_i32 s50, s50, s2
	v_lshl_add_u64 v[198:199], s[48:49], 0, v[0:1]
	s_mov_b32 m0, s50
	ds_read_b128 v[186:189], v214 offset:16384
	ds_read_b128 v[190:193], v214 offset:17408
	ds_read_b128 v[194:197], v214 offset:18432
	ds_read_b128 v[216:219], v214 offset:19456
	ds_read_b128 v[220:223], v214 offset:20480
	ds_read_b128 v[224:227], v214 offset:21504
	ds_read_b128 v[228:231], v214 offset:22528
	ds_read_b128 v[232:235], v214 offset:23552
	global_load_lds_dwordx4 v[198:199], off
	s_add_i32 m0, s50, 0x2000
	v_lshl_add_u64 v[236:237], s[48:49], 0, v[172:173]
	s_add_u32 s48, s48, s8
	s_addc_u32 s49, s49, 0
	s_add_i32 s47, s47, s2
	global_load_lds_dwordx4 v[236:237], off
	v_lshl_add_u64 v[238:239], s[48:49], 0, v[0:1]
	s_mov_b32 m0, s47
	v_lshl_add_u64 v[240:241], s[48:49], 0, v[172:173]
	global_load_lds_dwordx4 v[238:239], off
	s_add_i32 m0, s47, 0x2000
	v_lshl_add_u64 v[242:243], s[24:25], 0, v[176:177]
	global_load_lds_dwordx4 v[240:241], off
	s_mov_b32 m0, s29
	v_lshl_add_u64 v[244:245], s[24:25], 0, v[174:175]
	global_load_lds_dwordx4 v[242:243], off
	s_mov_b32 m0, s30
	s_nop 0
	global_load_lds_dwordx4 v[244:245], off
	s_waitcnt vmcnt(8)
	s_waitcnt lgkmcnt(0)
	s_barrier
	s_setprio 1
	s_waitcnt lgkmcnt(0)
	v_mfma_f32_16x16x32_bf16 v[62:65], v[130:133], v[186:189], v[62:65]
	v_mfma_f32_16x16x32_bf16 v[58:61], v[138:141], v[186:189], v[58:61]
	v_mfma_f32_16x16x32_bf16 v[46:49], v[130:133], v[194:197], v[46:49]
	v_mfma_f32_16x16x32_bf16 v[42:45], v[138:141], v[194:197], v[42:45]
	v_mfma_f32_16x16x32_bf16 v[30:33], v[130:133], v[220:223], v[30:33]
	v_mfma_f32_16x16x32_bf16 v[26:29], v[138:141], v[220:223], v[26:29]
	v_mfma_f32_16x16x32_bf16 v[14:17], v[130:133], v[228:231], v[14:17]
	v_mfma_f32_16x16x32_bf16 v[10:13], v[138:141], v[228:231], v[10:13]
	v_mfma_f32_16x16x32_bf16 v[62:65], v[134:137], v[190:193], v[62:65]
	v_mfma_f32_16x16x32_bf16 v[58:61], v[142:145], v[190:193], v[58:61]
	v_mfma_f32_16x16x32_bf16 v[46:49], v[134:137], v[216:219], v[46:49]
	v_mfma_f32_16x16x32_bf16 v[42:45], v[142:145], v[216:219], v[42:45]
	v_mfma_f32_16x16x32_bf16 v[30:33], v[134:137], v[224:227], v[30:33]
	v_mfma_f32_16x16x32_bf16 v[26:29], v[142:145], v[224:227], v[26:29]
	v_mfma_f32_16x16x32_bf16 v[14:17], v[134:137], v[232:235], v[14:17]
	v_mfma_f32_16x16x32_bf16 v[10:13], v[142:145], v[232:235], v[10:13]
	v_mfma_f32_16x16x32_bf16 v[54:57], v[146:149], v[186:189], v[54:57]
	v_mfma_f32_16x16x32_bf16 v[50:53], v[154:157], v[186:189], v[50:53]
	v_mfma_f32_16x16x32_bf16 v[38:41], v[146:149], v[194:197], v[38:41]
	v_mfma_f32_16x16x32_bf16 v[34:37], v[154:157], v[194:197], v[34:37]
	v_mfma_f32_16x16x32_bf16 v[22:25], v[146:149], v[220:223], v[22:25]
	v_mfma_f32_16x16x32_bf16 v[18:21], v[154:157], v[220:223], v[18:21]
	v_mfma_f32_16x16x32_bf16 v[6:9], v[146:149], v[228:231], v[6:9]
	v_mfma_f32_16x16x32_bf16 v[2:5], v[154:157], v[228:231], v[2:5]
	v_mfma_f32_16x16x32_bf16 v[54:57], v[150:153], v[190:193], v[54:57]
	v_mfma_f32_16x16x32_bf16 v[50:53], v[182:185], v[190:193], v[50:53]
	v_mfma_f32_16x16x32_bf16 v[38:41], v[150:153], v[216:219], v[38:41]
	v_mfma_f32_16x16x32_bf16 v[34:37], v[182:185], v[216:219], v[34:37]
	v_mfma_f32_16x16x32_bf16 v[22:25], v[150:153], v[224:227], v[22:25]
	v_mfma_f32_16x16x32_bf16 v[18:21], v[182:185], v[224:227], v[18:21]
	v_mfma_f32_16x16x32_bf16 v[6:9], v[150:153], v[232:235], v[6:9]
	v_mfma_f32_16x16x32_bf16 v[2:5], v[182:185], v[232:235], v[2:5]
	s_setprio 0
	s_barrier
; #define PG8_STAGE(bufoff, gbase, voff) do { _Pragma("unroll") for (int _i = 0; _i < 2; ++_i) \
;         __builtin_amdgcn_global_load_lds((const unsigned*)((const char*)(gbase) + (voff)[_i]), (PG8_LAS unsigned*)(lds + (bufoff) + ldsw + _i * 8192), 16, 0, 0); } while (0)
; #define PG8_LDA(dst, b, h) do { _Pragma("unroll") for (int m = 0; m < 4; ++m) _Pragma("unroll") for (int k = 0; k < 2; ++k) dst[m][k] = *(const PG8_LAS bf16x8*)(lds + PG8_SA(b, h) + aoff + m * 2048 + k * 1024); } while (0)
; #define PG8_LDB(dst, b, h) do { _Pragma("unroll") for (int n = 0; n < 2; ++n) _Pragma("unroll") for (int k = 0; k < 2; ++k) dst[n][k] = *(const PG8_LAS bf16x8*)(lds + PG8_SB(b, h) + boff + n * 2048 + k * 1024); } while (0)
; #define PG8_MMA(ai, bj, At, Bt) do { __builtin_amdgcn_s_setprio(1); _Pragma("unroll") for (int m = 0; m < 4; ++m) _Pragma("unroll") for (int n = 0; n < 2; ++n) _Pragma("unroll") for (int k = 0; k < 2; ++k) \
;         acc[ai][bj][m][n] = __builtin_amdgcn_mfma_f32_16x16x32_bf16(Bt[n][k], At[m][k], acc[ai][bj][m][n], 0, 0, 0); __builtin_amdgcn_s_setprio(0); } while (0)
; #define PG8_WAIT_V(n) asm volatile("s_waitcnt vmcnt(" #n ")" ::: "memory")
; #define PG8_WAIT_L(n) asm volatile("s_waitcnt lgkmcnt(" #n ")" ::: "memory")
; #define PG8_BAR __builtin_amdgcn_s_barrier()
; #define PG8_SCHED __builtin_amdgcn_sched_barrier(0)
; template <class Epi, class Sched, bool ALIGN_EPI = false, bool SP2 = false>
; __device__ __forceinline__ void gemm_phase(PG8_LAS unsigned char* lds, const Gemm g, const Sched& S, const Epi& E) {
;     ...
;             PG8_LDB(B0, 1, 0); PG8_LDB(B1, 1, 1); PG8_SCHED; PG8_LDA(At, 1, 0); PG8_STAGE(PG8_SA(0, 1), a2 + hstep, voffA);
;             PG8_WAIT_V(8); PG8_WAIT_L(0); PG8_BAR; PG8_MMA(0, 0, At, B0); PG8_MMA(0, 1, At, B1); PG8_BAR; PG8_SCHED;
;             PG8_LDA(At, 1, 1); PG8_STAGE(PG8_SB(1, 0), b3, voffB); PG8_STAGE(PG8_SB(1, 1), b3 + hstep, voffB); PG8_STAGE(PG8_SA(1, 0), a3, voffA);
	s_add_i32 s47, 0, 0x18000
	s_add_i32 s48, 0, 0x1c000
	v_add_u32_e32 v142, s47, v165
	v_add_u32_e32 v182, s48, v165
	ds_read_b128 v[130:133], v142
	ds_read_b128 v[134:137], v142 offset:1024
	ds_read_b128 v[138:141], v142 offset:2048
	ds_read_b128 v[142:145], v142 offset:3072
	ds_read_b128 v[146:149], v182
	ds_read_b128 v[150:153], v182 offset:1024
	ds_read_b128 v[154:157], v182 offset:2048
	ds_read_b128 v[182:185], v182 offset:3072
	s_add_u32 s24, s24, s8
	s_addc_u32 s25, s25, 0
	s_mov_b32 m0, s31
	v_lshl_add_u64 v[246:247], s[24:25], 0, v[176:177]
	ds_read_b128 v[186:189], v214 offset:32768
	ds_read_b128 v[190:193], v214 offset:33792
	ds_read_b128 v[194:197], v214 offset:34816
	ds_read_b128 v[216:219], v214 offset:35840
	ds_read_b128 v[220:223], v214 offset:36864
	ds_read_b128 v[224:227], v214 offset:37888
	ds_read_b128 v[228:231], v214 offset:38912
	ds_read_b128 v[232:235], v214 offset:39936
	global_load_lds_dwordx4 v[246:247], off
	v_lshl_add_u64 v[246:247], s[24:25], 0, v[174:175]
	s_mov_b32 m0, s34
	s_nop 0
	global_load_lds_dwordx4 v[246:247], off
	s_waitcnt vmcnt(8)
	s_waitcnt lgkmcnt(0)
	s_barrier
	s_setprio 1
	s_waitcnt lgkmcnt(0)
	v_mfma_f32_16x16x32_bf16 v[126:129], v[130:133], v[186:189], v[126:129]
	v_mfma_f32_16x16x32_bf16 v[122:125], v[138:141], v[186:189], v[122:125]
	v_mfma_f32_16x16x32_bf16 v[110:113], v[130:133], v[194:197], v[110:113]
	v_mfma_f32_16x16x32_bf16 v[106:109], v[138:141], v[194:197], v[106:109]
	v_mfma_f32_16x16x32_bf16 v[94:97], v[130:133], v[220:223], v[94:97]
	v_mfma_f32_16x16x32_bf16 v[90:93], v[138:141], v[220:223], v[90:93]
	v_mfma_f32_16x16x32_bf16 v[78:81], v[130:133], v[228:231], v[78:81]
	v_mfma_f32_16x16x32_bf16 v[74:77], v[138:141], v[228:231], v[74:77]
	v_mfma_f32_16x16x32_bf16 v[126:129], v[134:137], v[190:193], v[126:129]
	v_mfma_f32_16x16x32_bf16 v[122:125], v[142:145], v[190:193], v[122:125]
	v_mfma_f32_16x16x32_bf16 v[110:113], v[134:137], v[216:219], v[110:113]
	v_mfma_f32_16x16x32_bf16 v[106:109], v[142:145], v[216:219], v[106:109]
	v_mfma_f32_16x16x32_bf16 v[94:97], v[134:137], v[224:227], v[94:97]
	v_mfma_f32_16x16x32_bf16 v[90:93], v[142:145], v[224:227], v[90:93]
	v_mfma_f32_16x16x32_bf16 v[78:81], v[134:137], v[232:235], v[78:81]
	v_mfma_f32_16x16x32_bf16 v[74:77], v[142:145], v[232:235], v[74:77]
	v_mfma_f32_16x16x32_bf16 v[118:121], v[146:149], v[186:189], v[118:121]
	v_mfma_f32_16x16x32_bf16 v[114:117], v[154:157], v[186:189], v[114:117]
	v_mfma_f32_16x16x32_bf16 v[102:105], v[146:149], v[194:197], v[102:105]
	v_mfma_f32_16x16x32_bf16 v[98:101], v[154:157], v[194:197], v[98:101]
	v_mfma_f32_16x16x32_bf16 v[86:89], v[146:149], v[220:223], v[86:89]
	v_mfma_f32_16x16x32_bf16 v[82:85], v[154:157], v[220:223], v[82:85]
	v_mfma_f32_16x16x32_bf16 v[70:73], v[146:149], v[228:231], v[70:73]
	v_mfma_f32_16x16x32_bf16 v[66:69], v[154:157], v[228:231], v[66:69]
	v_mfma_f32_16x16x32_bf16 v[118:121], v[150:153], v[190:193], v[118:121]
	v_mfma_f32_16x16x32_bf16 v[114:117], v[182:185], v[190:193], v[114:117]
	v_mfma_f32_16x16x32_bf16 v[102:105], v[150:153], v[216:219], v[102:105]
	v_mfma_f32_16x16x32_bf16 v[98:101], v[182:185], v[216:219], v[98:101]
	v_mfma_f32_16x16x32_bf16 v[86:89], v[150:153], v[224:227], v[86:89]
	v_mfma_f32_16x16x32_bf16 v[82:85], v[182:185], v[224:227], v[82:85]
	v_mfma_f32_16x16x32_bf16 v[70:73], v[150:153], v[232:235], v[70:73]
	v_mfma_f32_16x16x32_bf16 v[66:69], v[182:185], v[232:235], v[66:69]
	s_setprio 0
	s_barrier
	s_add_i32 s24, s47, s2
	v_lshl_add_u64 v[198:199], v[198:199], 0, s[90:91]
	s_mov_b32 m0, s24
	ds_read_b128 v[186:189], v214 offset:49152
	ds_read_b128 v[190:193], v214 offset:50176
	ds_read_b128 v[194:197], v214 offset:51200
	ds_read_b128 v[216:219], v214 offset:52224
	ds_read_b128 v[220:223], v214 offset:53248
	ds_read_b128 v[224:227], v214 offset:54272
	ds_read_b128 v[228:231], v214 offset:55296
	ds_read_b128 v[232:235], v214 offset:56320
	global_load_lds_dwordx4 v[198:199], off
	v_lshl_add_u64 v[198:199], v[236:237], 0, s[90:91]
	s_add_i32 m0, s24, 0x2000
	s_add_i32 s24, s48, s2
	global_load_lds_dwordx4 v[198:199], off
	v_lshl_add_u64 v[198:199], v[238:239], 0, s[90:91]
	s_mov_b32 m0, s24
	s_nop 0
	global_load_lds_dwordx4 v[198:199], off
	v_lshl_add_u64 v[198:199], v[240:241], 0, s[90:91]
	s_add_i32 m0, s24, 0x2000
	s_nop 0
	global_load_lds_dwordx4 v[198:199], off
	v_lshl_add_u64 v[198:199], v[242:243], 0, s[90:91]
	s_mov_b32 m0, s38
	s_nop 0
	global_load_lds_dwordx4 v[198:199], off
	v_lshl_add_u64 v[198:199], v[244:245], 0, s[90:91]
	s_mov_b32 m0, s39
	s_nop 0
	global_load_lds_dwordx4 v[198:199], off
	s_waitcnt vmcnt(8)
	s_waitcnt lgkmcnt(0)
	s_barrier
; #define PG8_WAIT_V(n) asm volatile("s_waitcnt vmcnt(" #n ")" ::: "memory")
; #define PG8_WAIT_L(n) asm volatile("s_waitcnt lgkmcnt(" #n ")" ::: "memory")
; template <class Epi, class Sched, bool ALIGN_EPI = false, bool SP2 = false>
; __device__ __forceinline__ void gemm_phase(PG8_LAS unsigned char* lds, const Gemm g, const Sched& S, const Epi& E) {
;     ...
;             PG8_WAIT_V(8); PG8_WAIT_L(0); PG8_BAR; PG8_MMA(1, 0, At, B0); PG8_MMA(1, 1, At, B1); PG8_BAR; PG8_SCHED;
;             } else {
;             PG8_LDB(B0, 0, 0); PG8_SCHED; PG8_LDA(At, 0, 0); PG8_STAGE(PG8_SA(1, 1), a1 + hstep, voffA);
;             PG8_WAIT_L(8); PG8_BAR; PG8_WAIT_L(0); PG8_MMA(0, 0, At, B0); PG8_BAR; PG8_SCHED;
;             PG8_LDB(B1, 0, 1); PG8_STAGE(PG8_SB(0, 0), b2, voffB);
;             PG8_BAR; PG8_WAIT_L(0); PG8_MMA(0, 1, At, B1); PG8_BAR;
;             PG8_LDA(At, 0, 1); PG8_STAGE(PG8_SA(0, 0), a2, voffA);
;             PG8_BAR; PG8_WAIT_L(0); PG8_MMA(1, 0, At, B0); PG8_BAR; PG8_SCHED;
;             PG8_STAGE(PG8_SB(0, 1), b2 + hstep, voffB);
;             PG8_WAIT_V(6); PG8_BAR; PG8_MMA(1, 1, At, B1); PG8_BAR;
;             PG8_LDB(B0, 1, 0); PG8_SCHED; PG8_LDA(At, 1, 0); PG8_STAGE(PG8_SA(0, 1), a2 + hstep, voffA);
;             PG8_WAIT_L(8); PG8_BAR; PG8_WAIT_L(0); PG8_MMA(0, 0, At, B0); PG8_BAR; PG8_SCHED;
;             PG8_LDB(B1, 1, 1); PG8_STAGE(PG8_SB(1, 0), b3, voffB);
;             PG8_BAR; PG8_WAIT_L(0); PG8_MMA(0, 1, At, B1); PG8_BAR;
;             PG8_LDA(At, 1, 1); PG8_STAGE(PG8_SA(1, 0), a3, voffA);
;             PG8_BAR; PG8_WAIT_L(0); PG8_MMA(1, 0, At, B0); PG8_BAR; PG8_SCHED;
;             PG8_STAGE(PG8_SB(1, 1), b3 + hstep, voffB);
;             PG8_WAIT_V(6); PG8_BAR; PG8_MMA(1, 1, At, B1); PG8_BAR;
;             }
;         }
;         if constexpr (ALIGN_EPI) { if (wr == 0) PG8_BAR; }
;     __device__ __forceinline__ void operator()(const f32x4 (&acc)[2][2][4][2], const Unit& u, int wr, int wc, int fr, int fq) const {
;         const int row0 = u.pm * BM + wr * 64 + fr, col0 = u.pn * BM + wc * 32 + 8 * fq;
; #pragma unroll
;         for (int ai = 0; ai < 2; ++ai) {
;             u32x4 xv[4][2];
; #pragma unroll
;             for (int m = 0; m < 4; ++m)
; #pragma unroll
;                 for (int bj = 0; bj < 2; ++bj) xv[m][bj] = *(const u32x4*)(XB + (size_t)(row0 + ai * HALF + m * 16) * 1024 + col0 + bj * HALF);
	s_setprio 1
	s_waitcnt lgkmcnt(0)
	v_mfma_f32_16x16x32_bf16 v[62:65], v[130:133], v[186:189], v[62:65]
	v_mfma_f32_16x16x32_bf16 v[58:61], v[138:141], v[186:189], v[58:61]
	v_mfma_f32_16x16x32_bf16 v[46:49], v[130:133], v[194:197], v[46:49]
	v_mfma_f32_16x16x32_bf16 v[42:45], v[138:141], v[194:197], v[42:45]
	v_mfma_f32_16x16x32_bf16 v[30:33], v[130:133], v[220:223], v[30:33]
	v_mfma_f32_16x16x32_bf16 v[26:29], v[138:141], v[220:223], v[26:29]
	v_mfma_f32_16x16x32_bf16 v[14:17], v[130:133], v[228:231], v[14:17]
	v_mfma_f32_16x16x32_bf16 v[10:13], v[138:141], v[228:231], v[10:13]
	v_mfma_f32_16x16x32_bf16 v[62:65], v[134:137], v[190:193], v[62:65]
	v_mfma_f32_16x16x32_bf16 v[58:61], v[142:145], v[190:193], v[58:61]
	v_mfma_f32_16x16x32_bf16 v[46:49], v[134:137], v[216:219], v[46:49]
	v_mfma_f32_16x16x32_bf16 v[42:45], v[142:145], v[216:219], v[42:45]
	v_mfma_f32_16x16x32_bf16 v[30:33], v[134:137], v[224:227], v[30:33]
	v_mfma_f32_16x16x32_bf16 v[26:29], v[142:145], v[224:227], v[26:29]
	v_mfma_f32_16x16x32_bf16 v[14:17], v[134:137], v[232:235], v[14:17]
	v_mfma_f32_16x16x32_bf16 v[10:13], v[142:145], v[232:235], v[10:13]
	v_mfma_f32_16x16x32_bf16 v[54:57], v[146:149], v[186:189], v[54:57]
	v_mfma_f32_16x16x32_bf16 v[50:53], v[154:157], v[186:189], v[50:53]
	v_mfma_f32_16x16x32_bf16 v[38:41], v[146:149], v[194:197], v[38:41]
	v_mfma_f32_16x16x32_bf16 v[34:37], v[154:157], v[194:197], v[34:37]
	v_mfma_f32_16x16x32_bf16 v[22:25], v[146:149], v[220:223], v[22:25]
	v_mfma_f32_16x16x32_bf16 v[18:21], v[154:157], v[220:223], v[18:21]
	v_mfma_f32_16x16x32_bf16 v[6:9], v[146:149], v[228:231], v[6:9]
	v_mfma_f32_16x16x32_bf16 v[2:5], v[154:157], v[228:231], v[2:5]
	v_mfma_f32_16x16x32_bf16 v[54:57], v[150:153], v[190:193], v[54:57]
	v_mfma_f32_16x16x32_bf16 v[50:53], v[182:185], v[190:193], v[50:53]
	v_mfma_f32_16x16x32_bf16 v[38:41], v[150:153], v[216:219], v[38:41]
	v_mfma_f32_16x16x32_bf16 v[34:37], v[182:185], v[216:219], v[34:37]
	v_mfma_f32_16x16x32_bf16 v[22:25], v[150:153], v[224:227], v[22:25]
	v_mfma_f32_16x16x32_bf16 v[18:21], v[182:185], v[224:227], v[18:21]
	v_mfma_f32_16x16x32_bf16 v[6:9], v[150:153], v[232:235], v[6:9]
	v_mfma_f32_16x16x32_bf16 v[2:5], v[182:185], v[232:235], v[2:5]
	s_setprio 0
	s_barrier
	s_add_u32 s22, s22, 0x100
	s_addc_u32 s23, s23, 0
	s_add_u32 s44, s44, 0x100
	s_addc_u32 s45, s45, 0
	s_cmp_ge_u32 s46, s36
	s_mov_b32 s24, s46
	s_cbranch_scc0 .LBB0_42
	v_lshl_or_b32 v198, s9, 8, v213
	v_lshl_add_u32 v217, s41, 8, v158
	v_lshlrev_b32_e32 v246, 1, v198
	v_lshl_add_u32 v246, v217, 11, v246
	v_mov_b32_e32 v247, 0
	s_mov_b32 s22, 0x8000
	s_mov_b32 s23, 0
	s_mov_b32 s88, 0x28000
	v_lshl_add_u64 v[246:247], s[94:95], 0, v[246:247]
	v_xor_b32_e32 v215, 16, v201
	v_xor_b32_e32 v216, 32, v201
	v_mov_b32_e32 v198, v246
	v_mov_b32_e32 v199, v247
	global_load_dwordx4 v[130:133], v[246:247], off
	global_load_dwordx4 v[134:137], v[246:247], off offset:256
	v_lshl_add_u64 v[246:247], v[246:247], 0, s[22:23]
	global_load_dwordx4 v[138:141], v[246:247], off
	global_load_dwordx4 v[142:145], v[246:247], off offset:256
	v_lshl_add_u64 v[246:247], v[246:247], 0, s[22:23]
	global_load_dwordx4 v[146:149], v[246:247], off
	global_load_dwordx4 v[150:153], v[246:247], off offset:256
	v_lshl_add_u64 v[246:247], v[246:247], 0, s[22:23]
	global_load_dwordx4 v[154:157], v[246:247], off
	global_load_dwordx4 v[218:221], v[246:247], off offset:256
	v_lshl_add_u64 v[246:247], v[246:247], 0, s[88:89]
	global_load_dwordx4 v[182:185], v[246:247], off
	global_load_dwordx4 v[186:189], v[246:247], off offset:256
	v_lshl_add_u64 v[246:247], v[246:247], 0, s[22:23]
	global_load_dwordx4 v[190:193], v[246:247], off
	global_load_dwordx4 v[194:197], v[246:247], off offset:256
	v_lshl_add_u64 v[246:247], v[246:247], 0, s[22:23]
	global_load_dwordx4 v[222:225], v[246:247], off
	global_load_dwordx4 v[226:229], v[246:247], off offset:256
	v_lshl_add_u64 v[246:247], v[246:247], 0, s[22:23]
	global_load_dwordx4 v[230:233], v[246:247], off
	global_load_dwordx4 v[234:237], v[246:247], off offset:256
	v_lshlrev_b32_e32 v215, 2, v215
	v_lshlrev_b32_e32 v216, 2, v216
	s_and_b64 vcc, exec, s[12:13]
	s_cbranch_vccz .LBB0_45
	s_barrier

; #define PG8_STAGE(bufoff, gbase, voff) do { _Pragma("unroll") for (int _i = 0; _i < 2; ++_i) \
;         __builtin_amdgcn_global_load_lds((const unsigned*)((const char*)(gbase) + (voff)[_i]), (PG8_LAS unsigned*)(lds + (bufoff) + ldsw + _i * 8192), 16, 0, 0); } while (0)
; #define PG8_LDA(dst, b, h) do { _Pragma("unroll") for (int m = 0; m < 4; ++m) _Pragma("unroll") for (int k = 0; k < 2; ++k) dst[m][k] = *(const PG8_LAS bf16x8*)(lds + PG8_SA(b, h) + aoff + m * 2048 + k * 1024); } while (0)
; #define PG8_LDB(dst, b, h) do { _Pragma("unroll") for (int n = 0; n < 2; ++n) _Pragma("unroll") for (int k = 0; k < 2; ++k) dst[n][k] = *(const PG8_LAS bf16x8*)(lds + PG8_SB(b, h) + boff + n * 2048 + k * 1024); } while (0)
; #define PG8_WAIT_V(n) asm volatile("s_waitcnt vmcnt(" #n ")" ::: "memory")
; #define PG8_WAIT_L(n) asm volatile("s_waitcnt lgkmcnt(" #n ")" ::: "memory")
; #define PG8_BAR __builtin_amdgcn_s_barrier()
; #define PG8_SCHED __builtin_amdgcn_sched_barrier(0)
; template <class Epi, class Sched, bool ALIGN_EPI = false, bool SP2 = false>
; __device__ __forceinline__ void gemm_phase(PG8_LAS unsigned char* lds, const Gemm g, const Sched& S, const Epi& E) {
;     ...
;         const bool has_next = S.next(ui + 1, nxt);
;         const char* nA = has_next ? (const char*)g.A + (size_t)nxt.pm * tstep : cA; const char* nB = has_next ? (const char*)g.Bt + (size_t)nxt.pn * tstep : cB;
;         for (int t = 0; t < nt; t += 2) {
;             const bool last = (t == nt - 2);
;             const char* a1 = cA + (size_t)(t + 1) * kstep;
;             const char* a2 = last ? nA : cA + (size_t)(t + 2) * kstep; const char* b2 = last ? nB : cB + (size_t)(t + 2) * kstep;
;             const char* a3 = a2 + kstep; const char* b3 = b2 + kstep;
;             if (last && has_next) S.a_ready(nxt);
;             if constexpr (SP2) {
;             PG8_LDB(B0, 0, 0); PG8_LDB(B1, 0, 1); PG8_SCHED; PG8_LDA(At, 0, 0); PG8_STAGE(PG8_SA(1, 1), a1 + hstep, voffA);
;             PG8_WAIT_V(8); PG8_WAIT_L(0); PG8_BAR; PG8_MMA(0, 0, At, B0); PG8_MMA(0, 1, At, B1); PG8_BAR; PG8_SCHED;
;             PG8_LDA(At, 0, 1); PG8_STAGE(PG8_SB(0, 0), b2, voffB); PG8_STAGE(PG8_SB(0, 1), b2 + hstep, voffB); PG8_STAGE(PG8_SA(0, 0), a2, voffA);
;             PG8_WAIT_V(8); PG8_WAIT_L(0); PG8_BAR; PG8_MMA(1, 0, At, B0); PG8_MMA(1, 1, At, B1); PG8_BAR; PG8_SCHED;
.LBB0_329:
	s_ashr_i32 s21, s20, 31
	s_lshl_b64 s[22:23], s[20:21], 19
	s_add_u32 s22, s94, s22
	s_addc_u32 s23, s95, s23
	s_and_b64 s[24:25], s[4:5], exec
	s_cselect_b32 s21, s23, s29
	s_cselect_b32 s27, s22, s28
	s_ashr_i32 s19, s18, 31
	s_lshl_b64 s[24:25], s[18:19], 19
	v_readlane_b32 s34, v251, 0
	v_readlane_b32 s35, v251, 1
	s_add_u32 s24, s34, s24
	s_addc_u32 s25, s35, s25
	s_and_b64 s[34:35], s[4:5], exec
	s_cselect_b32 s19, s25, s31
	s_cselect_b32 s60, s24, s30
	s_add_u32 s28, s28, 0x40080
	s_addc_u32 s29, s29, 0
	s_add_u32 s61, s30, 0x100
	s_waitcnt vmcnt(0)
	s_addc_u32 s62, s31, 0
	s_mov_b32 s63, -2
	s_add_u32 s30, s28, 0xfffc0080
	s_addc_u32 s31, s29, -1
	s_add_i32 s64, 0, 0x10000
	s_cmp_eq_u32 s63, 12
	s_cselect_b32 s35, s21, s31
	s_cselect_b32 s34, s27, s30
	v_add_u32_e32 v156, s64, v149
	s_cselect_b32 s31, s19, s62
	s_cselect_b32 s30, s60, s61
	s_add_i32 s66, 0, 0x14000
	ds_read_b128 v[144:147], v156
	ds_read_b128 v[152:155], v156 offset:1024
	ds_read_b128 v[172:175], v156 offset:2048
	ds_read_b128 v[176:179], v156 offset:3072
	v_add_u32_e32 v156, s66, v149
	ds_read_b128 v[180:183], v156
	ds_read_b128 v[184:187], v156 offset:1024
	ds_read_b128 v[188:191], v156 offset:2048
	ds_read_b128 v[192:195], v156 offset:3072
	s_add_i32 m0, s46, 0xc000
	ds_read_b128 v[196:199], v151
	ds_read_b128 v[214:217], v151 offset:1024
	ds_read_b128 v[218:221], v151 offset:2048
	ds_read_b128 v[222:225], v151 offset:3072
	ds_read_b128 v[226:229], v151 offset:4096
	ds_read_b128 v[230:233], v151 offset:5120
	ds_read_b128 v[234:237], v151 offset:6144
	ds_read_b128 v[238:241], v151 offset:7168
	global_load_lds_dwordx4 v140, s[28:29]
	s_add_i32 m0, s46, 0xe000
	s_nop 0
	global_load_lds_dwordx4 v142, s[28:29]
	s_waitcnt vmcnt(8)
	s_waitcnt lgkmcnt(0)
	s_barrier
	s_setprio 1
	s_waitcnt lgkmcnt(0)
	v_mfma_f32_16x16x32_bf16 v[62:65], v[144:147], v[196:199], 0
	v_mfma_f32_16x16x32_bf16 v[58:61], v[172:175], v[196:199], 0
	v_mfma_f32_16x16x32_bf16 v[54:57], v[144:147], v[218:221], 0
	v_mfma_f32_16x16x32_bf16 v[50:53], v[172:175], v[218:221], 0
	v_mfma_f32_16x16x32_bf16 v[46:49], v[144:147], v[226:229], 0
	v_mfma_f32_16x16x32_bf16 v[42:45], v[172:175], v[226:229], 0
	v_mfma_f32_16x16x32_bf16 v[38:41], v[144:147], v[234:237], 0
	v_mfma_f32_16x16x32_bf16 v[34:37], v[172:175], v[234:237], 0
	v_mfma_f32_16x16x32_bf16 v[62:65], v[152:155], v[214:217], v[62:65]
	v_mfma_f32_16x16x32_bf16 v[58:61], v[176:179], v[214:217], v[58:61]
	v_mfma_f32_16x16x32_bf16 v[54:57], v[152:155], v[222:225], v[54:57]
	v_mfma_f32_16x16x32_bf16 v[50:53], v[176:179], v[222:225], v[50:53]
	v_mfma_f32_16x16x32_bf16 v[46:49], v[152:155], v[230:233], v[46:49]
	v_mfma_f32_16x16x32_bf16 v[42:45], v[176:179], v[230:233], v[42:45]
	v_mfma_f32_16x16x32_bf16 v[38:41], v[152:155], v[238:241], v[38:41]
	v_mfma_f32_16x16x32_bf16 v[34:37], v[176:179], v[238:241], v[34:37]
	v_mfma_f32_16x16x32_bf16 v[126:129], v[180:183], v[196:199], 0
	v_mfma_f32_16x16x32_bf16 v[122:125], v[188:191], v[196:199], 0
	v_mfma_f32_16x16x32_bf16 v[118:121], v[180:183], v[218:221], 0
	v_mfma_f32_16x16x32_bf16 v[114:117], v[188:191], v[218:221], 0
	v_mfma_f32_16x16x32_bf16 v[110:113], v[180:183], v[226:229], 0
	v_mfma_f32_16x16x32_bf16 v[106:109], v[188:191], v[226:229], 0
	v_mfma_f32_16x16x32_bf16 v[102:105], v[180:183], v[234:237], 0
	v_mfma_f32_16x16x32_bf16 v[98:101], v[188:191], v[234:237], 0
	v_mfma_f32_16x16x32_bf16 v[126:129], v[184:187], v[214:217], v[126:129]
	v_mfma_f32_16x16x32_bf16 v[122:125], v[192:195], v[214:217], v[122:125]
	v_mfma_f32_16x16x32_bf16 v[118:121], v[184:187], v[222:225], v[118:121]
	v_mfma_f32_16x16x32_bf16 v[114:117], v[192:195], v[222:225], v[114:117]
	v_mfma_f32_16x16x32_bf16 v[110:113], v[184:187], v[230:233], v[110:113]
	v_mfma_f32_16x16x32_bf16 v[106:109], v[192:195], v[230:233], v[106:109]
	v_mfma_f32_16x16x32_bf16 v[102:105], v[184:187], v[238:241], v[102:105]
	v_mfma_f32_16x16x32_bf16 v[98:101], v[192:195], v[238:241], v[98:101]
	s_setprio 0
	s_barrier
	s_add_i32 s64, s64, s2
	s_mov_b32 m0, s64
	ds_read_b128 v[196:199], v151 offset:16384
	ds_read_b128 v[214:217], v151 offset:17408
	ds_read_b128 v[218:221], v151 offset:18432
	ds_read_b128 v[222:225], v151 offset:19456
	ds_read_b128 v[226:229], v151 offset:20480
	ds_read_b128 v[230:233], v151 offset:21504
	ds_read_b128 v[234:237], v151 offset:22528
	ds_read_b128 v[238:241], v151 offset:23552
	global_load_lds_dwordx4 v0, s[30:31]
	s_add_i32 m0, s64, 0x2000
	s_add_u32 s64, s30, 0x40000
	s_addc_u32 s65, s31, 0
	s_add_i32 s66, s66, s2
	global_load_lds_dwordx4 v130, s[30:31]
	s_mov_b32 m0, s66
	s_nop 0
	global_load_lds_dwordx4 v0, s[64:65]
	s_add_i32 m0, s66, 0x2000
	s_nop 0
	global_load_lds_dwordx4 v130, s[64:65]
	s_mov_b32 m0, s46
	s_nop 0
	global_load_lds_dwordx4 v134, s[34:35]
	s_mov_b32 m0, s47
	s_nop 0
	global_load_lds_dwordx4 v132, s[34:35]
	s_waitcnt vmcnt(8)
	s_waitcnt lgkmcnt(0)
	s_barrier
; #define PG8_STAGE(bufoff, gbase, voff) do { _Pragma("unroll") for (int _i = 0; _i < 2; ++_i) \
;         __builtin_amdgcn_global_load_lds((const unsigned*)((const char*)(gbase) + (voff)[_i]), (PG8_LAS unsigned*)(lds + (bufoff) + ldsw + _i * 8192), 16, 0, 0); } while (0)
; #define PG8_LDA(dst, b, h) do { _Pragma("unroll") for (int m = 0; m < 4; ++m) _Pragma("unroll") for (int k = 0; k < 2; ++k) dst[m][k] = *(const PG8_LAS bf16x8*)(lds + PG8_SA(b, h) + aoff + m * 2048 + k * 1024); } while (0)
; #define PG8_LDB(dst, b, h) do { _Pragma("unroll") for (int n = 0; n < 2; ++n) _Pragma("unroll") for (int k = 0; k < 2; ++k) dst[n][k] = *(const PG8_LAS bf16x8*)(lds + PG8_SB(b, h) + boff + n * 2048 + k * 1024); } while (0)
; #define PG8_MMA(ai, bj, At, Bt) do { __builtin_amdgcn_s_setprio(1); _Pragma("unroll") for (int m = 0; m < 4; ++m) _Pragma("unroll") for (int n = 0; n < 2; ++n) _Pragma("unroll") for (int k = 0; k < 2; ++k) \
;         acc[ai][bj][m][n] = __builtin_amdgcn_mfma_f32_16x16x32_bf16(Bt[n][k], At[m][k], acc[ai][bj][m][n], 0, 0, 0); __builtin_amdgcn_s_setprio(0); } while (0)
; #define PG8_WAIT_V(n) asm volatile("s_waitcnt vmcnt(" #n ")" ::: "memory")
; #define PG8_WAIT_L(n) asm volatile("s_waitcnt lgkmcnt(" #n ")" ::: "memory")
; #define PG8_BAR __builtin_amdgcn_s_barrier()
; #define PG8_SCHED __builtin_amdgcn_sched_barrier(0)
; template <class Epi, class Sched, bool ALIGN_EPI = false, bool SP2 = false>
; __device__ __forceinline__ void gemm_phase(PG8_LAS unsigned char* lds, const Gemm g, const Sched& S, const Epi& E) {
;     ...
;             PG8_WAIT_V(8); PG8_WAIT_L(0); PG8_BAR; PG8_MMA(1, 0, At, B0); PG8_MMA(1, 1, At, B1); PG8_BAR; PG8_SCHED;
;             PG8_LDB(B0, 1, 0); PG8_LDB(B1, 1, 1); PG8_SCHED; PG8_LDA(At, 1, 0); PG8_STAGE(PG8_SA(0, 1), a2 + hstep, voffA);
;             PG8_WAIT_V(8); PG8_WAIT_L(0); PG8_BAR; PG8_MMA(0, 0, At, B0); PG8_MMA(0, 1, At, B1); PG8_BAR; PG8_SCHED;
	s_setprio 1
	s_waitcnt lgkmcnt(0)
	v_mfma_f32_16x16x32_bf16 v[30:33], v[144:147], v[196:199], 0
	v_mfma_f32_16x16x32_bf16 v[26:29], v[172:175], v[196:199], 0
	v_mfma_f32_16x16x32_bf16 v[22:25], v[144:147], v[218:221], 0
	v_mfma_f32_16x16x32_bf16 v[18:21], v[172:175], v[218:221], 0
	v_mfma_f32_16x16x32_bf16 v[14:17], v[144:147], v[226:229], 0
	v_mfma_f32_16x16x32_bf16 v[10:13], v[172:175], v[226:229], 0
	v_mfma_f32_16x16x32_bf16 v[6:9], v[144:147], v[234:237], 0
	v_mfma_f32_16x16x32_bf16 v[2:5], v[172:175], v[234:237], 0
	v_mfma_f32_16x16x32_bf16 v[30:33], v[152:155], v[214:217], v[30:33]
	v_mfma_f32_16x16x32_bf16 v[26:29], v[176:179], v[214:217], v[26:29]
	v_mfma_f32_16x16x32_bf16 v[22:25], v[152:155], v[222:225], v[22:25]
	v_mfma_f32_16x16x32_bf16 v[18:21], v[176:179], v[222:225], v[18:21]
	v_mfma_f32_16x16x32_bf16 v[14:17], v[152:155], v[230:233], v[14:17]
	v_mfma_f32_16x16x32_bf16 v[10:13], v[176:179], v[230:233], v[10:13]
	v_mfma_f32_16x16x32_bf16 v[6:9], v[152:155], v[238:241], v[6:9]
	v_mfma_f32_16x16x32_bf16 v[2:5], v[176:179], v[238:241], v[2:5]
	v_mfma_f32_16x16x32_bf16 v[94:97], v[180:183], v[196:199], 0
	v_mfma_f32_16x16x32_bf16 v[90:93], v[188:191], v[196:199], 0
	v_mfma_f32_16x16x32_bf16 v[86:89], v[180:183], v[218:221], 0
	v_mfma_f32_16x16x32_bf16 v[82:85], v[188:191], v[218:221], 0
	v_mfma_f32_16x16x32_bf16 v[78:81], v[180:183], v[226:229], 0
	v_mfma_f32_16x16x32_bf16 v[74:77], v[188:191], v[226:229], 0
	v_mfma_f32_16x16x32_bf16 v[70:73], v[180:183], v[234:237], 0
	v_mfma_f32_16x16x32_bf16 v[66:69], v[188:191], v[234:237], 0
	v_mfma_f32_16x16x32_bf16 v[94:97], v[184:187], v[214:217], v[94:97]
	v_mfma_f32_16x16x32_bf16 v[90:93], v[192:195], v[214:217], v[90:93]
	v_mfma_f32_16x16x32_bf16 v[86:89], v[184:187], v[222:225], v[86:89]
	v_mfma_f32_16x16x32_bf16 v[82:85], v[192:195], v[222:225], v[82:85]
	v_mfma_f32_16x16x32_bf16 v[78:81], v[184:187], v[230:233], v[78:81]
	v_mfma_f32_16x16x32_bf16 v[74:77], v[192:195], v[230:233], v[74:77]
	v_mfma_f32_16x16x32_bf16 v[70:73], v[184:187], v[238:241], v[70:73]
	v_mfma_f32_16x16x32_bf16 v[66:69], v[192:195], v[238:241], v[66:69]
	s_setprio 0
	s_barrier
	s_add_i32 s64, 0, 0x18000
	v_add_u32_e32 v158, s64, v149
	s_add_i32 s65, 0, 0x1c000
	ds_read_b128 v[144:147], v158
	ds_read_b128 v[152:155], v158 offset:1024
	ds_read_b128 v[172:175], v158 offset:2048
	ds_read_b128 v[176:179], v158 offset:3072
	v_add_u32_e32 v158, s65, v149
	ds_read_b128 v[180:183], v158
	ds_read_b128 v[184:187], v158 offset:1024
	ds_read_b128 v[188:191], v158 offset:2048
	ds_read_b128 v[192:195], v158 offset:3072
	s_add_u32 s34, s34, 0x40000
	s_addc_u32 s35, s35, 0
	s_mov_b32 m0, s48
	ds_read_b128 v[196:199], v151 offset:32768
	ds_read_b128 v[214:217], v151 offset:33792
	ds_read_b128 v[218:221], v151 offset:34816
	ds_read_b128 v[222:225], v151 offset:35840
	ds_read_b128 v[226:229], v151 offset:36864
	ds_read_b128 v[230:233], v151 offset:37888
	ds_read_b128 v[234:237], v151 offset:38912
	ds_read_b128 v[238:241], v151 offset:39936
	global_load_lds_dwordx4 v134, s[34:35]
	s_mov_b32 m0, s49
	s_nop 0
	global_load_lds_dwordx4 v132, s[34:35]
	s_waitcnt vmcnt(8)
	s_waitcnt lgkmcnt(0)
	s_barrier
	s_setprio 1
	s_waitcnt lgkmcnt(0)
	v_mfma_f32_16x16x32_bf16 v[62:65], v[144:147], v[196:199], v[62:65]
	v_mfma_f32_16x16x32_bf16 v[58:61], v[172:175], v[196:199], v[58:61]
	v_mfma_f32_16x16x32_bf16 v[54:57], v[144:147], v[218:221], v[54:57]
	v_mfma_f32_16x16x32_bf16 v[50:53], v[172:175], v[218:221], v[50:53]
	v_mfma_f32_16x16x32_bf16 v[46:49], v[144:147], v[226:229], v[46:49]
	v_mfma_f32_16x16x32_bf16 v[42:45], v[172:175], v[226:229], v[42:45]
	v_mfma_f32_16x16x32_bf16 v[38:41], v[144:147], v[234:237], v[38:41]
	v_mfma_f32_16x16x32_bf16 v[34:37], v[172:175], v[234:237], v[34:37]
	v_mfma_f32_16x16x32_bf16 v[62:65], v[152:155], v[214:217], v[62:65]
	v_mfma_f32_16x16x32_bf16 v[58:61], v[176:179], v[214:217], v[58:61]
	v_mfma_f32_16x16x32_bf16 v[54:57], v[152:155], v[222:225], v[54:57]
	v_mfma_f32_16x16x32_bf16 v[50:53], v[176:179], v[222:225], v[50:53]
	v_mfma_f32_16x16x32_bf16 v[46:49], v[152:155], v[230:233], v[46:49]
	v_mfma_f32_16x16x32_bf16 v[42:45], v[176:179], v[230:233], v[42:45]
	v_mfma_f32_16x16x32_bf16 v[38:41], v[152:155], v[238:241], v[38:41]
	v_mfma_f32_16x16x32_bf16 v[34:37], v[176:179], v[238:241], v[34:37]
	v_mfma_f32_16x16x32_bf16 v[126:129], v[180:183], v[196:199], v[126:129]
	v_mfma_f32_16x16x32_bf16 v[122:125], v[188:191], v[196:199], v[122:125]
	v_mfma_f32_16x16x32_bf16 v[118:121], v[180:183], v[218:221], v[118:121]
	v_mfma_f32_16x16x32_bf16 v[114:117], v[188:191], v[218:221], v[114:117]
	v_mfma_f32_16x16x32_bf16 v[110:113], v[180:183], v[226:229], v[110:113]
	v_mfma_f32_16x16x32_bf16 v[106:109], v[188:191], v[226:229], v[106:109]
	v_mfma_f32_16x16x32_bf16 v[102:105], v[180:183], v[234:237], v[102:105]
	v_mfma_f32_16x16x32_bf16 v[98:101], v[188:191], v[234:237], v[98:101]
	v_mfma_f32_16x16x32_bf16 v[126:129], v[184:187], v[214:217], v[126:129]
	v_mfma_f32_16x16x32_bf16 v[122:125], v[192:195], v[214:217], v[122:125]
	v_mfma_f32_16x16x32_bf16 v[118:121], v[184:187], v[222:225], v[118:121]
	v_mfma_f32_16x16x32_bf16 v[114:117], v[192:195], v[222:225], v[114:117]
	v_mfma_f32_16x16x32_bf16 v[110:113], v[184:187], v[230:233], v[110:113]
	v_mfma_f32_16x16x32_bf16 v[106:109], v[192:195], v[230:233], v[106:109]
	v_mfma_f32_16x16x32_bf16 v[102:105], v[184:187], v[238:241], v[102:105]
	v_mfma_f32_16x16x32_bf16 v[98:101], v[192:195], v[238:241], v[98:101]
	s_setprio 0
	s_barrier
; #define PG8_STAGE(bufoff, gbase, voff) do { _Pragma("unroll") for (int _i = 0; _i < 2; ++_i) \
;         __builtin_amdgcn_global_load_lds((const unsigned*)((const char*)(gbase) + (voff)[_i]), (PG8_LAS unsigned*)(lds + (bufoff) + ldsw + _i * 8192), 16, 0, 0); } while (0)
; #define PG8_LDA(dst, b, h) do { _Pragma("unroll") for (int m = 0; m < 4; ++m) _Pragma("unroll") for (int k = 0; k < 2; ++k) dst[m][k] = *(const PG8_LAS bf16x8*)(lds + PG8_SA(b, h) + aoff + m * 2048 + k * 1024); } while (0)
; #define PG8_LDB(dst, b, h) do { _Pragma("unroll") for (int n = 0; n < 2; ++n) _Pragma("unroll") for (int k = 0; k < 2; ++k) dst[n][k] = *(const PG8_LAS bf16x8*)(lds + PG8_SB(b, h) + boff + n * 2048 + k * 1024); } while (0)
; template <class Epi, class Sched, bool ALIGN_EPI = false, bool SP2 = false>
; __device__ __forceinline__ void gemm_phase(PG8_LAS unsigned char* lds, const Gemm g, const Sched& S, const Epi& E) {
;     ...
;         for (int t = 0; t < nt; t += 2) {
;             const bool last = (t == nt - 2);
;             const char* a1 = cA + (size_t)(t + 1) * kstep;
;             const char* a2 = last ? nA : cA + (size_t)(t + 2) * kstep; const char* b2 = last ? nB : cB + (size_t)(t + 2) * kstep;
;             const char* a3 = a2 + kstep; const char* b3 = b2 + kstep;
;             if (last && has_next) S.a_ready(nxt);
;             if constexpr (SP2) {
;             PG8_LDB(B0, 0, 0); PG8_LDB(B1, 0, 1); PG8_SCHED; PG8_LDA(At, 0, 0); PG8_STAGE(PG8_SA(1, 1), a1 + hstep, voffA);
;             PG8_WAIT_V(8); PG8_WAIT_L(0); PG8_BAR; PG8_MMA(0, 0, At, B0); PG8_MMA(0, 1, At, B1); PG8_BAR; PG8_SCHED;
;             PG8_LDA(At, 0, 1); PG8_STAGE(PG8_SB(0, 0), b2, voffB); PG8_STAGE(PG8_SB(0, 1), b2 + hstep, voffB); PG8_STAGE(PG8_SA(0, 0), a2, voffA);
;             PG8_WAIT_V(8); PG8_WAIT_L(0); PG8_BAR; PG8_MMA(1, 0, At, B0); PG8_MMA(1, 1, At, B1); PG8_BAR; PG8_SCHED;
;             PG8_LDB(B0, 1, 0); PG8_LDB(B1, 1, 1); PG8_SCHED; PG8_LDA(At, 1, 0); PG8_STAGE(PG8_SA(0, 1), a2 + hstep, voffA);
;             PG8_WAIT_V(8); PG8_WAIT_L(0); PG8_BAR; PG8_MMA(0, 0, At, B0); PG8_MMA(0, 1, At, B1); PG8_BAR; PG8_SCHED;
;             PG8_LDA(At, 1, 1); PG8_STAGE(PG8_SB(1, 0), b3, voffB); PG8_STAGE(PG8_SB(1, 1), b3 + hstep, voffB); PG8_STAGE(PG8_SA(1, 0), a3, voffA);
;             PG8_WAIT_V(8); PG8_WAIT_L(0); PG8_BAR; PG8_MMA(1, 0, At, B0); PG8_MMA(1, 1, At, B1); PG8_BAR; PG8_SCHED;
	s_add_u32 s98, s34, 0xfffc0080
	s_addc_u32 s99, s35, -1
	s_add_i32 s34, s64, s2
	s_add_u32 s100, s30, 0x80
	s_addc_u32 s101, s31, 0
	s_mov_b32 m0, s34
	ds_read_b128 v[196:199], v151 offset:49152
	ds_read_b128 v[214:217], v151 offset:50176
	ds_read_b128 v[218:221], v151 offset:51200
	ds_read_b128 v[222:225], v151 offset:52224
	ds_read_b128 v[226:229], v151 offset:53248
	ds_read_b128 v[230:233], v151 offset:54272
	ds_read_b128 v[234:237], v151 offset:55296
	ds_read_b128 v[238:241], v151 offset:56320
	global_load_lds_dwordx4 v0, s[100:101]
	s_add_i32 m0, s34, 0x2000
	s_add_u32 s30, s30, 0x40080
	s_addc_u32 s31, s31, 0
	s_add_i32 s34, s65, s2
	global_load_lds_dwordx4 v130, s[100:101]
	s_mov_b32 m0, s34
	s_nop 0
	global_load_lds_dwordx4 v0, s[30:31]
	s_add_i32 m0, s34, 0x2000
	s_nop 0
	global_load_lds_dwordx4 v130, s[30:31]
	s_mov_b32 m0, s52
	s_nop 0
	global_load_lds_dwordx4 v134, s[98:99]
	s_mov_b32 m0, s53
	s_nop 0
	global_load_lds_dwordx4 v132, s[98:99]
	s_waitcnt vmcnt(8)
	s_waitcnt lgkmcnt(0)
	s_barrier
	s_setprio 1
	s_waitcnt lgkmcnt(0)
	v_mfma_f32_16x16x32_bf16 v[30:33], v[144:147], v[196:199], v[30:33]
	v_mfma_f32_16x16x32_bf16 v[26:29], v[172:175], v[196:199], v[26:29]
	v_mfma_f32_16x16x32_bf16 v[22:25], v[144:147], v[218:221], v[22:25]
	v_mfma_f32_16x16x32_bf16 v[18:21], v[172:175], v[218:221], v[18:21]
	v_mfma_f32_16x16x32_bf16 v[14:17], v[144:147], v[226:229], v[14:17]
	v_mfma_f32_16x16x32_bf16 v[10:13], v[172:175], v[226:229], v[10:13]
	v_mfma_f32_16x16x32_bf16 v[6:9], v[144:147], v[234:237], v[6:9]
	v_mfma_f32_16x16x32_bf16 v[2:5], v[172:175], v[234:237], v[2:5]
	v_mfma_f32_16x16x32_bf16 v[30:33], v[152:155], v[214:217], v[30:33]
	v_mfma_f32_16x16x32_bf16 v[26:29], v[176:179], v[214:217], v[26:29]
	v_mfma_f32_16x16x32_bf16 v[22:25], v[152:155], v[222:225], v[22:25]
	v_mfma_f32_16x16x32_bf16 v[18:21], v[176:179], v[222:225], v[18:21]
	v_mfma_f32_16x16x32_bf16 v[14:17], v[152:155], v[230:233], v[14:17]
	v_mfma_f32_16x16x32_bf16 v[10:13], v[176:179], v[230:233], v[10:13]
	v_mfma_f32_16x16x32_bf16 v[6:9], v[152:155], v[238:241], v[6:9]
	v_mfma_f32_16x16x32_bf16 v[2:5], v[176:179], v[238:241], v[2:5]
	v_mfma_f32_16x16x32_bf16 v[94:97], v[180:183], v[196:199], v[94:97]
	v_mfma_f32_16x16x32_bf16 v[90:93], v[188:191], v[196:199], v[90:93]
	v_mfma_f32_16x16x32_bf16 v[86:89], v[180:183], v[218:221], v[86:89]
	v_mfma_f32_16x16x32_bf16 v[82:85], v[188:191], v[218:221], v[82:85]
	v_mfma_f32_16x16x32_bf16 v[78:81], v[180:183], v[226:229], v[78:81]
	v_mfma_f32_16x16x32_bf16 v[74:77], v[188:191], v[226:229], v[74:77]
	v_mfma_f32_16x16x32_bf16 v[70:73], v[180:183], v[234:237], v[70:73]
	v_mfma_f32_16x16x32_bf16 v[66:69], v[188:191], v[234:237], v[66:69]
	v_mfma_f32_16x16x32_bf16 v[94:97], v[184:187], v[214:217], v[94:97]
	v_mfma_f32_16x16x32_bf16 v[90:93], v[192:195], v[214:217], v[90:93]
	v_mfma_f32_16x16x32_bf16 v[86:89], v[184:187], v[222:225], v[86:89]
	v_mfma_f32_16x16x32_bf16 v[82:85], v[192:195], v[222:225], v[82:85]
	v_mfma_f32_16x16x32_bf16 v[78:81], v[184:187], v[230:233], v[78:81]
	v_mfma_f32_16x16x32_bf16 v[74:77], v[192:195], v[230:233], v[74:77]
	v_mfma_f32_16x16x32_bf16 v[70:73], v[184:187], v[238:241], v[70:73]
	v_mfma_f32_16x16x32_bf16 v[66:69], v[192:195], v[238:241], v[66:69]
	s_setprio 0
	s_barrier
	s_add_i32 s63, s63, 2
	s_add_u32 s28, s28, 0x100
	s_addc_u32 s29, s29, 0
	s_add_u32 s61, s61, 0x100
	s_addc_u32 s62, s62, 0
.LBB0_330:
	s_add_u32 s30, s28, 0xfffc0080
	s_addc_u32 s31, s29, -1
	s_add_i32 s64, 0, 0x10000
	s_cmp_eq_u32 s63, 12
	s_cselect_b32 s35, s21, s31
	s_cselect_b32 s34, s27, s30
	v_add_u32_e32 v156, s64, v149
	s_cselect_b32 s31, s19, s62
	s_cselect_b32 s30, s60, s61
	s_add_i32 s66, 0, 0x14000
	ds_read_b128 v[144:147], v156
	ds_read_b128 v[152:155], v156 offset:1024
	ds_read_b128 v[172:175], v156 offset:2048
	ds_read_b128 v[176:179], v156 offset:3072
	v_add_u32_e32 v156, s66, v149
	ds_read_b128 v[180:183], v156
	ds_read_b128 v[184:187], v156 offset:1024
	ds_read_b128 v[188:191], v156 offset:2048
	ds_read_b128 v[192:195], v156 offset:3072
	s_add_i32 m0, s46, 0xc000
	ds_read_b128 v[196:199], v151
	ds_read_b128 v[214:217], v151 offset:1024
	ds_read_b128 v[218:221], v151 offset:2048
	ds_read_b128 v[222:225], v151 offset:3072
	ds_read_b128 v[226:229], v151 offset:4096
	ds_read_b128 v[230:233], v151 offset:5120
	ds_read_b128 v[234:237], v151 offset:6144
	ds_read_b128 v[238:241], v151 offset:7168
	global_load_lds_dwordx4 v140, s[28:29]
	s_add_i32 m0, s46, 0xe000
	s_nop 0
	global_load_lds_dwordx4 v142, s[28:29]
	s_waitcnt vmcnt(8)
	s_waitcnt lgkmcnt(0)
	s_barrier
; #define PG8_STAGE(bufoff, gbase, voff) do { _Pragma("unroll") for (int _i = 0; _i < 2; ++_i) \
;         __builtin_amdgcn_global_load_lds((const unsigned*)((const char*)(gbase) + (voff)[_i]), (PG8_LAS unsigned*)(lds + (bufoff) + ldsw + _i * 8192), 16, 0, 0); } while (0)
; #define PG8_LDA(dst, b, h) do { _Pragma("unroll") for (int m = 0; m < 4; ++m) _Pragma("unroll") for (int k = 0; k < 2; ++k) dst[m][k] = *(const PG8_LAS bf16x8*)(lds + PG8_SA(b, h) + aoff + m * 2048 + k * 1024); } while (0)
; #define PG8_MMA(ai, bj, At, Bt) do { __builtin_amdgcn_s_setprio(1); _Pragma("unroll") for (int m = 0; m < 4; ++m) _Pragma("unroll") for (int n = 0; n < 2; ++n) _Pragma("unroll") for (int k = 0; k < 2; ++k) \
;         acc[ai][bj][m][n] = __builtin_amdgcn_mfma_f32_16x16x32_bf16(Bt[n][k], At[m][k], acc[ai][bj][m][n], 0, 0, 0); __builtin_amdgcn_s_setprio(0); } while (0)
; #define PG8_WAIT_V(n) asm volatile("s_waitcnt vmcnt(" #n ")" ::: "memory")
; #define PG8_WAIT_L(n) asm volatile("s_waitcnt lgkmcnt(" #n ")" ::: "memory")
; #define PG8_BAR __builtin_amdgcn_s_barrier()
; #define PG8_SCHED __builtin_amdgcn_sched_barrier(0)
; template <class Epi, class Sched, bool ALIGN_EPI = false, bool SP2 = false>
; __device__ __forceinline__ void gemm_phase(PG8_LAS unsigned char* lds, const Gemm g, const Sched& S, const Epi& E) {
;     ...
;             PG8_WAIT_V(8); PG8_WAIT_L(0); PG8_BAR; PG8_MMA(0, 0, At, B0); PG8_MMA(0, 1, At, B1); PG8_BAR; PG8_SCHED;
;             PG8_LDA(At, 0, 1); PG8_STAGE(PG8_SB(0, 0), b2, voffB); PG8_STAGE(PG8_SB(0, 1), b2 + hstep, voffB); PG8_STAGE(PG8_SA(0, 0), a2, voffA);
;             PG8_WAIT_V(8); PG8_WAIT_L(0); PG8_BAR; PG8_MMA(1, 0, At, B0); PG8_MMA(1, 1, At, B1); PG8_BAR; PG8_SCHED;
	s_setprio 1
	s_waitcnt lgkmcnt(0)
	v_mfma_f32_16x16x32_bf16 v[62:65], v[144:147], v[196:199], v[62:65]
	v_mfma_f32_16x16x32_bf16 v[58:61], v[172:175], v[196:199], v[58:61]
	v_mfma_f32_16x16x32_bf16 v[54:57], v[144:147], v[218:221], v[54:57]
	v_mfma_f32_16x16x32_bf16 v[50:53], v[172:175], v[218:221], v[50:53]
	v_mfma_f32_16x16x32_bf16 v[46:49], v[144:147], v[226:229], v[46:49]
	v_mfma_f32_16x16x32_bf16 v[42:45], v[172:175], v[226:229], v[42:45]
	v_mfma_f32_16x16x32_bf16 v[38:41], v[144:147], v[234:237], v[38:41]
	v_mfma_f32_16x16x32_bf16 v[34:37], v[172:175], v[234:237], v[34:37]
	v_mfma_f32_16x16x32_bf16 v[62:65], v[152:155], v[214:217], v[62:65]
	v_mfma_f32_16x16x32_bf16 v[58:61], v[176:179], v[214:217], v[58:61]
	v_mfma_f32_16x16x32_bf16 v[54:57], v[152:155], v[222:225], v[54:57]
	v_mfma_f32_16x16x32_bf16 v[50:53], v[176:179], v[222:225], v[50:53]
	v_mfma_f32_16x16x32_bf16 v[46:49], v[152:155], v[230:233], v[46:49]
	v_mfma_f32_16x16x32_bf16 v[42:45], v[176:179], v[230:233], v[42:45]
	v_mfma_f32_16x16x32_bf16 v[38:41], v[152:155], v[238:241], v[38:41]
	v_mfma_f32_16x16x32_bf16 v[34:37], v[176:179], v[238:241], v[34:37]
	v_mfma_f32_16x16x32_bf16 v[126:129], v[180:183], v[196:199], v[126:129]
	v_mfma_f32_16x16x32_bf16 v[122:125], v[188:191], v[196:199], v[122:125]
	v_mfma_f32_16x16x32_bf16 v[118:121], v[180:183], v[218:221], v[118:121]
	v_mfma_f32_16x16x32_bf16 v[114:117], v[188:191], v[218:221], v[114:117]
	v_mfma_f32_16x16x32_bf16 v[110:113], v[180:183], v[226:229], v[110:113]
	v_mfma_f32_16x16x32_bf16 v[106:109], v[188:191], v[226:229], v[106:109]
	v_mfma_f32_16x16x32_bf16 v[102:105], v[180:183], v[234:237], v[102:105]
	v_mfma_f32_16x16x32_bf16 v[98:101], v[188:191], v[234:237], v[98:101]
	v_mfma_f32_16x16x32_bf16 v[126:129], v[184:187], v[214:217], v[126:129]
	v_mfma_f32_16x16x32_bf16 v[122:125], v[192:195], v[214:217], v[122:125]
	v_mfma_f32_16x16x32_bf16 v[118:121], v[184:187], v[222:225], v[118:121]
	v_mfma_f32_16x16x32_bf16 v[114:117], v[192:195], v[222:225], v[114:117]
	v_mfma_f32_16x16x32_bf16 v[110:113], v[184:187], v[230:233], v[110:113]
	v_mfma_f32_16x16x32_bf16 v[106:109], v[192:195], v[230:233], v[106:109]
	v_mfma_f32_16x16x32_bf16 v[102:105], v[184:187], v[238:241], v[102:105]
	v_mfma_f32_16x16x32_bf16 v[98:101], v[192:195], v[238:241], v[98:101]
	s_setprio 0
	s_barrier
	s_add_i32 s64, s64, s2
	s_mov_b32 m0, s64
	ds_read_b128 v[196:199], v151 offset:16384
	ds_read_b128 v[214:217], v151 offset:17408
	ds_read_b128 v[218:221], v151 offset:18432
	ds_read_b128 v[222:225], v151 offset:19456
	ds_read_b128 v[226:229], v151 offset:20480
	ds_read_b128 v[230:233], v151 offset:21504
	ds_read_b128 v[234:237], v151 offset:22528
	ds_read_b128 v[238:241], v151 offset:23552
	global_load_lds_dwordx4 v0, s[30:31]
	s_add_i32 m0, s64, 0x2000
	s_add_u32 s64, s30, 0x40000
	s_addc_u32 s65, s31, 0
	s_add_i32 s66, s66, s2
	global_load_lds_dwordx4 v130, s[30:31]
	s_mov_b32 m0, s66
	s_nop 0
	global_load_lds_dwordx4 v0, s[64:65]
	s_add_i32 m0, s66, 0x2000
	s_nop 0
	global_load_lds_dwordx4 v130, s[64:65]
	s_mov_b32 m0, s46
	s_nop 0
	global_load_lds_dwordx4 v134, s[34:35]
	s_mov_b32 m0, s47
	s_nop 0
	global_load_lds_dwordx4 v132, s[34:35]
	s_waitcnt vmcnt(8)
	s_waitcnt lgkmcnt(0)
	s_barrier
	s_setprio 1
	s_waitcnt lgkmcnt(0)
	v_mfma_f32_16x16x32_bf16 v[30:33], v[144:147], v[196:199], v[30:33]
	v_mfma_f32_16x16x32_bf16 v[26:29], v[172:175], v[196:199], v[26:29]
	v_mfma_f32_16x16x32_bf16 v[22:25], v[144:147], v[218:221], v[22:25]
	v_mfma_f32_16x16x32_bf16 v[18:21], v[172:175], v[218:221], v[18:21]
	v_mfma_f32_16x16x32_bf16 v[14:17], v[144:147], v[226:229], v[14:17]
	v_mfma_f32_16x16x32_bf16 v[10:13], v[172:175], v[226:229], v[10:13]
	v_mfma_f32_16x16x32_bf16 v[6:9], v[144:147], v[234:237], v[6:9]
	v_mfma_f32_16x16x32_bf16 v[2:5], v[172:175], v[234:237], v[2:5]
	v_mfma_f32_16x16x32_bf16 v[30:33], v[152:155], v[214:217], v[30:33]
	v_mfma_f32_16x16x32_bf16 v[26:29], v[176:179], v[214:217], v[26:29]
	v_mfma_f32_16x16x32_bf16 v[22:25], v[152:155], v[222:225], v[22:25]
	v_mfma_f32_16x16x32_bf16 v[18:21], v[176:179], v[222:225], v[18:21]
	v_mfma_f32_16x16x32_bf16 v[14:17], v[152:155], v[230:233], v[14:17]
	v_mfma_f32_16x16x32_bf16 v[10:13], v[176:179], v[230:233], v[10:13]
	v_mfma_f32_16x16x32_bf16 v[6:9], v[152:155], v[238:241], v[6:9]
	v_mfma_f32_16x16x32_bf16 v[2:5], v[176:179], v[238:241], v[2:5]
	v_mfma_f32_16x16x32_bf16 v[94:97], v[180:183], v[196:199], v[94:97]
	v_mfma_f32_16x16x32_bf16 v[90:93], v[188:191], v[196:199], v[90:93]
	v_mfma_f32_16x16x32_bf16 v[86:89], v[180:183], v[218:221], v[86:89]
	v_mfma_f32_16x16x32_bf16 v[82:85], v[188:191], v[218:221], v[82:85]
	v_mfma_f32_16x16x32_bf16 v[78:81], v[180:183], v[226:229], v[78:81]
	v_mfma_f32_16x16x32_bf16 v[74:77], v[188:191], v[226:229], v[74:77]
	v_mfma_f32_16x16x32_bf16 v[70:73], v[180:183], v[234:237], v[70:73]
	v_mfma_f32_16x16x32_bf16 v[66:69], v[188:191], v[234:237], v[66:69]
	v_mfma_f32_16x16x32_bf16 v[94:97], v[184:187], v[214:217], v[94:97]
	v_mfma_f32_16x16x32_bf16 v[90:93], v[192:195], v[214:217], v[90:93]
	v_mfma_f32_16x16x32_bf16 v[86:89], v[184:187], v[222:225], v[86:89]
	v_mfma_f32_16x16x32_bf16 v[82:85], v[192:195], v[222:225], v[82:85]
	v_mfma_f32_16x16x32_bf16 v[78:81], v[184:187], v[230:233], v[78:81]
	v_mfma_f32_16x16x32_bf16 v[74:77], v[192:195], v[230:233], v[74:77]
	v_mfma_f32_16x16x32_bf16 v[70:73], v[184:187], v[238:241], v[70:73]
	v_mfma_f32_16x16x32_bf16 v[66:69], v[192:195], v[238:241], v[66:69]
	s_setprio 0
	s_barrier
; #define PG8_STAGE(bufoff, gbase, voff) do { _Pragma("unroll") for (int _i = 0; _i < 2; ++_i) \
;         __builtin_amdgcn_global_load_lds((const unsigned*)((const char*)(gbase) + (voff)[_i]), (PG8_LAS unsigned*)(lds + (bufoff) + ldsw + _i * 8192), 16, 0, 0); } while (0)
; #define PG8_BAR __builtin_amdgcn_s_barrier()
; template <class Epi, class Sched, bool ALIGN_EPI = false, bool SP2 = false>
; __device__ __forceinline__ void gemm_phase(PG8_LAS unsigned char* lds, const Gemm g, const Sched& S, const Epi& E) {
;     ...
;             PG8_LDB(B0, 1, 0); PG8_LDB(B1, 1, 1); PG8_SCHED; PG8_LDA(At, 1, 0); PG8_STAGE(PG8_SA(0, 1), a2 + hstep, voffA);
;             PG8_WAIT_V(8); PG8_WAIT_L(0); PG8_BAR; PG8_MMA(0, 0, At, B0); PG8_MMA(0, 1, At, B1); PG8_BAR; PG8_SCHED;
;             PG8_LDA(At, 1, 1); PG8_STAGE(PG8_SB(1, 0), b3, voffB); PG8_STAGE(PG8_SB(1, 1), b3 + hstep, voffB); PG8_STAGE(PG8_SA(1, 0), a3, voffA);
;             PG8_WAIT_V(8); PG8_WAIT_L(0); PG8_BAR; PG8_MMA(1, 0, At, B0); PG8_MMA(1, 1, At, B1); PG8_BAR; PG8_SCHED;
;             } else {
;             PG8_LDB(B0, 0, 0); PG8_SCHED; PG8_LDA(At, 0, 0); PG8_STAGE(PG8_SA(1, 1), a1 + hstep, voffA);
;             PG8_WAIT_L(8); PG8_BAR; PG8_WAIT_L(0); PG8_MMA(0, 0, At, B0); PG8_BAR; PG8_SCHED;
;             PG8_LDB(B1, 0, 1); PG8_STAGE(PG8_SB(0, 0), b2, voffB);
;             PG8_BAR; PG8_WAIT_L(0); PG8_MMA(0, 1, At, B1); PG8_BAR;
;             PG8_LDA(At, 0, 1); PG8_STAGE(PG8_SA(0, 0), a2, voffA);
;             PG8_BAR; PG8_WAIT_L(0); PG8_MMA(1, 0, At, B0); PG8_BAR; PG8_SCHED;
;             PG8_STAGE(PG8_SB(0, 1), b2 + hstep, voffB);
;             PG8_WAIT_V(6); PG8_BAR; PG8_MMA(1, 1, At, B1); PG8_BAR;
;             PG8_LDB(B0, 1, 0); PG8_SCHED; PG8_LDA(At, 1, 0); PG8_STAGE(PG8_SA(0, 1), a2 + hstep, voffA);
;             PG8_WAIT_L(8); PG8_BAR; PG8_WAIT_L(0); PG8_MMA(0, 0, At, B0); PG8_BAR; PG8_SCHED;
;             PG8_LDB(B1, 1, 1); PG8_STAGE(PG8_SB(1, 0), b3, voffB);
;             PG8_BAR; PG8_WAIT_L(0); PG8_MMA(0, 1, At, B1); PG8_BAR;
;             PG8_LDA(At, 1, 1); PG8_STAGE(PG8_SA(1, 0), a3, voffA);
;             PG8_BAR; PG8_WAIT_L(0); PG8_MMA(1, 0, At, B0); PG8_BAR; PG8_SCHED;
;             PG8_STAGE(PG8_SB(1, 1), b3 + hstep, voffB);
;             PG8_WAIT_V(6); PG8_BAR; PG8_MMA(1, 1, At, B1); PG8_BAR;
;             }
;         }
;         if constexpr (ALIGN_EPI) { if (wr == 0) PG8_BAR; }
	s_add_i32 s64, 0, 0x18000
	v_add_u32_e32 v158, s64, v149
	s_add_i32 s65, 0, 0x1c000
	ds_read_b128 v[144:147], v158
	ds_read_b128 v[152:155], v158 offset:1024
	ds_read_b128 v[172:175], v158 offset:2048
	ds_read_b128 v[176:179], v158 offset:3072
	v_add_u32_e32 v158, s65, v149
	ds_read_b128 v[180:183], v158
	ds_read_b128 v[184:187], v158 offset:1024
	ds_read_b128 v[188:191], v158 offset:2048
	ds_read_b128 v[192:195], v158 offset:3072
	s_add_u32 s34, s34, 0x40000
	s_addc_u32 s35, s35, 0
	s_mov_b32 m0, s48
	ds_read_b128 v[196:199], v151 offset:32768
	ds_read_b128 v[214:217], v151 offset:33792
	ds_read_b128 v[218:221], v151 offset:34816
	ds_read_b128 v[222:225], v151 offset:35840
	ds_read_b128 v[226:229], v151 offset:36864
	ds_read_b128 v[230:233], v151 offset:37888
	ds_read_b128 v[234:237], v151 offset:38912
	ds_read_b128 v[238:241], v151 offset:39936
	global_load_lds_dwordx4 v134, s[34:35]
	s_mov_b32 m0, s49
	s_nop 0
	global_load_lds_dwordx4 v132, s[34:35]
	s_waitcnt vmcnt(8)
	s_waitcnt lgkmcnt(0)
	s_barrier
	s_setprio 1
	s_waitcnt lgkmcnt(0)
	v_mfma_f32_16x16x32_bf16 v[62:65], v[144:147], v[196:199], v[62:65]
	v_mfma_f32_16x16x32_bf16 v[58:61], v[172:175], v[196:199], v[58:61]
	v_mfma_f32_16x16x32_bf16 v[54:57], v[144:147], v[218:221], v[54:57]
	v_mfma_f32_16x16x32_bf16 v[50:53], v[172:175], v[218:221], v[50:53]
	v_mfma_f32_16x16x32_bf16 v[46:49], v[144:147], v[226:229], v[46:49]
	v_mfma_f32_16x16x32_bf16 v[42:45], v[172:175], v[226:229], v[42:45]
	v_mfma_f32_16x16x32_bf16 v[38:41], v[144:147], v[234:237], v[38:41]
	v_mfma_f32_16x16x32_bf16 v[34:37], v[172:175], v[234:237], v[34:37]
	v_mfma_f32_16x16x32_bf16 v[62:65], v[152:155], v[214:217], v[62:65]
	v_mfma_f32_16x16x32_bf16 v[58:61], v[176:179], v[214:217], v[58:61]
	v_mfma_f32_16x16x32_bf16 v[54:57], v[152:155], v[222:225], v[54:57]
	v_mfma_f32_16x16x32_bf16 v[50:53], v[176:179], v[222:225], v[50:53]
	v_mfma_f32_16x16x32_bf16 v[46:49], v[152:155], v[230:233], v[46:49]
	v_mfma_f32_16x16x32_bf16 v[42:45], v[176:179], v[230:233], v[42:45]
	v_mfma_f32_16x16x32_bf16 v[38:41], v[152:155], v[238:241], v[38:41]
	v_mfma_f32_16x16x32_bf16 v[34:37], v[176:179], v[238:241], v[34:37]
	v_mfma_f32_16x16x32_bf16 v[126:129], v[180:183], v[196:199], v[126:129]
	v_mfma_f32_16x16x32_bf16 v[122:125], v[188:191], v[196:199], v[122:125]
	v_mfma_f32_16x16x32_bf16 v[118:121], v[180:183], v[218:221], v[118:121]
	v_mfma_f32_16x16x32_bf16 v[114:117], v[188:191], v[218:221], v[114:117]
	v_mfma_f32_16x16x32_bf16 v[110:113], v[180:183], v[226:229], v[110:113]
	v_mfma_f32_16x16x32_bf16 v[106:109], v[188:191], v[226:229], v[106:109]
	v_mfma_f32_16x16x32_bf16 v[102:105], v[180:183], v[234:237], v[102:105]
	v_mfma_f32_16x16x32_bf16 v[98:101], v[188:191], v[234:237], v[98:101]
	v_mfma_f32_16x16x32_bf16 v[126:129], v[184:187], v[214:217], v[126:129]
	v_mfma_f32_16x16x32_bf16 v[122:125], v[192:195], v[214:217], v[122:125]
	v_mfma_f32_16x16x32_bf16 v[118:121], v[184:187], v[222:225], v[118:121]
	v_mfma_f32_16x16x32_bf16 v[114:117], v[192:195], v[222:225], v[114:117]
	v_mfma_f32_16x16x32_bf16 v[110:113], v[184:187], v[230:233], v[110:113]
	v_mfma_f32_16x16x32_bf16 v[106:109], v[192:195], v[230:233], v[106:109]
	v_mfma_f32_16x16x32_bf16 v[102:105], v[184:187], v[238:241], v[102:105]
	v_mfma_f32_16x16x32_bf16 v[98:101], v[192:195], v[238:241], v[98:101]
	s_setprio 0
	s_barrier
	s_add_u32 s98, s34, 0xfffc0080
	s_addc_u32 s99, s35, -1
	s_add_i32 s34, s64, s2
	s_add_u32 s100, s30, 0x80
	s_addc_u32 s101, s31, 0
	s_mov_b32 m0, s34
	ds_read_b128 v[196:199], v151 offset:49152
	ds_read_b128 v[214:217], v151 offset:50176
	ds_read_b128 v[218:221], v151 offset:51200
	ds_read_b128 v[222:225], v151 offset:52224
	ds_read_b128 v[226:229], v151 offset:53248
	ds_read_b128 v[230:233], v151 offset:54272
	ds_read_b128 v[234:237], v151 offset:55296
	ds_read_b128 v[238:241], v151 offset:56320
	global_load_lds_dwordx4 v0, s[100:101]
	s_add_i32 m0, s34, 0x2000
	s_add_u32 s30, s30, 0x40080
	s_addc_u32 s31, s31, 0
	s_add_i32 s34, s65, s2
	global_load_lds_dwordx4 v130, s[100:101]
	s_mov_b32 m0, s34
	s_nop 0
	global_load_lds_dwordx4 v0, s[30:31]
	s_add_i32 m0, s34, 0x2000
	s_nop 0
	global_load_lds_dwordx4 v130, s[30:31]
	s_mov_b32 m0, s52
	s_nop 0
	global_load_lds_dwordx4 v134, s[98:99]
	s_mov_b32 m0, s53
	s_nop 0
	global_load_lds_dwordx4 v132, s[98:99]
	s_waitcnt vmcnt(8)
	s_waitcnt lgkmcnt(0)
	s_barrier
	s_setprio 1
	s_waitcnt lgkmcnt(0)
	v_mfma_f32_16x16x32_bf16 v[30:33], v[144:147], v[196:199], v[30:33]
	v_mfma_f32_16x16x32_bf16 v[26:29], v[172:175], v[196:199], v[26:29]
	v_mfma_f32_16x16x32_bf16 v[22:25], v[144:147], v[218:221], v[22:25]
	v_mfma_f32_16x16x32_bf16 v[18:21], v[172:175], v[218:221], v[18:21]
	v_mfma_f32_16x16x32_bf16 v[14:17], v[144:147], v[226:229], v[14:17]
	v_mfma_f32_16x16x32_bf16 v[10:13], v[172:175], v[226:229], v[10:13]
	v_mfma_f32_16x16x32_bf16 v[6:9], v[144:147], v[234:237], v[6:9]
	v_mfma_f32_16x16x32_bf16 v[2:5], v[172:175], v[234:237], v[2:5]
	v_mfma_f32_16x16x32_bf16 v[30:33], v[152:155], v[214:217], v[30:33]
	v_mfma_f32_16x16x32_bf16 v[26:29], v[176:179], v[214:217], v[26:29]
	v_mfma_f32_16x16x32_bf16 v[22:25], v[152:155], v[222:225], v[22:25]
	v_mfma_f32_16x16x32_bf16 v[18:21], v[176:179], v[222:225], v[18:21]
	v_mfma_f32_16x16x32_bf16 v[14:17], v[152:155], v[230:233], v[14:17]
	v_mfma_f32_16x16x32_bf16 v[10:13], v[176:179], v[230:233], v[10:13]
	v_mfma_f32_16x16x32_bf16 v[6:9], v[152:155], v[238:241], v[6:9]
	v_mfma_f32_16x16x32_bf16 v[2:5], v[176:179], v[238:241], v[2:5]
	v_mfma_f32_16x16x32_bf16 v[94:97], v[180:183], v[196:199], v[94:97]
	v_mfma_f32_16x16x32_bf16 v[90:93], v[188:191], v[196:199], v[90:93]
	v_mfma_f32_16x16x32_bf16 v[86:89], v[180:183], v[218:221], v[86:89]
	v_mfma_f32_16x16x32_bf16 v[82:85], v[188:191], v[218:221], v[82:85]
	v_mfma_f32_16x16x32_bf16 v[78:81], v[180:183], v[226:229], v[78:81]
	v_mfma_f32_16x16x32_bf16 v[74:77], v[188:191], v[226:229], v[74:77]
	v_mfma_f32_16x16x32_bf16 v[70:73], v[180:183], v[234:237], v[70:73]
	v_mfma_f32_16x16x32_bf16 v[66:69], v[188:191], v[234:237], v[66:69]
	v_mfma_f32_16x16x32_bf16 v[94:97], v[184:187], v[214:217], v[94:97]
	v_mfma_f32_16x16x32_bf16 v[90:93], v[192:195], v[214:217], v[90:93]
	v_mfma_f32_16x16x32_bf16 v[86:89], v[184:187], v[222:225], v[86:89]
	v_mfma_f32_16x16x32_bf16 v[82:85], v[192:195], v[222:225], v[82:85]
	v_mfma_f32_16x16x32_bf16 v[78:81], v[184:187], v[230:233], v[78:81]
	v_mfma_f32_16x16x32_bf16 v[74:77], v[192:195], v[230:233], v[74:77]
	v_mfma_f32_16x16x32_bf16 v[70:73], v[184:187], v[238:241], v[70:73]
	v_mfma_f32_16x16x32_bf16 v[66:69], v[192:195], v[238:241], v[66:69]
	s_setprio 0
	s_barrier
	s_add_i32 s63, s63, 2
	s_add_u32 s28, s28, 0x100
	s_addc_u32 s29, s29, 0
	s_add_u32 s61, s61, 0x100
	s_addc_u32 s62, s62, 0
	s_cmp_gt_u32 s63, 13
	s_cbranch_scc0 .LBB0_330
	s_and_b64 vcc, exec, s[14:15]
	s_cbranch_vccz .LBB0_333
	s_barrier

; #define PG8_STAGE(bufoff, gbase, voff) do { _Pragma("unroll") for (int _i = 0; _i < 2; ++_i) \
;         __builtin_amdgcn_global_load_lds((const unsigned*)((const char*)(gbase) + (voff)[_i]), (PG8_LAS unsigned*)(lds + (bufoff) + ldsw + _i * 8192), 16, 0, 0); } while (0)
; #define PG8_LDA(dst, b, h) do { _Pragma("unroll") for (int m = 0; m < 4; ++m) _Pragma("unroll") for (int k = 0; k < 2; ++k) dst[m][k] = *(const PG8_LAS bf16x8*)(lds + PG8_SA(b, h) + aoff + m * 2048 + k * 1024); } while (0)
; #define PG8_LDB(dst, b, h) do { _Pragma("unroll") for (int n = 0; n < 2; ++n) _Pragma("unroll") for (int k = 0; k < 2; ++k) dst[n][k] = *(const PG8_LAS bf16x8*)(lds + PG8_SB(b, h) + boff + n * 2048 + k * 1024); } while (0)
; #define PG8_WAIT_V(n) asm volatile("s_waitcnt vmcnt(" #n ")" ::: "memory")
; #define PG8_WAIT_L(n) asm volatile("s_waitcnt lgkmcnt(" #n ")" ::: "memory")
; #define PG8_BAR __builtin_amdgcn_s_barrier()
; #define PG8_SCHED __builtin_amdgcn_sched_barrier(0)
; template <class Epi, class Sched, bool ALIGN_EPI = false, bool SP2 = false>
; __device__ __forceinline__ void gemm_phase(PG8_LAS unsigned char* lds, const Gemm g, const Sched& S, const Epi& E) {
;     ...
;         const bool has_next = S.next(ui + 1, nxt);
;         const char* nA = has_next ? (const char*)g.A + (size_t)nxt.pm * tstep : cA; const char* nB = has_next ? (const char*)g.Bt + (size_t)nxt.pn * tstep : cB;
;         for (int t = 0; t < nt; t += 2) {
;             const bool last = (t == nt - 2);
;             const char* a1 = cA + (size_t)(t + 1) * kstep;
;             const char* a2 = last ? nA : cA + (size_t)(t + 2) * kstep; const char* b2 = last ? nB : cB + (size_t)(t + 2) * kstep;
;             const char* a3 = a2 + kstep; const char* b3 = b2 + kstep;
;             if (last && has_next) S.a_ready(nxt);
;             if constexpr (SP2) {
;             PG8_LDB(B0, 0, 0); PG8_LDB(B1, 0, 1); PG8_SCHED; PG8_LDA(At, 0, 0); PG8_STAGE(PG8_SA(1, 1), a1 + hstep, voffA);
;             PG8_WAIT_V(8); PG8_WAIT_L(0); PG8_BAR; PG8_MMA(0, 0, At, B0); PG8_MMA(0, 1, At, B1); PG8_BAR; PG8_SCHED;
;             PG8_LDA(At, 0, 1); PG8_STAGE(PG8_SB(0, 0), b2, voffB); PG8_STAGE(PG8_SB(0, 1), b2 + hstep, voffB); PG8_STAGE(PG8_SA(0, 0), a2, voffA);
;             PG8_WAIT_V(8); PG8_WAIT_L(0); PG8_BAR; PG8_MMA(1, 0, At, B0); PG8_MMA(1, 1, At, B1); PG8_BAR; PG8_SCHED;
.LBB0_458:
	s_add_u32 s47, s20, 0x100
	s_addc_u32 s48, s21, 0
	s_mov_b32 s49, -2
	s_waitcnt lgkmcnt(0)
	s_waitcnt vmcnt(0)
	s_add_u32 s20, s18, 0x100
	s_addc_u32 s21, s19, 0
	s_add_i32 s50, 0, 0x10000
	s_cmp_eq_u32 s49, 40
	s_cselect_b32 s25, s9, s21
	s_cselect_b32 s24, s8, s20
	s_cselect_b32 s23, s17, s48
	s_cselect_b32 s22, s16, s47
	s_add_i32 s51, 0, 0x14000
	v_add_u32_e32 v142, s50, v165
	v_add_u32_e32 v182, s51, v165
	ds_read_b128 v[130:133], v142
	ds_read_b128 v[134:137], v142 offset:1024
	ds_read_b128 v[138:141], v142 offset:2048
	ds_read_b128 v[142:145], v142 offset:3072
	ds_read_b128 v[146:149], v182
	ds_read_b128 v[150:153], v182 offset:1024
	ds_read_b128 v[154:157], v182 offset:2048
	ds_read_b128 v[182:185], v182 offset:3072
	s_add_i32 m0, s28, 0xc000
	ds_read_b128 v[186:189], v214
	ds_read_b128 v[190:193], v214 offset:1024
	ds_read_b128 v[194:197], v214 offset:2048
	ds_read_b128 v[216:219], v214 offset:3072
	ds_read_b128 v[220:223], v214 offset:4096
	ds_read_b128 v[224:227], v214 offset:5120
	ds_read_b128 v[228:231], v214 offset:6144
	ds_read_b128 v[232:235], v214 offset:7168
	global_load_lds_dwordx4 v178, s[18:19]
	s_add_i32 m0, s28, 0xe000
	s_nop 0
	global_load_lds_dwordx4 v180, s[18:19]
	s_waitcnt vmcnt(8)
	s_waitcnt lgkmcnt(0)
	s_barrier
	s_setprio 1
	s_waitcnt lgkmcnt(0)
	v_mfma_f32_16x16x32_bf16 v[126:129], v[130:133], v[186:189], 0
	v_mfma_f32_16x16x32_bf16 v[122:125], v[138:141], v[186:189], 0
	v_mfma_f32_16x16x32_bf16 v[110:113], v[130:133], v[194:197], 0
	v_mfma_f32_16x16x32_bf16 v[106:109], v[138:141], v[194:197], 0
	v_mfma_f32_16x16x32_bf16 v[94:97], v[130:133], v[220:223], 0
	v_mfma_f32_16x16x32_bf16 v[90:93], v[138:141], v[220:223], 0
	v_mfma_f32_16x16x32_bf16 v[78:81], v[130:133], v[228:231], 0
	v_mfma_f32_16x16x32_bf16 v[74:77], v[138:141], v[228:231], 0
	v_mfma_f32_16x16x32_bf16 v[126:129], v[134:137], v[190:193], v[126:129]
	v_mfma_f32_16x16x32_bf16 v[122:125], v[142:145], v[190:193], v[122:125]
	v_mfma_f32_16x16x32_bf16 v[110:113], v[134:137], v[216:219], v[110:113]
	v_mfma_f32_16x16x32_bf16 v[106:109], v[142:145], v[216:219], v[106:109]
	v_mfma_f32_16x16x32_bf16 v[94:97], v[134:137], v[224:227], v[94:97]
	v_mfma_f32_16x16x32_bf16 v[90:93], v[142:145], v[224:227], v[90:93]
	v_mfma_f32_16x16x32_bf16 v[78:81], v[134:137], v[232:235], v[78:81]
	v_mfma_f32_16x16x32_bf16 v[74:77], v[142:145], v[232:235], v[74:77]
	v_mfma_f32_16x16x32_bf16 v[118:121], v[146:149], v[186:189], 0
	v_mfma_f32_16x16x32_bf16 v[114:117], v[154:157], v[186:189], 0
	v_mfma_f32_16x16x32_bf16 v[102:105], v[146:149], v[194:197], 0
	v_mfma_f32_16x16x32_bf16 v[98:101], v[154:157], v[194:197], 0
	v_mfma_f32_16x16x32_bf16 v[86:89], v[146:149], v[220:223], 0
	v_mfma_f32_16x16x32_bf16 v[82:85], v[154:157], v[220:223], 0
	v_mfma_f32_16x16x32_bf16 v[70:73], v[146:149], v[228:231], 0
	v_mfma_f32_16x16x32_bf16 v[66:69], v[154:157], v[228:231], 0
	v_mfma_f32_16x16x32_bf16 v[118:121], v[150:153], v[190:193], v[118:121]
	v_mfma_f32_16x16x32_bf16 v[114:117], v[182:185], v[190:193], v[114:117]
	v_mfma_f32_16x16x32_bf16 v[102:105], v[150:153], v[216:219], v[102:105]
	v_mfma_f32_16x16x32_bf16 v[98:101], v[182:185], v[216:219], v[98:101]
	v_mfma_f32_16x16x32_bf16 v[86:89], v[150:153], v[224:227], v[86:89]
	v_mfma_f32_16x16x32_bf16 v[82:85], v[182:185], v[224:227], v[82:85]
	v_mfma_f32_16x16x32_bf16 v[70:73], v[150:153], v[232:235], v[70:73]
	v_mfma_f32_16x16x32_bf16 v[66:69], v[182:185], v[232:235], v[66:69]
	s_setprio 0
	s_barrier
	s_add_i32 s18, s50, s2
	s_mov_b32 m0, s18
	ds_read_b128 v[186:189], v214 offset:16384
	ds_read_b128 v[190:193], v214 offset:17408
	ds_read_b128 v[194:197], v214 offset:18432
	ds_read_b128 v[216:219], v214 offset:19456
	ds_read_b128 v[220:223], v214 offset:20480
	ds_read_b128 v[224:227], v214 offset:21504
	ds_read_b128 v[228:231], v214 offset:22528
	ds_read_b128 v[232:235], v214 offset:23552
	global_load_lds_dwordx4 v0, s[22:23]
	s_add_i32 m0, s18, 0x2000
	s_add_u32 s18, s22, 0xb0000
	s_addc_u32 s19, s23, 0
	s_add_i32 s50, s51, s2
	global_load_lds_dwordx4 v172, s[22:23]
	s_mov_b32 m0, s50
	s_nop 0
	global_load_lds_dwordx4 v0, s[18:19]
	s_add_i32 m0, s50, 0x2000
	s_nop 0
	global_load_lds_dwordx4 v172, s[18:19]
	s_mov_b32 m0, s28
	s_nop 0
	global_load_lds_dwordx4 v176, s[24:25]
	s_mov_b32 m0, s29
	s_nop 0
	global_load_lds_dwordx4 v174, s[24:25]
	s_waitcnt vmcnt(8)
	s_waitcnt lgkmcnt(0)
	s_barrier
	s_setprio 1
	s_waitcnt lgkmcnt(0)
	v_mfma_f32_16x16x32_bf16 v[62:65], v[130:133], v[186:189], 0
	v_mfma_f32_16x16x32_bf16 v[58:61], v[138:141], v[186:189], 0
	v_mfma_f32_16x16x32_bf16 v[46:49], v[130:133], v[194:197], 0
	v_mfma_f32_16x16x32_bf16 v[42:45], v[138:141], v[194:197], 0
	v_mfma_f32_16x16x32_bf16 v[30:33], v[130:133], v[220:223], 0
	v_mfma_f32_16x16x32_bf16 v[26:29], v[138:141], v[220:223], 0
	v_mfma_f32_16x16x32_bf16 v[14:17], v[130:133], v[228:231], 0
	v_mfma_f32_16x16x32_bf16 v[10:13], v[138:141], v[228:231], 0
	v_mfma_f32_16x16x32_bf16 v[62:65], v[134:137], v[190:193], v[62:65]
	v_mfma_f32_16x16x32_bf16 v[58:61], v[142:145], v[190:193], v[58:61]
	v_mfma_f32_16x16x32_bf16 v[46:49], v[134:137], v[216:219], v[46:49]
	v_mfma_f32_16x16x32_bf16 v[42:45], v[142:145], v[216:219], v[42:45]
	v_mfma_f32_16x16x32_bf16 v[30:33], v[134:137], v[224:227], v[30:33]
	v_mfma_f32_16x16x32_bf16 v[26:29], v[142:145], v[224:227], v[26:29]
	v_mfma_f32_16x16x32_bf16 v[14:17], v[134:137], v[232:235], v[14:17]
	v_mfma_f32_16x16x32_bf16 v[10:13], v[142:145], v[232:235], v[10:13]
	v_mfma_f32_16x16x32_bf16 v[54:57], v[146:149], v[186:189], 0
	v_mfma_f32_16x16x32_bf16 v[50:53], v[154:157], v[186:189], 0
	v_mfma_f32_16x16x32_bf16 v[38:41], v[146:149], v[194:197], 0
	v_mfma_f32_16x16x32_bf16 v[34:37], v[154:157], v[194:197], 0
	v_mfma_f32_16x16x32_bf16 v[22:25], v[146:149], v[220:223], 0
	v_mfma_f32_16x16x32_bf16 v[18:21], v[154:157], v[220:223], 0
	v_mfma_f32_16x16x32_bf16 v[6:9], v[146:149], v[228:231], 0
	v_mfma_f32_16x16x32_bf16 v[2:5], v[154:157], v[228:231], 0
	v_mfma_f32_16x16x32_bf16 v[54:57], v[150:153], v[190:193], v[54:57]
	v_mfma_f32_16x16x32_bf16 v[50:53], v[182:185], v[190:193], v[50:53]
	v_mfma_f32_16x16x32_bf16 v[38:41], v[150:153], v[216:219], v[38:41]
	v_mfma_f32_16x16x32_bf16 v[34:37], v[182:185], v[216:219], v[34:37]
	v_mfma_f32_16x16x32_bf16 v[22:25], v[150:153], v[224:227], v[22:25]
	v_mfma_f32_16x16x32_bf16 v[18:21], v[182:185], v[224:227], v[18:21]
	v_mfma_f32_16x16x32_bf16 v[6:9], v[150:153], v[232:235], v[6:9]
	v_mfma_f32_16x16x32_bf16 v[2:5], v[182:185], v[232:235], v[2:5]
	s_setprio 0
	s_barrier
; #define PG8_STAGE(bufoff, gbase, voff) do { _Pragma("unroll") for (int _i = 0; _i < 2; ++_i) \
;         __builtin_amdgcn_global_load_lds((const unsigned*)((const char*)(gbase) + (voff)[_i]), (PG8_LAS unsigned*)(lds + (bufoff) + ldsw + _i * 8192), 16, 0, 0); } while (0)
; #define PG8_LDA(dst, b, h) do { _Pragma("unroll") for (int m = 0; m < 4; ++m) _Pragma("unroll") for (int k = 0; k < 2; ++k) dst[m][k] = *(const PG8_LAS bf16x8*)(lds + PG8_SA(b, h) + aoff + m * 2048 + k * 1024); } while (0)
; #define PG8_LDB(dst, b, h) do { _Pragma("unroll") for (int n = 0; n < 2; ++n) _Pragma("unroll") for (int k = 0; k < 2; ++k) dst[n][k] = *(const PG8_LAS bf16x8*)(lds + PG8_SB(b, h) + boff + n * 2048 + k * 1024); } while (0)
; #define PG8_MMA(ai, bj, At, Bt) do { __builtin_amdgcn_s_setprio(1); _Pragma("unroll") for (int m = 0; m < 4; ++m) _Pragma("unroll") for (int n = 0; n < 2; ++n) _Pragma("unroll") for (int k = 0; k < 2; ++k) \
;         acc[ai][bj][m][n] = __builtin_amdgcn_mfma_f32_16x16x32_bf16(Bt[n][k], At[m][k], acc[ai][bj][m][n], 0, 0, 0); __builtin_amdgcn_s_setprio(0); } while (0)
; #define PG8_WAIT_V(n) asm volatile("s_waitcnt vmcnt(" #n ")" ::: "memory")
; #define PG8_WAIT_L(n) asm volatile("s_waitcnt lgkmcnt(" #n ")" ::: "memory")
; #define PG8_BAR __builtin_amdgcn_s_barrier()
; #define PG8_SCHED __builtin_amdgcn_sched_barrier(0)
; template <class Epi, class Sched, bool ALIGN_EPI = false, bool SP2 = false>
; __device__ __forceinline__ void gemm_phase(PG8_LAS unsigned char* lds, const Gemm g, const Sched& S, const Epi& E) {
;     ...
;             PG8_LDB(B0, 1, 0); PG8_LDB(B1, 1, 1); PG8_SCHED; PG8_LDA(At, 1, 0); PG8_STAGE(PG8_SA(0, 1), a2 + hstep, voffA);
;             PG8_WAIT_V(8); PG8_WAIT_L(0); PG8_BAR; PG8_MMA(0, 0, At, B0); PG8_MMA(0, 1, At, B1); PG8_BAR; PG8_SCHED;
;             PG8_LDA(At, 1, 1); PG8_STAGE(PG8_SB(1, 0), b3, voffB); PG8_STAGE(PG8_SB(1, 1), b3 + hstep, voffB); PG8_STAGE(PG8_SA(1, 0), a3, voffA);
;             PG8_WAIT_V(8); PG8_WAIT_L(0); PG8_BAR; PG8_MMA(1, 0, At, B0); PG8_MMA(1, 1, At, B1); PG8_BAR; PG8_SCHED;
	s_add_i32 s50, 0, 0x18000
	s_add_i32 s51, 0, 0x1c000
	v_add_u32_e32 v142, s50, v165
	v_add_u32_e32 v182, s51, v165
	ds_read_b128 v[130:133], v142
	ds_read_b128 v[134:137], v142 offset:1024
	ds_read_b128 v[138:141], v142 offset:2048
	ds_read_b128 v[142:145], v142 offset:3072
	ds_read_b128 v[146:149], v182
	ds_read_b128 v[150:153], v182 offset:1024
	ds_read_b128 v[154:157], v182 offset:2048
	ds_read_b128 v[182:185], v182 offset:3072
	s_add_u32 s18, s24, 0xb0000
	s_addc_u32 s19, s25, 0
	s_mov_b32 m0, s30
	ds_read_b128 v[186:189], v214 offset:32768
	ds_read_b128 v[190:193], v214 offset:33792
	ds_read_b128 v[194:197], v214 offset:34816
	ds_read_b128 v[216:219], v214 offset:35840
	ds_read_b128 v[220:223], v214 offset:36864
	ds_read_b128 v[224:227], v214 offset:37888
	ds_read_b128 v[228:231], v214 offset:38912
	ds_read_b128 v[232:235], v214 offset:39936
	global_load_lds_dwordx4 v176, s[18:19]
	s_mov_b32 m0, s31
	s_nop 0
	global_load_lds_dwordx4 v174, s[18:19]
	s_waitcnt vmcnt(8)
	s_waitcnt lgkmcnt(0)
	s_barrier
	s_setprio 1
	s_waitcnt lgkmcnt(0)
	v_mfma_f32_16x16x32_bf16 v[126:129], v[130:133], v[186:189], v[126:129]
	v_mfma_f32_16x16x32_bf16 v[122:125], v[138:141], v[186:189], v[122:125]
	v_mfma_f32_16x16x32_bf16 v[110:113], v[130:133], v[194:197], v[110:113]
	v_mfma_f32_16x16x32_bf16 v[106:109], v[138:141], v[194:197], v[106:109]
	v_mfma_f32_16x16x32_bf16 v[94:97], v[130:133], v[220:223], v[94:97]
	v_mfma_f32_16x16x32_bf16 v[90:93], v[138:141], v[220:223], v[90:93]
	v_mfma_f32_16x16x32_bf16 v[78:81], v[130:133], v[228:231], v[78:81]
	v_mfma_f32_16x16x32_bf16 v[74:77], v[138:141], v[228:231], v[74:77]
	v_mfma_f32_16x16x32_bf16 v[126:129], v[134:137], v[190:193], v[126:129]
	v_mfma_f32_16x16x32_bf16 v[122:125], v[142:145], v[190:193], v[122:125]
	v_mfma_f32_16x16x32_bf16 v[110:113], v[134:137], v[216:219], v[110:113]
	v_mfma_f32_16x16x32_bf16 v[106:109], v[142:145], v[216:219], v[106:109]
	v_mfma_f32_16x16x32_bf16 v[94:97], v[134:137], v[224:227], v[94:97]
	v_mfma_f32_16x16x32_bf16 v[90:93], v[142:145], v[224:227], v[90:93]
	v_mfma_f32_16x16x32_bf16 v[78:81], v[134:137], v[232:235], v[78:81]
	v_mfma_f32_16x16x32_bf16 v[74:77], v[142:145], v[232:235], v[74:77]
	v_mfma_f32_16x16x32_bf16 v[118:121], v[146:149], v[186:189], v[118:121]
	v_mfma_f32_16x16x32_bf16 v[114:117], v[154:157], v[186:189], v[114:117]
	v_mfma_f32_16x16x32_bf16 v[102:105], v[146:149], v[194:197], v[102:105]
	v_mfma_f32_16x16x32_bf16 v[98:101], v[154:157], v[194:197], v[98:101]
	v_mfma_f32_16x16x32_bf16 v[86:89], v[146:149], v[220:223], v[86:89]
	v_mfma_f32_16x16x32_bf16 v[82:85], v[154:157], v[220:223], v[82:85]
	v_mfma_f32_16x16x32_bf16 v[70:73], v[146:149], v[228:231], v[70:73]
	v_mfma_f32_16x16x32_bf16 v[66:69], v[154:157], v[228:231], v[66:69]
	v_mfma_f32_16x16x32_bf16 v[118:121], v[150:153], v[190:193], v[118:121]
	v_mfma_f32_16x16x32_bf16 v[114:117], v[182:185], v[190:193], v[114:117]
	v_mfma_f32_16x16x32_bf16 v[102:105], v[150:153], v[216:219], v[102:105]
	v_mfma_f32_16x16x32_bf16 v[98:101], v[182:185], v[216:219], v[98:101]
	v_mfma_f32_16x16x32_bf16 v[86:89], v[150:153], v[224:227], v[86:89]
	v_mfma_f32_16x16x32_bf16 v[82:85], v[182:185], v[224:227], v[82:85]
	v_mfma_f32_16x16x32_bf16 v[70:73], v[150:153], v[232:235], v[70:73]
	v_mfma_f32_16x16x32_bf16 v[66:69], v[182:185], v[232:235], v[66:69]
	s_setprio 0
	s_barrier
	s_add_i32 s18, s50, s2
	s_add_u32 s98, s22, 0x80
	s_addc_u32 s99, s23, 0
	s_add_u32 s100, s24, 0x80
	s_addc_u32 s101, s25, 0
	s_mov_b32 m0, s18
	ds_read_b128 v[186:189], v214 offset:49152
	ds_read_b128 v[190:193], v214 offset:50176
	ds_read_b128 v[194:197], v214 offset:51200
	ds_read_b128 v[216:219], v214 offset:52224
	ds_read_b128 v[220:223], v214 offset:53248
	ds_read_b128 v[224:227], v214 offset:54272
	ds_read_b128 v[228:231], v214 offset:55296
	ds_read_b128 v[232:235], v214 offset:56320
	global_load_lds_dwordx4 v0, s[98:99]
	s_add_i32 m0, s18, 0x2000
	s_add_u32 s18, s22, 0xb0080
	s_addc_u32 s19, s23, 0
	s_add_i32 s22, s51, s2
	global_load_lds_dwordx4 v172, s[98:99]
	s_mov_b32 m0, s22
	s_nop 0
	global_load_lds_dwordx4 v0, s[18:19]
	s_add_i32 m0, s22, 0x2000
	s_nop 0
	global_load_lds_dwordx4 v172, s[18:19]
	s_mov_b32 m0, s35
	s_nop 0
	global_load_lds_dwordx4 v176, s[100:101]
	s_mov_b32 m0, s37
	s_nop 0
	global_load_lds_dwordx4 v174, s[100:101]
	s_waitcnt vmcnt(8)
	s_waitcnt lgkmcnt(0)
	s_barrier
	s_setprio 1
	s_waitcnt lgkmcnt(0)
	v_mfma_f32_16x16x32_bf16 v[62:65], v[130:133], v[186:189], v[62:65]
	v_mfma_f32_16x16x32_bf16 v[58:61], v[138:141], v[186:189], v[58:61]
	v_mfma_f32_16x16x32_bf16 v[46:49], v[130:133], v[194:197], v[46:49]
	v_mfma_f32_16x16x32_bf16 v[42:45], v[138:141], v[194:197], v[42:45]
	v_mfma_f32_16x16x32_bf16 v[30:33], v[130:133], v[220:223], v[30:33]
	v_mfma_f32_16x16x32_bf16 v[26:29], v[138:141], v[220:223], v[26:29]
	v_mfma_f32_16x16x32_bf16 v[14:17], v[130:133], v[228:231], v[14:17]
	v_mfma_f32_16x16x32_bf16 v[10:13], v[138:141], v[228:231], v[10:13]
	v_mfma_f32_16x16x32_bf16 v[62:65], v[134:137], v[190:193], v[62:65]
	v_mfma_f32_16x16x32_bf16 v[58:61], v[142:145], v[190:193], v[58:61]
	v_mfma_f32_16x16x32_bf16 v[46:49], v[134:137], v[216:219], v[46:49]
	v_mfma_f32_16x16x32_bf16 v[42:45], v[142:145], v[216:219], v[42:45]
	v_mfma_f32_16x16x32_bf16 v[30:33], v[134:137], v[224:227], v[30:33]
	v_mfma_f32_16x16x32_bf16 v[26:29], v[142:145], v[224:227], v[26:29]
	v_mfma_f32_16x16x32_bf16 v[14:17], v[134:137], v[232:235], v[14:17]
	v_mfma_f32_16x16x32_bf16 v[10:13], v[142:145], v[232:235], v[10:13]
	v_mfma_f32_16x16x32_bf16 v[54:57], v[146:149], v[186:189], v[54:57]
	v_mfma_f32_16x16x32_bf16 v[50:53], v[154:157], v[186:189], v[50:53]
	v_mfma_f32_16x16x32_bf16 v[38:41], v[146:149], v[194:197], v[38:41]
	v_mfma_f32_16x16x32_bf16 v[34:37], v[154:157], v[194:197], v[34:37]
	v_mfma_f32_16x16x32_bf16 v[22:25], v[146:149], v[220:223], v[22:25]
	v_mfma_f32_16x16x32_bf16 v[18:21], v[154:157], v[220:223], v[18:21]
	v_mfma_f32_16x16x32_bf16 v[6:9], v[146:149], v[228:231], v[6:9]
	v_mfma_f32_16x16x32_bf16 v[2:5], v[154:157], v[228:231], v[2:5]
	v_mfma_f32_16x16x32_bf16 v[54:57], v[150:153], v[190:193], v[54:57]
	v_mfma_f32_16x16x32_bf16 v[50:53], v[182:185], v[190:193], v[50:53]
	v_mfma_f32_16x16x32_bf16 v[38:41], v[150:153], v[216:219], v[38:41]
	v_mfma_f32_16x16x32_bf16 v[34:37], v[182:185], v[216:219], v[34:37]
	v_mfma_f32_16x16x32_bf16 v[22:25], v[150:153], v[224:227], v[22:25]
	v_mfma_f32_16x16x32_bf16 v[18:21], v[182:185], v[224:227], v[18:21]
	v_mfma_f32_16x16x32_bf16 v[6:9], v[150:153], v[232:235], v[6:9]
	v_mfma_f32_16x16x32_bf16 v[2:5], v[182:185], v[232:235], v[2:5]
	s_setprio 0
	s_barrier
	s_add_i32 s49, s49, 2
	s_add_u32 s47, s47, 0x100
	s_addc_u32 s48, s48, 0
	s_mov_b64 s[18:19], s[20:21]
; #define PG8_STAGE(bufoff, gbase, voff) do { _Pragma("unroll") for (int _i = 0; _i < 2; ++_i) \
;         __builtin_amdgcn_global_load_lds((const unsigned*)((const char*)(gbase) + (voff)[_i]), (PG8_LAS unsigned*)(lds + (bufoff) + ldsw + _i * 8192), 16, 0, 0); } while (0)
; #define PG8_LDA(dst, b, h) do { _Pragma("unroll") for (int m = 0; m < 4; ++m) _Pragma("unroll") for (int k = 0; k < 2; ++k) dst[m][k] = *(const PG8_LAS bf16x8*)(lds + PG8_SA(b, h) + aoff + m * 2048 + k * 1024); } while (0)
; #define PG8_LDB(dst, b, h) do { _Pragma("unroll") for (int n = 0; n < 2; ++n) _Pragma("unroll") for (int k = 0; k < 2; ++k) dst[n][k] = *(const PG8_LAS bf16x8*)(lds + PG8_SB(b, h) + boff + n * 2048 + k * 1024); } while (0)
; #define PG8_MMA(ai, bj, At, Bt) do { __builtin_amdgcn_s_setprio(1); _Pragma("unroll") for (int m = 0; m < 4; ++m) _Pragma("unroll") for (int n = 0; n < 2; ++n) _Pragma("unroll") for (int k = 0; k < 2; ++k) \
;         acc[ai][bj][m][n] = __builtin_amdgcn_mfma_f32_16x16x32_bf16(Bt[n][k], At[m][k], acc[ai][bj][m][n], 0, 0, 0); __builtin_amdgcn_s_setprio(0); } while (0)
; #define PG8_WAIT_V(n) asm volatile("s_waitcnt vmcnt(" #n ")" ::: "memory")
; #define PG8_BAR __builtin_amdgcn_s_barrier()
; template <class Epi, class Sched, bool ALIGN_EPI = false, bool SP2 = false>
; __device__ __forceinline__ void gemm_phase(PG8_LAS unsigned char* lds, const Gemm g, const Sched& S, const Epi& E) {
;     ...
;         for (int t = 0; t < nt; t += 2) {
;             const bool last = (t == nt - 2);
;             const char* a1 = cA + (size_t)(t + 1) * kstep;
;             const char* a2 = last ? nA : cA + (size_t)(t + 2) * kstep; const char* b2 = last ? nB : cB + (size_t)(t + 2) * kstep;
;             const char* a3 = a2 + kstep; const char* b3 = b2 + kstep;
;             if (last && has_next) S.a_ready(nxt);
;             if constexpr (SP2) {
;             PG8_LDB(B0, 0, 0); PG8_LDB(B1, 0, 1); PG8_SCHED; PG8_LDA(At, 0, 0); PG8_STAGE(PG8_SA(1, 1), a1 + hstep, voffA);
;             PG8_WAIT_V(8); PG8_WAIT_L(0); PG8_BAR; PG8_MMA(0, 0, At, B0); PG8_MMA(0, 1, At, B1); PG8_BAR; PG8_SCHED;
;             PG8_LDA(At, 0, 1); PG8_STAGE(PG8_SB(0, 0), b2, voffB); PG8_STAGE(PG8_SB(0, 1), b2 + hstep, voffB); PG8_STAGE(PG8_SA(0, 0), a2, voffA);
;             PG8_WAIT_V(8); PG8_WAIT_L(0); PG8_BAR; PG8_MMA(1, 0, At, B0); PG8_MMA(1, 1, At, B1); PG8_BAR; PG8_SCHED;
.LBB0_459:
	s_add_u32 s20, s18, 0x100
	s_addc_u32 s21, s19, 0
	s_add_i32 s50, 0, 0x10000
	s_cmp_eq_u32 s49, 40
	s_cselect_b32 s25, s9, s21
	s_cselect_b32 s24, s8, s20
	s_cselect_b32 s23, s17, s48
	s_cselect_b32 s22, s16, s47
	s_add_i32 s51, 0, 0x14000
	v_add_u32_e32 v142, s50, v165
	v_add_u32_e32 v182, s51, v165
	ds_read_b128 v[130:133], v142
	ds_read_b128 v[134:137], v142 offset:1024
	ds_read_b128 v[138:141], v142 offset:2048
	ds_read_b128 v[142:145], v142 offset:3072
	ds_read_b128 v[146:149], v182
	ds_read_b128 v[150:153], v182 offset:1024
	ds_read_b128 v[154:157], v182 offset:2048
	ds_read_b128 v[182:185], v182 offset:3072
	s_add_i32 m0, s28, 0xc000
	ds_read_b128 v[186:189], v214
	ds_read_b128 v[190:193], v214 offset:1024
	ds_read_b128 v[194:197], v214 offset:2048
	ds_read_b128 v[216:219], v214 offset:3072
	ds_read_b128 v[220:223], v214 offset:4096
	ds_read_b128 v[224:227], v214 offset:5120
	ds_read_b128 v[228:231], v214 offset:6144
	ds_read_b128 v[232:235], v214 offset:7168
	global_load_lds_dwordx4 v178, s[18:19]
	s_add_i32 m0, s28, 0xe000
	s_nop 0
	global_load_lds_dwordx4 v180, s[18:19]
	s_waitcnt vmcnt(8)
	s_waitcnt lgkmcnt(0)
	s_barrier
	s_setprio 1
	s_waitcnt lgkmcnt(0)
	v_mfma_f32_16x16x32_bf16 v[126:129], v[130:133], v[186:189], v[126:129]
	v_mfma_f32_16x16x32_bf16 v[122:125], v[138:141], v[186:189], v[122:125]
	v_mfma_f32_16x16x32_bf16 v[110:113], v[130:133], v[194:197], v[110:113]
	v_mfma_f32_16x16x32_bf16 v[106:109], v[138:141], v[194:197], v[106:109]
	v_mfma_f32_16x16x32_bf16 v[94:97], v[130:133], v[220:223], v[94:97]
	v_mfma_f32_16x16x32_bf16 v[90:93], v[138:141], v[220:223], v[90:93]
	v_mfma_f32_16x16x32_bf16 v[78:81], v[130:133], v[228:231], v[78:81]
	v_mfma_f32_16x16x32_bf16 v[74:77], v[138:141], v[228:231], v[74:77]
	v_mfma_f32_16x16x32_bf16 v[126:129], v[134:137], v[190:193], v[126:129]
	v_mfma_f32_16x16x32_bf16 v[122:125], v[142:145], v[190:193], v[122:125]
	v_mfma_f32_16x16x32_bf16 v[110:113], v[134:137], v[216:219], v[110:113]
	v_mfma_f32_16x16x32_bf16 v[106:109], v[142:145], v[216:219], v[106:109]
	v_mfma_f32_16x16x32_bf16 v[94:97], v[134:137], v[224:227], v[94:97]
	v_mfma_f32_16x16x32_bf16 v[90:93], v[142:145], v[224:227], v[90:93]
	v_mfma_f32_16x16x32_bf16 v[78:81], v[134:137], v[232:235], v[78:81]
	v_mfma_f32_16x16x32_bf16 v[74:77], v[142:145], v[232:235], v[74:77]
	v_mfma_f32_16x16x32_bf16 v[118:121], v[146:149], v[186:189], v[118:121]
	v_mfma_f32_16x16x32_bf16 v[114:117], v[154:157], v[186:189], v[114:117]
	v_mfma_f32_16x16x32_bf16 v[102:105], v[146:149], v[194:197], v[102:105]
	v_mfma_f32_16x16x32_bf16 v[98:101], v[154:157], v[194:197], v[98:101]
	v_mfma_f32_16x16x32_bf16 v[86:89], v[146:149], v[220:223], v[86:89]
	v_mfma_f32_16x16x32_bf16 v[82:85], v[154:157], v[220:223], v[82:85]
	v_mfma_f32_16x16x32_bf16 v[70:73], v[146:149], v[228:231], v[70:73]
	v_mfma_f32_16x16x32_bf16 v[66:69], v[154:157], v[228:231], v[66:69]
	v_mfma_f32_16x16x32_bf16 v[118:121], v[150:153], v[190:193], v[118:121]
	v_mfma_f32_16x16x32_bf16 v[114:117], v[182:185], v[190:193], v[114:117]
	v_mfma_f32_16x16x32_bf16 v[102:105], v[150:153], v[216:219], v[102:105]
	v_mfma_f32_16x16x32_bf16 v[98:101], v[182:185], v[216:219], v[98:101]
	v_mfma_f32_16x16x32_bf16 v[86:89], v[150:153], v[224:227], v[86:89]
	v_mfma_f32_16x16x32_bf16 v[82:85], v[182:185], v[224:227], v[82:85]
	v_mfma_f32_16x16x32_bf16 v[70:73], v[150:153], v[232:235], v[70:73]
	v_mfma_f32_16x16x32_bf16 v[66:69], v[182:185], v[232:235], v[66:69]
	s_setprio 0
	s_barrier
	s_add_i32 s18, s50, s2
	s_mov_b32 m0, s18
	ds_read_b128 v[186:189], v214 offset:16384
	ds_read_b128 v[190:193], v214 offset:17408
	ds_read_b128 v[194:197], v214 offset:18432
	ds_read_b128 v[216:219], v214 offset:19456
	ds_read_b128 v[220:223], v214 offset:20480
	ds_read_b128 v[224:227], v214 offset:21504
	ds_read_b128 v[228:231], v214 offset:22528
	ds_read_b128 v[232:235], v214 offset:23552
	global_load_lds_dwordx4 v0, s[22:23]
	s_add_i32 m0, s18, 0x2000
	s_add_u32 s18, s22, 0xb0000
	s_addc_u32 s19, s23, 0
	s_add_i32 s50, s51, s2
	global_load_lds_dwordx4 v172, s[22:23]
	s_mov_b32 m0, s50
	s_nop 0
	global_load_lds_dwordx4 v0, s[18:19]
	s_add_i32 m0, s50, 0x2000
	s_nop 0
	global_load_lds_dwordx4 v172, s[18:19]
	s_mov_b32 m0, s28
	s_nop 0
	global_load_lds_dwordx4 v176, s[24:25]
	s_mov_b32 m0, s29
	s_nop 0
	global_load_lds_dwordx4 v174, s[24:25]
	s_waitcnt vmcnt(8)
	s_waitcnt lgkmcnt(0)
	s_barrier
	s_setprio 1
	s_waitcnt lgkmcnt(0)
	v_mfma_f32_16x16x32_bf16 v[62:65], v[130:133], v[186:189], v[62:65]
	v_mfma_f32_16x16x32_bf16 v[58:61], v[138:141], v[186:189], v[58:61]
	v_mfma_f32_16x16x32_bf16 v[46:49], v[130:133], v[194:197], v[46:49]
	v_mfma_f32_16x16x32_bf16 v[42:45], v[138:141], v[194:197], v[42:45]
	v_mfma_f32_16x16x32_bf16 v[30:33], v[130:133], v[220:223], v[30:33]
	v_mfma_f32_16x16x32_bf16 v[26:29], v[138:141], v[220:223], v[26:29]
	v_mfma_f32_16x16x32_bf16 v[14:17], v[130:133], v[228:231], v[14:17]
	v_mfma_f32_16x16x32_bf16 v[10:13], v[138:141], v[228:231], v[10:13]
	v_mfma_f32_16x16x32_bf16 v[62:65], v[134:137], v[190:193], v[62:65]
	v_mfma_f32_16x16x32_bf16 v[58:61], v[142:145], v[190:193], v[58:61]
	v_mfma_f32_16x16x32_bf16 v[46:49], v[134:137], v[216:219], v[46:49]
	v_mfma_f32_16x16x32_bf16 v[42:45], v[142:145], v[216:219], v[42:45]
	v_mfma_f32_16x16x32_bf16 v[30:33], v[134:137], v[224:227], v[30:33]
	v_mfma_f32_16x16x32_bf16 v[26:29], v[142:145], v[224:227], v[26:29]
	v_mfma_f32_16x16x32_bf16 v[14:17], v[134:137], v[232:235], v[14:17]
	v_mfma_f32_16x16x32_bf16 v[10:13], v[142:145], v[232:235], v[10:13]
	v_mfma_f32_16x16x32_bf16 v[54:57], v[146:149], v[186:189], v[54:57]
	v_mfma_f32_16x16x32_bf16 v[50:53], v[154:157], v[186:189], v[50:53]
	v_mfma_f32_16x16x32_bf16 v[38:41], v[146:149], v[194:197], v[38:41]
	v_mfma_f32_16x16x32_bf16 v[34:37], v[154:157], v[194:197], v[34:37]
	v_mfma_f32_16x16x32_bf16 v[22:25], v[146:149], v[220:223], v[22:25]
	v_mfma_f32_16x16x32_bf16 v[18:21], v[154:157], v[220:223], v[18:21]
	v_mfma_f32_16x16x32_bf16 v[6:9], v[146:149], v[228:231], v[6:9]
	v_mfma_f32_16x16x32_bf16 v[2:5], v[154:157], v[228:231], v[2:5]
	v_mfma_f32_16x16x32_bf16 v[54:57], v[150:153], v[190:193], v[54:57]
	v_mfma_f32_16x16x32_bf16 v[50:53], v[182:185], v[190:193], v[50:53]
	v_mfma_f32_16x16x32_bf16 v[38:41], v[150:153], v[216:219], v[38:41]
	v_mfma_f32_16x16x32_bf16 v[34:37], v[182:185], v[216:219], v[34:37]
	v_mfma_f32_16x16x32_bf16 v[22:25], v[150:153], v[224:227], v[22:25]
	v_mfma_f32_16x16x32_bf16 v[18:21], v[182:185], v[224:227], v[18:21]
	v_mfma_f32_16x16x32_bf16 v[6:9], v[150:153], v[232:235], v[6:9]
	v_mfma_f32_16x16x32_bf16 v[2:5], v[182:185], v[232:235], v[2:5]
	s_setprio 0
	s_barrier
; #define PG8_STAGE(bufoff, gbase, voff) do { _Pragma("unroll") for (int _i = 0; _i < 2; ++_i) \
;         __builtin_amdgcn_global_load_lds((const unsigned*)((const char*)(gbase) + (voff)[_i]), (PG8_LAS unsigned*)(lds + (bufoff) + ldsw + _i * 8192), 16, 0, 0); } while (0)
; #define PG8_LDA(dst, b, h) do { _Pragma("unroll") for (int m = 0; m < 4; ++m) _Pragma("unroll") for (int k = 0; k < 2; ++k) dst[m][k] = *(const PG8_LAS bf16x8*)(lds + PG8_SA(b, h) + aoff + m * 2048 + k * 1024); } while (0)
; #define PG8_LDB(dst, b, h) do { _Pragma("unroll") for (int n = 0; n < 2; ++n) _Pragma("unroll") for (int k = 0; k < 2; ++k) dst[n][k] = *(const PG8_LAS bf16x8*)(lds + PG8_SB(b, h) + boff + n * 2048 + k * 1024); } while (0)
; #define PG8_MMA(ai, bj, At, Bt) do { __builtin_amdgcn_s_setprio(1); _Pragma("unroll") for (int m = 0; m < 4; ++m) _Pragma("unroll") for (int n = 0; n < 2; ++n) _Pragma("unroll") for (int k = 0; k < 2; ++k) \
;         acc[ai][bj][m][n] = __builtin_amdgcn_mfma_f32_16x16x32_bf16(Bt[n][k], At[m][k], acc[ai][bj][m][n], 0, 0, 0); __builtin_amdgcn_s_setprio(0); } while (0)
; #define PG8_WAIT_V(n) asm volatile("s_waitcnt vmcnt(" #n ")" ::: "memory")
; #define PG8_WAIT_L(n) asm volatile("s_waitcnt lgkmcnt(" #n ")" ::: "memory")
; #define PG8_BAR __builtin_amdgcn_s_barrier()
; #define PG8_SCHED __builtin_amdgcn_sched_barrier(0)
; template <class Epi, class Sched, bool ALIGN_EPI = false, bool SP2 = false>
; __device__ __forceinline__ void gemm_phase(PG8_LAS unsigned char* lds, const Gemm g, const Sched& S, const Epi& E) {
;     ...
;             PG8_LDB(B0, 1, 0); PG8_LDB(B1, 1, 1); PG8_SCHED; PG8_LDA(At, 1, 0); PG8_STAGE(PG8_SA(0, 1), a2 + hstep, voffA);
;             PG8_WAIT_V(8); PG8_WAIT_L(0); PG8_BAR; PG8_MMA(0, 0, At, B0); PG8_MMA(0, 1, At, B1); PG8_BAR; PG8_SCHED;
;             PG8_LDA(At, 1, 1); PG8_STAGE(PG8_SB(1, 0), b3, voffB); PG8_STAGE(PG8_SB(1, 1), b3 + hstep, voffB); PG8_STAGE(PG8_SA(1, 0), a3, voffA);
	s_add_i32 s50, 0, 0x18000
	s_add_i32 s51, 0, 0x1c000
	v_add_u32_e32 v142, s50, v165
	v_add_u32_e32 v182, s51, v165
	ds_read_b128 v[130:133], v142
	ds_read_b128 v[134:137], v142 offset:1024
	ds_read_b128 v[138:141], v142 offset:2048
	ds_read_b128 v[142:145], v142 offset:3072
	ds_read_b128 v[146:149], v182
	ds_read_b128 v[150:153], v182 offset:1024
	ds_read_b128 v[154:157], v182 offset:2048
	ds_read_b128 v[182:185], v182 offset:3072
	s_add_u32 s18, s24, 0xb0000
	s_addc_u32 s19, s25, 0
	s_mov_b32 m0, s30
	ds_read_b128 v[186:189], v214 offset:32768
	ds_read_b128 v[190:193], v214 offset:33792
	ds_read_b128 v[194:197], v214 offset:34816
	ds_read_b128 v[216:219], v214 offset:35840
	ds_read_b128 v[220:223], v214 offset:36864
	ds_read_b128 v[224:227], v214 offset:37888
	ds_read_b128 v[228:231], v214 offset:38912
	ds_read_b128 v[232:235], v214 offset:39936
	global_load_lds_dwordx4 v176, s[18:19]
	s_mov_b32 m0, s31
	s_nop 0
	global_load_lds_dwordx4 v174, s[18:19]
	s_waitcnt vmcnt(8)
	s_waitcnt lgkmcnt(0)
	s_barrier
	s_setprio 1
	s_waitcnt lgkmcnt(0)
	v_mfma_f32_16x16x32_bf16 v[126:129], v[130:133], v[186:189], v[126:129]
	v_mfma_f32_16x16x32_bf16 v[122:125], v[138:141], v[186:189], v[122:125]
	v_mfma_f32_16x16x32_bf16 v[110:113], v[130:133], v[194:197], v[110:113]
	v_mfma_f32_16x16x32_bf16 v[106:109], v[138:141], v[194:197], v[106:109]
	v_mfma_f32_16x16x32_bf16 v[94:97], v[130:133], v[220:223], v[94:97]
	v_mfma_f32_16x16x32_bf16 v[90:93], v[138:141], v[220:223], v[90:93]
	v_mfma_f32_16x16x32_bf16 v[78:81], v[130:133], v[228:231], v[78:81]
	v_mfma_f32_16x16x32_bf16 v[74:77], v[138:141], v[228:231], v[74:77]
	v_mfma_f32_16x16x32_bf16 v[126:129], v[134:137], v[190:193], v[126:129]
	v_mfma_f32_16x16x32_bf16 v[122:125], v[142:145], v[190:193], v[122:125]
	v_mfma_f32_16x16x32_bf16 v[110:113], v[134:137], v[216:219], v[110:113]
	v_mfma_f32_16x16x32_bf16 v[106:109], v[142:145], v[216:219], v[106:109]
	v_mfma_f32_16x16x32_bf16 v[94:97], v[134:137], v[224:227], v[94:97]
	v_mfma_f32_16x16x32_bf16 v[90:93], v[142:145], v[224:227], v[90:93]
	v_mfma_f32_16x16x32_bf16 v[78:81], v[134:137], v[232:235], v[78:81]
	v_mfma_f32_16x16x32_bf16 v[74:77], v[142:145], v[232:235], v[74:77]
	v_mfma_f32_16x16x32_bf16 v[118:121], v[146:149], v[186:189], v[118:121]
	v_mfma_f32_16x16x32_bf16 v[114:117], v[154:157], v[186:189], v[114:117]
	v_mfma_f32_16x16x32_bf16 v[102:105], v[146:149], v[194:197], v[102:105]
	v_mfma_f32_16x16x32_bf16 v[98:101], v[154:157], v[194:197], v[98:101]
	v_mfma_f32_16x16x32_bf16 v[86:89], v[146:149], v[220:223], v[86:89]
	v_mfma_f32_16x16x32_bf16 v[82:85], v[154:157], v[220:223], v[82:85]
	v_mfma_f32_16x16x32_bf16 v[70:73], v[146:149], v[228:231], v[70:73]
	v_mfma_f32_16x16x32_bf16 v[66:69], v[154:157], v[228:231], v[66:69]
	v_mfma_f32_16x16x32_bf16 v[118:121], v[150:153], v[190:193], v[118:121]
	v_mfma_f32_16x16x32_bf16 v[114:117], v[182:185], v[190:193], v[114:117]
	v_mfma_f32_16x16x32_bf16 v[102:105], v[150:153], v[216:219], v[102:105]
	v_mfma_f32_16x16x32_bf16 v[98:101], v[182:185], v[216:219], v[98:101]
	v_mfma_f32_16x16x32_bf16 v[86:89], v[150:153], v[224:227], v[86:89]
	v_mfma_f32_16x16x32_bf16 v[82:85], v[182:185], v[224:227], v[82:85]
	v_mfma_f32_16x16x32_bf16 v[70:73], v[150:153], v[232:235], v[70:73]
	v_mfma_f32_16x16x32_bf16 v[66:69], v[182:185], v[232:235], v[66:69]
	s_setprio 0
	s_barrier
	s_add_i32 s18, s50, s2
	s_add_u32 s98, s22, 0x80
	s_addc_u32 s99, s23, 0
	s_add_u32 s100, s24, 0x80
	s_addc_u32 s101, s25, 0
	s_mov_b32 m0, s18
	ds_read_b128 v[186:189], v214 offset:49152
	ds_read_b128 v[190:193], v214 offset:50176
	ds_read_b128 v[194:197], v214 offset:51200
	ds_read_b128 v[216:219], v214 offset:52224
	ds_read_b128 v[220:223], v214 offset:53248
	ds_read_b128 v[224:227], v214 offset:54272
	ds_read_b128 v[228:231], v214 offset:55296
	ds_read_b128 v[232:235], v214 offset:56320
	global_load_lds_dwordx4 v0, s[98:99]
	s_add_i32 m0, s18, 0x2000
	s_add_u32 s18, s22, 0xb0080
	s_addc_u32 s19, s23, 0
	s_add_i32 s22, s51, s2
	global_load_lds_dwordx4 v172, s[98:99]
	s_mov_b32 m0, s22
	s_nop 0
	global_load_lds_dwordx4 v0, s[18:19]
	s_add_i32 m0, s22, 0x2000
	s_nop 0
	global_load_lds_dwordx4 v172, s[18:19]
	s_mov_b32 m0, s35
	s_nop 0
	global_load_lds_dwordx4 v176, s[100:101]
	s_mov_b32 m0, s37
	s_nop 0
	global_load_lds_dwordx4 v174, s[100:101]
	s_waitcnt vmcnt(8)
	s_waitcnt lgkmcnt(0)
	s_barrier
; #define PG8_STAGE(bufoff, gbase, voff) do { _Pragma("unroll") for (int _i = 0; _i < 2; ++_i) \
;         __builtin_amdgcn_global_load_lds((const unsigned*)((const char*)(gbase) + (voff)[_i]), (PG8_LAS unsigned*)(lds + (bufoff) + ldsw + _i * 8192), 16, 0, 0); } while (0)
; #define PG8_LDA(dst, b, h) do { _Pragma("unroll") for (int m = 0; m < 4; ++m) _Pragma("unroll") for (int k = 0; k < 2; ++k) dst[m][k] = *(const PG8_LAS bf16x8*)(lds + PG8_SA(b, h) + aoff + m * 2048 + k * 1024); } while (0)
; #define PG8_MMA(ai, bj, At, Bt) do { __builtin_amdgcn_s_setprio(1); _Pragma("unroll") for (int m = 0; m < 4; ++m) _Pragma("unroll") for (int n = 0; n < 2; ++n) _Pragma("unroll") for (int k = 0; k < 2; ++k) \
;         acc[ai][bj][m][n] = __builtin_amdgcn_mfma_f32_16x16x32_bf16(Bt[n][k], At[m][k], acc[ai][bj][m][n], 0, 0, 0); __builtin_amdgcn_s_setprio(0); } while (0)
; #define PG8_WAIT_V(n) asm volatile("s_waitcnt vmcnt(" #n ")" ::: "memory")
; #define PG8_WAIT_L(n) asm volatile("s_waitcnt lgkmcnt(" #n ")" ::: "memory")
; #define PG8_BAR __builtin_amdgcn_s_barrier()
; #define PG8_SCHED __builtin_amdgcn_sched_barrier(0)
; template <class Epi, class Sched, bool ALIGN_EPI = false, bool SP2 = false>
; __device__ __forceinline__ void gemm_phase(PG8_LAS unsigned char* lds, const Gemm g, const Sched& S, const Epi& E) {
;     ...
;             PG8_WAIT_V(8); PG8_WAIT_L(0); PG8_BAR; PG8_MMA(0, 0, At, B0); PG8_MMA(0, 1, At, B1); PG8_BAR; PG8_SCHED;
;             PG8_LDA(At, 1, 1); PG8_STAGE(PG8_SB(1, 0), b3, voffB); PG8_STAGE(PG8_SB(1, 1), b3 + hstep, voffB); PG8_STAGE(PG8_SA(1, 0), a3, voffA);
;             PG8_WAIT_V(8); PG8_WAIT_L(0); PG8_BAR; PG8_MMA(1, 0, At, B0); PG8_MMA(1, 1, At, B1); PG8_BAR; PG8_SCHED;
;     __device__ __forceinline__ void operator()(const f32x4 (&acc)[2][2][4][2], const Unit& u, int wr, int wc, int fr, int fq) const {
;     ...
;         for (int ai = 0; ai < 2; ++ai) {
;             u32x4 xv[4][2];
; #pragma unroll
;             for (int m = 0; m < 4; ++m)
; #pragma unroll
;                 for (int bj = 0; bj < 2; ++bj) xv[m][bj] = *(const u32x4*)(XB + (size_t)(row0 + ai * HALF + m * 16) * 1024 + col0 + bj * HALF);
;             asm volatile("" ::: "memory");
	s_setprio 1
	s_waitcnt lgkmcnt(0)
	v_mfma_f32_16x16x32_bf16 v[62:65], v[130:133], v[186:189], v[62:65]
	v_mfma_f32_16x16x32_bf16 v[58:61], v[138:141], v[186:189], v[58:61]
	v_mfma_f32_16x16x32_bf16 v[46:49], v[130:133], v[194:197], v[46:49]
	v_mfma_f32_16x16x32_bf16 v[42:45], v[138:141], v[194:197], v[42:45]
	v_mfma_f32_16x16x32_bf16 v[30:33], v[130:133], v[220:223], v[30:33]
	v_mfma_f32_16x16x32_bf16 v[26:29], v[138:141], v[220:223], v[26:29]
	v_mfma_f32_16x16x32_bf16 v[14:17], v[130:133], v[228:231], v[14:17]
	v_mfma_f32_16x16x32_bf16 v[10:13], v[138:141], v[228:231], v[10:13]
	v_mfma_f32_16x16x32_bf16 v[62:65], v[134:137], v[190:193], v[62:65]
	v_mfma_f32_16x16x32_bf16 v[58:61], v[142:145], v[190:193], v[58:61]
	v_mfma_f32_16x16x32_bf16 v[46:49], v[134:137], v[216:219], v[46:49]
	v_mfma_f32_16x16x32_bf16 v[42:45], v[142:145], v[216:219], v[42:45]
	v_mfma_f32_16x16x32_bf16 v[30:33], v[134:137], v[224:227], v[30:33]
	v_mfma_f32_16x16x32_bf16 v[26:29], v[142:145], v[224:227], v[26:29]
	v_mfma_f32_16x16x32_bf16 v[14:17], v[134:137], v[232:235], v[14:17]
	v_mfma_f32_16x16x32_bf16 v[10:13], v[142:145], v[232:235], v[10:13]
	v_mfma_f32_16x16x32_bf16 v[54:57], v[146:149], v[186:189], v[54:57]
	v_mfma_f32_16x16x32_bf16 v[50:53], v[154:157], v[186:189], v[50:53]
	v_mfma_f32_16x16x32_bf16 v[38:41], v[146:149], v[194:197], v[38:41]
	v_mfma_f32_16x16x32_bf16 v[34:37], v[154:157], v[194:197], v[34:37]
	v_mfma_f32_16x16x32_bf16 v[22:25], v[146:149], v[220:223], v[22:25]
	v_mfma_f32_16x16x32_bf16 v[18:21], v[154:157], v[220:223], v[18:21]
	v_mfma_f32_16x16x32_bf16 v[6:9], v[146:149], v[228:231], v[6:9]
	v_mfma_f32_16x16x32_bf16 v[2:5], v[154:157], v[228:231], v[2:5]
	v_mfma_f32_16x16x32_bf16 v[54:57], v[150:153], v[190:193], v[54:57]
	v_mfma_f32_16x16x32_bf16 v[50:53], v[182:185], v[190:193], v[50:53]
	v_mfma_f32_16x16x32_bf16 v[38:41], v[150:153], v[216:219], v[38:41]
	v_mfma_f32_16x16x32_bf16 v[34:37], v[182:185], v[216:219], v[34:37]
	v_mfma_f32_16x16x32_bf16 v[22:25], v[150:153], v[224:227], v[22:25]
	v_mfma_f32_16x16x32_bf16 v[18:21], v[182:185], v[224:227], v[18:21]
	v_mfma_f32_16x16x32_bf16 v[6:9], v[150:153], v[232:235], v[6:9]
	v_mfma_f32_16x16x32_bf16 v[2:5], v[182:185], v[232:235], v[2:5]
	s_setprio 0
	s_barrier
	s_add_i32 s49, s49, 2
	s_add_u32 s47, s47, 0x100
	s_addc_u32 s48, s48, 0
	s_cmp_gt_u32 s49, 41
	s_mov_b64 s[18:19], s[20:21]
	s_cbranch_scc0 .LBB0_459
	v_lshl_or_b32 v198, s45, 8, v213
	v_lshl_add_u32 v217, s46, 8, v158
	v_lshlrev_b32_e32 v246, 1, v198
	v_lshl_add_u32 v246, v217, 11, v246
	v_mov_b32_e32 v247, 0
	s_mov_b32 s18, 0x8000
	s_mov_b32 s19, 0
	s_mov_b32 s88, 0x28000
	v_lshl_add_u64 v[246:247], s[94:95], 0, v[246:247]
	v_xor_b32_e32 v215, 16, v201
	v_xor_b32_e32 v216, 32, v201
	v_mov_b32_e32 v198, v246
	v_mov_b32_e32 v199, v247
	global_load_dwordx4 v[130:133], v[246:247], off
	global_load_dwordx4 v[134:137], v[246:247], off offset:256
	v_lshl_add_u64 v[246:247], v[246:247], 0, s[18:19]
	global_load_dwordx4 v[138:141], v[246:247], off
	global_load_dwordx4 v[142:145], v[246:247], off offset:256
	v_lshl_add_u64 v[246:247], v[246:247], 0, s[18:19]
	global_load_dwordx4 v[146:149], v[246:247], off
	global_load_dwordx4 v[150:153], v[246:247], off offset:256
	v_lshl_add_u64 v[246:247], v[246:247], 0, s[18:19]
	global_load_dwordx4 v[154:157], v[246:247], off
	global_load_dwordx4 v[218:221], v[246:247], off offset:256
	v_lshl_add_u64 v[246:247], v[246:247], 0, s[88:89]
	global_load_dwordx4 v[182:185], v[246:247], off
	global_load_dwordx4 v[186:189], v[246:247], off offset:256
	v_lshl_add_u64 v[246:247], v[246:247], 0, s[18:19]
	global_load_dwordx4 v[190:193], v[246:247], off
	global_load_dwordx4 v[194:197], v[246:247], off offset:256
	v_lshl_add_u64 v[246:247], v[246:247], 0, s[18:19]
	global_load_dwordx4 v[222:225], v[246:247], off
	global_load_dwordx4 v[226:229], v[246:247], off offset:256
	v_lshl_add_u64 v[246:247], v[246:247], 0, s[18:19]
	global_load_dwordx4 v[230:233], v[246:247], off
	global_load_dwordx4 v[234:237], v[246:247], off offset:256
	v_lshlrev_b32_e32 v215, 2, v215
	v_lshlrev_b32_e32 v216, 2, v216
	s_and_b64 vcc, exec, s[14:15]
	s_cbranch_vccz .LBB0_462
	s_barrier

; #define PG8_STAGE(bufoff, gbase, voff) do { _Pragma("unroll") for (int _i = 0; _i < 2; ++_i) \
;         __builtin_amdgcn_global_load_lds((const unsigned*)((const char*)(gbase) + (voff)[_i]), (PG8_LAS unsigned*)(lds + (bufoff) + ldsw + _i * 8192), 16, 0, 0); } while (0)
; #define PG8_LDA(dst, b, h) do { _Pragma("unroll") for (int m = 0; m < 4; ++m) _Pragma("unroll") for (int k = 0; k < 2; ++k) dst[m][k] = *(const PG8_LAS bf16x8*)(lds + PG8_SA(b, h) + aoff + m * 2048 + k * 1024); } while (0)
; #define PG8_LDB(dst, b, h) do { _Pragma("unroll") for (int n = 0; n < 2; ++n) _Pragma("unroll") for (int k = 0; k < 2; ++k) dst[n][k] = *(const PG8_LAS bf16x8*)(lds + PG8_SB(b, h) + boff + n * 2048 + k * 1024); } while (0)
; #define PG8_WAIT_V(n) asm volatile("s_waitcnt vmcnt(" #n ")" ::: "memory")
; #define PG8_WAIT_L(n) asm volatile("s_waitcnt lgkmcnt(" #n ")" ::: "memory")
; #define PG8_BAR __builtin_amdgcn_s_barrier()
; #define PG8_SCHED __builtin_amdgcn_sched_barrier(0)
; template <class Epi, class Sched, bool ALIGN_EPI = false, bool SP2 = false>
; __device__ __forceinline__ void gemm_phase(PG8_LAS unsigned char* lds, const Gemm g, const Sched& S, const Epi& E) {
;     ...
;         const bool has_next = S.next(ui + 1, nxt);
;         const char* nA = has_next ? (const char*)g.A + (size_t)nxt.pm * tstep : cA; const char* nB = has_next ? (const char*)g.Bt + (size_t)nxt.pn * tstep : cB;
;         for (int t = 0; t < nt; t += 2) {
;             const bool last = (t == nt - 2);
;             const char* a1 = cA + (size_t)(t + 1) * kstep;
;             const char* a2 = last ? nA : cA + (size_t)(t + 2) * kstep; const char* b2 = last ? nB : cB + (size_t)(t + 2) * kstep;
;             const char* a3 = a2 + kstep; const char* b3 = b2 + kstep;
;             if (last && has_next) S.a_ready(nxt);
;             if constexpr (SP2) {
;             PG8_LDB(B0, 0, 0); PG8_LDB(B1, 0, 1); PG8_SCHED; PG8_LDA(At, 0, 0); PG8_STAGE(PG8_SA(1, 1), a1 + hstep, voffA);
;             PG8_WAIT_V(8); PG8_WAIT_L(0); PG8_BAR; PG8_MMA(0, 0, At, B0); PG8_MMA(0, 1, At, B1); PG8_BAR; PG8_SCHED;
;             PG8_LDA(At, 0, 1); PG8_STAGE(PG8_SB(0, 0), b2, voffB); PG8_STAGE(PG8_SB(0, 1), b2 + hstep, voffB); PG8_STAGE(PG8_SA(0, 0), a2, voffA);
;             PG8_WAIT_V(8); PG8_WAIT_L(0); PG8_BAR; PG8_MMA(1, 0, At, B0); PG8_MMA(1, 1, At, B1); PG8_BAR; PG8_SCHED;
.LBB0_492:
	s_ashr_i32 s17, s16, 31
	s_lshl_b64 s[18:19], s[16:17], 19
	s_add_u32 s18, s94, s18
	s_addc_u32 s19, s95, s19
	s_and_b64 s[20:21], s[4:5], exec
	s_cselect_b32 s17, s19, s23
	s_cselect_b32 s46, s18, s22
	s_ashr_i32 s15, s14, 31
	s_lshl_b64 s[20:21], s[14:15], 19
	s_add_u32 s20, s28, s20
	s_addc_u32 s21, s29, s21
	s_and_b64 s[26:27], s[4:5], exec
	s_cselect_b32 s15, s21, s25
	s_cselect_b32 s47, s20, s24
	s_add_u32 s22, s22, 0x40080
	s_addc_u32 s23, s23, 0
	s_add_u32 s48, s24, 0x100
	s_addc_u32 s49, s25, 0
	s_mov_b32 s50, -2
	s_add_u32 s24, s22, 0xfffc0080
	s_addc_u32 s25, s23, -1
	s_add_i32 s51, 0, 0x10000
	s_cmp_eq_u32 s50, 12
	s_cselect_b32 s27, s17, s25
	s_cselect_b32 s26, s46, s24
	v_add_u32_e32 v146, s51, v149
	s_cselect_b32 s25, s15, s49
	s_cselect_b32 s24, s47, s48
	s_add_i32 s54, 0, 0x14000
	ds_read_b128 v[142:145], v146
	ds_read_b128 v[152:155], v146 offset:1024
	ds_read_b128 v[172:175], v146 offset:2048
	ds_read_b128 v[176:179], v146 offset:3072
	v_add_u32_e32 v146, s54, v149
	ds_read_b128 v[180:183], v146
	ds_read_b128 v[184:187], v146 offset:1024
	ds_read_b128 v[188:191], v146 offset:2048
	ds_read_b128 v[192:195], v146 offset:3072
	s_add_i32 m0, s30, 0xc000
	ds_read_b128 v[196:199], v151
	ds_read_b128 v[214:217], v151 offset:1024
	ds_read_b128 v[218:221], v151 offset:2048
	ds_read_b128 v[222:225], v151 offset:3072
	ds_read_b128 v[226:229], v151 offset:4096
	ds_read_b128 v[230:233], v151 offset:5120
	ds_read_b128 v[234:237], v151 offset:6144
	ds_read_b128 v[238:241], v151 offset:7168
	global_load_lds_dwordx4 v138, s[22:23]
	s_add_i32 m0, s30, 0xe000
	s_nop 0
	global_load_lds_dwordx4 v140, s[22:23]
	s_waitcnt vmcnt(8)
	s_waitcnt lgkmcnt(0)
	s_barrier
	s_setprio 1
	s_waitcnt lgkmcnt(0)
	v_mfma_f32_16x16x32_bf16 v[126:129], v[142:145], v[196:199], 0
	v_mfma_f32_16x16x32_bf16 v[118:121], v[172:175], v[196:199], 0
	v_mfma_f32_16x16x32_bf16 v[110:113], v[142:145], v[218:221], 0
	v_mfma_f32_16x16x32_bf16 v[102:105], v[172:175], v[218:221], 0
	v_mfma_f32_16x16x32_bf16 v[94:97], v[142:145], v[226:229], 0
	v_mfma_f32_16x16x32_bf16 v[86:89], v[172:175], v[226:229], 0
	v_mfma_f32_16x16x32_bf16 v[78:81], v[142:145], v[234:237], 0
	v_mfma_f32_16x16x32_bf16 v[70:73], v[172:175], v[234:237], 0
	v_mfma_f32_16x16x32_bf16 v[126:129], v[152:155], v[214:217], v[126:129]
	v_mfma_f32_16x16x32_bf16 v[118:121], v[176:179], v[214:217], v[118:121]
	v_mfma_f32_16x16x32_bf16 v[110:113], v[152:155], v[222:225], v[110:113]
	v_mfma_f32_16x16x32_bf16 v[102:105], v[176:179], v[222:225], v[102:105]
	v_mfma_f32_16x16x32_bf16 v[94:97], v[152:155], v[230:233], v[94:97]
	v_mfma_f32_16x16x32_bf16 v[86:89], v[176:179], v[230:233], v[86:89]
	v_mfma_f32_16x16x32_bf16 v[78:81], v[152:155], v[238:241], v[78:81]
	v_mfma_f32_16x16x32_bf16 v[70:73], v[176:179], v[238:241], v[70:73]
	v_mfma_f32_16x16x32_bf16 v[122:125], v[180:183], v[196:199], 0
	v_mfma_f32_16x16x32_bf16 v[114:117], v[188:191], v[196:199], 0
	v_mfma_f32_16x16x32_bf16 v[106:109], v[180:183], v[218:221], 0
	v_mfma_f32_16x16x32_bf16 v[98:101], v[188:191], v[218:221], 0
	v_mfma_f32_16x16x32_bf16 v[90:93], v[180:183], v[226:229], 0
	v_mfma_f32_16x16x32_bf16 v[82:85], v[188:191], v[226:229], 0
	v_mfma_f32_16x16x32_bf16 v[74:77], v[180:183], v[234:237], 0
	v_mfma_f32_16x16x32_bf16 v[66:69], v[188:191], v[234:237], 0
	v_mfma_f32_16x16x32_bf16 v[122:125], v[184:187], v[214:217], v[122:125]
	v_mfma_f32_16x16x32_bf16 v[114:117], v[192:195], v[214:217], v[114:117]
	v_mfma_f32_16x16x32_bf16 v[106:109], v[184:187], v[222:225], v[106:109]
	v_mfma_f32_16x16x32_bf16 v[98:101], v[192:195], v[222:225], v[98:101]
	v_mfma_f32_16x16x32_bf16 v[90:93], v[184:187], v[230:233], v[90:93]
	v_mfma_f32_16x16x32_bf16 v[82:85], v[192:195], v[230:233], v[82:85]
	v_mfma_f32_16x16x32_bf16 v[74:77], v[184:187], v[238:241], v[74:77]
	v_mfma_f32_16x16x32_bf16 v[66:69], v[192:195], v[238:241], v[66:69]
	s_setprio 0
	s_barrier
	s_add_i32 s51, s51, s2
	s_mov_b32 m0, s51
	ds_read_b128 v[196:199], v151 offset:16384
	ds_read_b128 v[214:217], v151 offset:17408
	ds_read_b128 v[218:221], v151 offset:18432
	ds_read_b128 v[222:225], v151 offset:19456
	ds_read_b128 v[226:229], v151 offset:20480
	ds_read_b128 v[230:233], v151 offset:21504
	ds_read_b128 v[234:237], v151 offset:22528
	ds_read_b128 v[238:241], v151 offset:23552
	global_load_lds_dwordx4 v0, s[24:25]
	s_add_i32 m0, s51, 0x2000
	s_add_u32 s52, s24, 0x40000
	s_addc_u32 s53, s25, 0
	s_add_i32 s51, s54, s2
	global_load_lds_dwordx4 v130, s[24:25]
	s_mov_b32 m0, s51
	s_nop 0
	global_load_lds_dwordx4 v0, s[52:53]
	s_add_i32 m0, s51, 0x2000
	s_nop 0
	global_load_lds_dwordx4 v130, s[52:53]
	s_mov_b32 m0, s30
	s_nop 0
	global_load_lds_dwordx4 v134, s[26:27]
	s_mov_b32 m0, s31
	s_nop 0
	global_load_lds_dwordx4 v132, s[26:27]
	s_waitcnt vmcnt(8)
	s_waitcnt lgkmcnt(0)
	s_barrier
; #define PG8_STAGE(bufoff, gbase, voff) do { _Pragma("unroll") for (int _i = 0; _i < 2; ++_i) \
;         __builtin_amdgcn_global_load_lds((const unsigned*)((const char*)(gbase) + (voff)[_i]), (PG8_LAS unsigned*)(lds + (bufoff) + ldsw + _i * 8192), 16, 0, 0); } while (0)
; #define PG8_LDA(dst, b, h) do { _Pragma("unroll") for (int m = 0; m < 4; ++m) _Pragma("unroll") for (int k = 0; k < 2; ++k) dst[m][k] = *(const PG8_LAS bf16x8*)(lds + PG8_SA(b, h) + aoff + m * 2048 + k * 1024); } while (0)
; #define PG8_LDB(dst, b, h) do { _Pragma("unroll") for (int n = 0; n < 2; ++n) _Pragma("unroll") for (int k = 0; k < 2; ++k) dst[n][k] = *(const PG8_LAS bf16x8*)(lds + PG8_SB(b, h) + boff + n * 2048 + k * 1024); } while (0)
; #define PG8_MMA(ai, bj, At, Bt) do { __builtin_amdgcn_s_setprio(1); _Pragma("unroll") for (int m = 0; m < 4; ++m) _Pragma("unroll") for (int n = 0; n < 2; ++n) _Pragma("unroll") for (int k = 0; k < 2; ++k) \
;         acc[ai][bj][m][n] = __builtin_amdgcn_mfma_f32_16x16x32_bf16(Bt[n][k], At[m][k], acc[ai][bj][m][n], 0, 0, 0); __builtin_amdgcn_s_setprio(0); } while (0)
; #define PG8_WAIT_V(n) asm volatile("s_waitcnt vmcnt(" #n ")" ::: "memory")
; #define PG8_WAIT_L(n) asm volatile("s_waitcnt lgkmcnt(" #n ")" ::: "memory")
; #define PG8_BAR __builtin_amdgcn_s_barrier()
; #define PG8_SCHED __builtin_amdgcn_sched_barrier(0)
; template <class Epi, class Sched, bool ALIGN_EPI = false, bool SP2 = false>
; __device__ __forceinline__ void gemm_phase(PG8_LAS unsigned char* lds, const Gemm g, const Sched& S, const Epi& E) {
;     ...
;             PG8_WAIT_V(8); PG8_WAIT_L(0); PG8_BAR; PG8_MMA(0, 0, At, B0); PG8_MMA(0, 1, At, B1); PG8_BAR; PG8_SCHED;
;             PG8_LDA(At, 0, 1); PG8_STAGE(PG8_SB(0, 0), b2, voffB); PG8_STAGE(PG8_SB(0, 1), b2 + hstep, voffB); PG8_STAGE(PG8_SA(0, 0), a2, voffA);
;             PG8_WAIT_V(8); PG8_WAIT_L(0); PG8_BAR; PG8_MMA(1, 0, At, B0); PG8_MMA(1, 1, At, B1); PG8_BAR; PG8_SCHED;
;             PG8_LDB(B0, 1, 0); PG8_LDB(B1, 1, 1); PG8_SCHED; PG8_LDA(At, 1, 0); PG8_STAGE(PG8_SA(0, 1), a2 + hstep, voffA);
;             PG8_WAIT_V(8); PG8_WAIT_L(0); PG8_BAR; PG8_MMA(0, 0, At, B0); PG8_MMA(0, 1, At, B1); PG8_BAR; PG8_SCHED;
	s_setprio 1
	s_waitcnt lgkmcnt(0)
	v_mfma_f32_16x16x32_bf16 v[62:65], v[142:145], v[196:199], 0
	v_mfma_f32_16x16x32_bf16 v[54:57], v[172:175], v[196:199], 0
	v_mfma_f32_16x16x32_bf16 v[46:49], v[142:145], v[218:221], 0
	v_mfma_f32_16x16x32_bf16 v[38:41], v[172:175], v[218:221], 0
	v_mfma_f32_16x16x32_bf16 v[30:33], v[142:145], v[226:229], 0
	v_mfma_f32_16x16x32_bf16 v[22:25], v[172:175], v[226:229], 0
	v_mfma_f32_16x16x32_bf16 v[14:17], v[142:145], v[234:237], 0
	v_mfma_f32_16x16x32_bf16 v[6:9], v[172:175], v[234:237], 0
	v_mfma_f32_16x16x32_bf16 v[62:65], v[152:155], v[214:217], v[62:65]
	v_mfma_f32_16x16x32_bf16 v[54:57], v[176:179], v[214:217], v[54:57]
	v_mfma_f32_16x16x32_bf16 v[46:49], v[152:155], v[222:225], v[46:49]
	v_mfma_f32_16x16x32_bf16 v[38:41], v[176:179], v[222:225], v[38:41]
	v_mfma_f32_16x16x32_bf16 v[30:33], v[152:155], v[230:233], v[30:33]
	v_mfma_f32_16x16x32_bf16 v[22:25], v[176:179], v[230:233], v[22:25]
	v_mfma_f32_16x16x32_bf16 v[14:17], v[152:155], v[238:241], v[14:17]
	v_mfma_f32_16x16x32_bf16 v[6:9], v[176:179], v[238:241], v[6:9]
	v_mfma_f32_16x16x32_bf16 v[58:61], v[180:183], v[196:199], 0
	v_mfma_f32_16x16x32_bf16 v[50:53], v[188:191], v[196:199], 0
	v_mfma_f32_16x16x32_bf16 v[42:45], v[180:183], v[218:221], 0
	v_mfma_f32_16x16x32_bf16 v[34:37], v[188:191], v[218:221], 0
	v_mfma_f32_16x16x32_bf16 v[26:29], v[180:183], v[226:229], 0
	v_mfma_f32_16x16x32_bf16 v[18:21], v[188:191], v[226:229], 0
	v_mfma_f32_16x16x32_bf16 v[10:13], v[180:183], v[234:237], 0
	v_mfma_f32_16x16x32_bf16 v[2:5], v[188:191], v[234:237], 0
	v_mfma_f32_16x16x32_bf16 v[58:61], v[184:187], v[214:217], v[58:61]
	v_mfma_f32_16x16x32_bf16 v[50:53], v[192:195], v[214:217], v[50:53]
	v_mfma_f32_16x16x32_bf16 v[42:45], v[184:187], v[222:225], v[42:45]
	v_mfma_f32_16x16x32_bf16 v[34:37], v[192:195], v[222:225], v[34:37]
	v_mfma_f32_16x16x32_bf16 v[26:29], v[184:187], v[230:233], v[26:29]
	v_mfma_f32_16x16x32_bf16 v[18:21], v[192:195], v[230:233], v[18:21]
	v_mfma_f32_16x16x32_bf16 v[10:13], v[184:187], v[238:241], v[10:13]
	v_mfma_f32_16x16x32_bf16 v[2:5], v[192:195], v[238:241], v[2:5]
	s_setprio 0
	s_barrier
	s_add_i32 s51, 0, 0x18000
	v_add_u32_e32 v158, s51, v149
	s_add_i32 s52, 0, 0x1c000
	ds_read_b128 v[142:145], v158
	ds_read_b128 v[152:155], v158 offset:1024
	ds_read_b128 v[172:175], v158 offset:2048
	ds_read_b128 v[176:179], v158 offset:3072
	v_add_u32_e32 v158, s52, v149
	ds_read_b128 v[180:183], v158
	ds_read_b128 v[184:187], v158 offset:1024
	ds_read_b128 v[188:191], v158 offset:2048
	ds_read_b128 v[192:195], v158 offset:3072
	s_add_u32 s26, s26, 0x40000
	s_addc_u32 s27, s27, 0
	s_mov_b32 m0, s34
	ds_read_b128 v[196:199], v151 offset:32768
	ds_read_b128 v[214:217], v151 offset:33792
	ds_read_b128 v[218:221], v151 offset:34816
	ds_read_b128 v[222:225], v151 offset:35840
	ds_read_b128 v[226:229], v151 offset:36864
	ds_read_b128 v[230:233], v151 offset:37888
	ds_read_b128 v[234:237], v151 offset:38912
	ds_read_b128 v[238:241], v151 offset:39936
	global_load_lds_dwordx4 v134, s[26:27]
	s_mov_b32 m0, s35
	s_nop 0
	global_load_lds_dwordx4 v132, s[26:27]
	s_waitcnt vmcnt(8)
	s_waitcnt lgkmcnt(0)
	s_barrier
	s_setprio 1
	s_waitcnt lgkmcnt(0)
	v_mfma_f32_16x16x32_bf16 v[126:129], v[142:145], v[196:199], v[126:129]
	v_mfma_f32_16x16x32_bf16 v[118:121], v[172:175], v[196:199], v[118:121]
	v_mfma_f32_16x16x32_bf16 v[110:113], v[142:145], v[218:221], v[110:113]
	v_mfma_f32_16x16x32_bf16 v[102:105], v[172:175], v[218:221], v[102:105]
	v_mfma_f32_16x16x32_bf16 v[94:97], v[142:145], v[226:229], v[94:97]
	v_mfma_f32_16x16x32_bf16 v[86:89], v[172:175], v[226:229], v[86:89]
	v_mfma_f32_16x16x32_bf16 v[78:81], v[142:145], v[234:237], v[78:81]
	v_mfma_f32_16x16x32_bf16 v[70:73], v[172:175], v[234:237], v[70:73]
	v_mfma_f32_16x16x32_bf16 v[126:129], v[152:155], v[214:217], v[126:129]
	v_mfma_f32_16x16x32_bf16 v[118:121], v[176:179], v[214:217], v[118:121]
	v_mfma_f32_16x16x32_bf16 v[110:113], v[152:155], v[222:225], v[110:113]
	v_mfma_f32_16x16x32_bf16 v[102:105], v[176:179], v[222:225], v[102:105]
	v_mfma_f32_16x16x32_bf16 v[94:97], v[152:155], v[230:233], v[94:97]
	v_mfma_f32_16x16x32_bf16 v[86:89], v[176:179], v[230:233], v[86:89]
	v_mfma_f32_16x16x32_bf16 v[78:81], v[152:155], v[238:241], v[78:81]
	v_mfma_f32_16x16x32_bf16 v[70:73], v[176:179], v[238:241], v[70:73]
	v_mfma_f32_16x16x32_bf16 v[122:125], v[180:183], v[196:199], v[122:125]
	v_mfma_f32_16x16x32_bf16 v[114:117], v[188:191], v[196:199], v[114:117]
	v_mfma_f32_16x16x32_bf16 v[106:109], v[180:183], v[218:221], v[106:109]
	v_mfma_f32_16x16x32_bf16 v[98:101], v[188:191], v[218:221], v[98:101]
	v_mfma_f32_16x16x32_bf16 v[90:93], v[180:183], v[226:229], v[90:93]
	v_mfma_f32_16x16x32_bf16 v[82:85], v[188:191], v[226:229], v[82:85]
	v_mfma_f32_16x16x32_bf16 v[74:77], v[180:183], v[234:237], v[74:77]
	v_mfma_f32_16x16x32_bf16 v[66:69], v[188:191], v[234:237], v[66:69]
	v_mfma_f32_16x16x32_bf16 v[122:125], v[184:187], v[214:217], v[122:125]
	v_mfma_f32_16x16x32_bf16 v[114:117], v[192:195], v[214:217], v[114:117]
	v_mfma_f32_16x16x32_bf16 v[106:109], v[184:187], v[222:225], v[106:109]
	v_mfma_f32_16x16x32_bf16 v[98:101], v[192:195], v[222:225], v[98:101]
	v_mfma_f32_16x16x32_bf16 v[90:93], v[184:187], v[230:233], v[90:93]
	v_mfma_f32_16x16x32_bf16 v[82:85], v[192:195], v[230:233], v[82:85]
	v_mfma_f32_16x16x32_bf16 v[74:77], v[184:187], v[238:241], v[74:77]
	v_mfma_f32_16x16x32_bf16 v[66:69], v[192:195], v[238:241], v[66:69]
	s_setprio 0
	s_barrier
; #define PG8_STAGE(bufoff, gbase, voff) do { _Pragma("unroll") for (int _i = 0; _i < 2; ++_i) \
;         __builtin_amdgcn_global_load_lds((const unsigned*)((const char*)(gbase) + (voff)[_i]), (PG8_LAS unsigned*)(lds + (bufoff) + ldsw + _i * 8192), 16, 0, 0); } while (0)
; #define PG8_LDA(dst, b, h) do { _Pragma("unroll") for (int m = 0; m < 4; ++m) _Pragma("unroll") for (int k = 0; k < 2; ++k) dst[m][k] = *(const PG8_LAS bf16x8*)(lds + PG8_SA(b, h) + aoff + m * 2048 + k * 1024); } while (0)
; #define PG8_LDB(dst, b, h) do { _Pragma("unroll") for (int n = 0; n < 2; ++n) _Pragma("unroll") for (int k = 0; k < 2; ++k) dst[n][k] = *(const PG8_LAS bf16x8*)(lds + PG8_SB(b, h) + boff + n * 2048 + k * 1024); } while (0)
; #define PG8_MMA(ai, bj, At, Bt) do { __builtin_amdgcn_s_setprio(1); _Pragma("unroll") for (int m = 0; m < 4; ++m) _Pragma("unroll") for (int n = 0; n < 2; ++n) _Pragma("unroll") for (int k = 0; k < 2; ++k) \
;         acc[ai][bj][m][n] = __builtin_amdgcn_mfma_f32_16x16x32_bf16(Bt[n][k], At[m][k], acc[ai][bj][m][n], 0, 0, 0); __builtin_amdgcn_s_setprio(0); } while (0)
; #define PG8_WAIT_V(n) asm volatile("s_waitcnt vmcnt(" #n ")" ::: "memory")
; template <class Epi, class Sched, bool ALIGN_EPI = false, bool SP2 = false>
; __device__ __forceinline__ void gemm_phase(PG8_LAS unsigned char* lds, const Gemm g, const Sched& S, const Epi& E) {
;     ...
;             PG8_LDB(B0, 0, 0); PG8_LDB(B1, 0, 1); PG8_SCHED; PG8_LDA(At, 0, 0); PG8_STAGE(PG8_SA(1, 1), a1 + hstep, voffA);
;             PG8_WAIT_V(8); PG8_WAIT_L(0); PG8_BAR; PG8_MMA(0, 0, At, B0); PG8_MMA(0, 1, At, B1); PG8_BAR; PG8_SCHED;
;             PG8_LDA(At, 0, 1); PG8_STAGE(PG8_SB(0, 0), b2, voffB); PG8_STAGE(PG8_SB(0, 1), b2 + hstep, voffB); PG8_STAGE(PG8_SA(0, 0), a2, voffA);
;             PG8_WAIT_V(8); PG8_WAIT_L(0); PG8_BAR; PG8_MMA(1, 0, At, B0); PG8_MMA(1, 1, At, B1); PG8_BAR; PG8_SCHED;
;             PG8_LDB(B0, 1, 0); PG8_LDB(B1, 1, 1); PG8_SCHED; PG8_LDA(At, 1, 0); PG8_STAGE(PG8_SA(0, 1), a2 + hstep, voffA);
;             PG8_WAIT_V(8); PG8_WAIT_L(0); PG8_BAR; PG8_MMA(0, 0, At, B0); PG8_MMA(0, 1, At, B1); PG8_BAR; PG8_SCHED;
;             PG8_LDA(At, 1, 1); PG8_STAGE(PG8_SB(1, 0), b3, voffB); PG8_STAGE(PG8_SB(1, 1), b3 + hstep, voffB); PG8_STAGE(PG8_SA(1, 0), a3, voffA);
;             PG8_WAIT_V(8); PG8_WAIT_L(0); PG8_BAR; PG8_MMA(1, 0, At, B0); PG8_MMA(1, 1, At, B1); PG8_BAR; PG8_SCHED;
	s_add_u32 s98, s26, 0xfffc0080
	s_addc_u32 s99, s27, -1
	s_add_i32 s26, s51, s2
	s_add_u32 s100, s24, 0x80
	s_addc_u32 s101, s25, 0
	s_mov_b32 m0, s26
	ds_read_b128 v[196:199], v151 offset:49152
	ds_read_b128 v[214:217], v151 offset:50176
	ds_read_b128 v[218:221], v151 offset:51200
	ds_read_b128 v[222:225], v151 offset:52224
	ds_read_b128 v[226:229], v151 offset:53248
	ds_read_b128 v[230:233], v151 offset:54272
	ds_read_b128 v[234:237], v151 offset:55296
	ds_read_b128 v[238:241], v151 offset:56320
	global_load_lds_dwordx4 v0, s[100:101]
	s_add_i32 m0, s26, 0x2000
	s_add_u32 s24, s24, 0x40080
	s_addc_u32 s25, s25, 0
	s_add_i32 s26, s52, s2
	global_load_lds_dwordx4 v130, s[100:101]
	s_mov_b32 m0, s26
	s_nop 0
	global_load_lds_dwordx4 v0, s[24:25]
	s_add_i32 m0, s26, 0x2000
	s_nop 0
	global_load_lds_dwordx4 v130, s[24:25]
	s_mov_b32 m0, s37
	s_nop 0
	global_load_lds_dwordx4 v134, s[98:99]
	s_mov_b32 m0, s38
	s_nop 0
	global_load_lds_dwordx4 v132, s[98:99]
	s_waitcnt vmcnt(8)
	s_waitcnt lgkmcnt(0)
	s_barrier
	s_setprio 1
	s_waitcnt lgkmcnt(0)
	v_mfma_f32_16x16x32_bf16 v[62:65], v[142:145], v[196:199], v[62:65]
	v_mfma_f32_16x16x32_bf16 v[54:57], v[172:175], v[196:199], v[54:57]
	v_mfma_f32_16x16x32_bf16 v[46:49], v[142:145], v[218:221], v[46:49]
	v_mfma_f32_16x16x32_bf16 v[38:41], v[172:175], v[218:221], v[38:41]
	v_mfma_f32_16x16x32_bf16 v[30:33], v[142:145], v[226:229], v[30:33]
	v_mfma_f32_16x16x32_bf16 v[22:25], v[172:175], v[226:229], v[22:25]
	v_mfma_f32_16x16x32_bf16 v[14:17], v[142:145], v[234:237], v[14:17]
	v_mfma_f32_16x16x32_bf16 v[6:9], v[172:175], v[234:237], v[6:9]
	v_mfma_f32_16x16x32_bf16 v[62:65], v[152:155], v[214:217], v[62:65]
	v_mfma_f32_16x16x32_bf16 v[54:57], v[176:179], v[214:217], v[54:57]
	v_mfma_f32_16x16x32_bf16 v[46:49], v[152:155], v[222:225], v[46:49]
	v_mfma_f32_16x16x32_bf16 v[38:41], v[176:179], v[222:225], v[38:41]
	v_mfma_f32_16x16x32_bf16 v[30:33], v[152:155], v[230:233], v[30:33]
	v_mfma_f32_16x16x32_bf16 v[22:25], v[176:179], v[230:233], v[22:25]
	v_mfma_f32_16x16x32_bf16 v[14:17], v[152:155], v[238:241], v[14:17]
	v_mfma_f32_16x16x32_bf16 v[6:9], v[176:179], v[238:241], v[6:9]
	v_mfma_f32_16x16x32_bf16 v[58:61], v[180:183], v[196:199], v[58:61]
	v_mfma_f32_16x16x32_bf16 v[50:53], v[188:191], v[196:199], v[50:53]
	v_mfma_f32_16x16x32_bf16 v[42:45], v[180:183], v[218:221], v[42:45]
	v_mfma_f32_16x16x32_bf16 v[34:37], v[188:191], v[218:221], v[34:37]
	v_mfma_f32_16x16x32_bf16 v[26:29], v[180:183], v[226:229], v[26:29]
	v_mfma_f32_16x16x32_bf16 v[18:21], v[188:191], v[226:229], v[18:21]
	v_mfma_f32_16x16x32_bf16 v[10:13], v[180:183], v[234:237], v[10:13]
	v_mfma_f32_16x16x32_bf16 v[2:5], v[188:191], v[234:237], v[2:5]
	v_mfma_f32_16x16x32_bf16 v[58:61], v[184:187], v[214:217], v[58:61]
	v_mfma_f32_16x16x32_bf16 v[50:53], v[192:195], v[214:217], v[50:53]
	v_mfma_f32_16x16x32_bf16 v[42:45], v[184:187], v[222:225], v[42:45]
	v_mfma_f32_16x16x32_bf16 v[34:37], v[192:195], v[222:225], v[34:37]
	v_mfma_f32_16x16x32_bf16 v[26:29], v[184:187], v[230:233], v[26:29]
	v_mfma_f32_16x16x32_bf16 v[18:21], v[192:195], v[230:233], v[18:21]
	v_mfma_f32_16x16x32_bf16 v[10:13], v[184:187], v[238:241], v[10:13]
	v_mfma_f32_16x16x32_bf16 v[2:5], v[192:195], v[238:241], v[2:5]
	s_setprio 0
	s_barrier
	s_add_i32 s50, s50, 2
	s_add_u32 s22, s22, 0x100
	s_addc_u32 s23, s23, 0
	s_add_u32 s48, s48, 0x100
	s_addc_u32 s49, s49, 0
.LBB0_493:
	s_add_u32 s24, s22, 0xfffc0080
	s_addc_u32 s25, s23, -1
	s_add_i32 s51, 0, 0x10000
	s_cmp_eq_u32 s50, 12
	s_cselect_b32 s27, s17, s25
	s_cselect_b32 s26, s46, s24
	v_add_u32_e32 v146, s51, v149
	s_cselect_b32 s25, s15, s49
	s_cselect_b32 s24, s47, s48
	s_add_i32 s54, 0, 0x14000
	ds_read_b128 v[142:145], v146
	ds_read_b128 v[152:155], v146 offset:1024
	ds_read_b128 v[172:175], v146 offset:2048
	ds_read_b128 v[176:179], v146 offset:3072
	v_add_u32_e32 v146, s54, v149
	ds_read_b128 v[180:183], v146
	ds_read_b128 v[184:187], v146 offset:1024
	ds_read_b128 v[188:191], v146 offset:2048
	ds_read_b128 v[192:195], v146 offset:3072
	s_add_i32 m0, s30, 0xc000
	ds_read_b128 v[196:199], v151
	ds_read_b128 v[214:217], v151 offset:1024
	ds_read_b128 v[218:221], v151 offset:2048
	ds_read_b128 v[222:225], v151 offset:3072
	ds_read_b128 v[226:229], v151 offset:4096
	ds_read_b128 v[230:233], v151 offset:5120
	ds_read_b128 v[234:237], v151 offset:6144
	ds_read_b128 v[238:241], v151 offset:7168
	global_load_lds_dwordx4 v138, s[22:23]
	s_add_i32 m0, s30, 0xe000
	s_nop 0
	global_load_lds_dwordx4 v140, s[22:23]
	s_waitcnt vmcnt(8)
	s_waitcnt lgkmcnt(0)
	s_barrier
; #define PG8_STAGE(bufoff, gbase, voff) do { _Pragma("unroll") for (int _i = 0; _i < 2; ++_i) \
;         __builtin_amdgcn_global_load_lds((const unsigned*)((const char*)(gbase) + (voff)[_i]), (PG8_LAS unsigned*)(lds + (bufoff) + ldsw + _i * 8192), 16, 0, 0); } while (0)
; #define PG8_LDA(dst, b, h) do { _Pragma("unroll") for (int m = 0; m < 4; ++m) _Pragma("unroll") for (int k = 0; k < 2; ++k) dst[m][k] = *(const PG8_LAS bf16x8*)(lds + PG8_SA(b, h) + aoff + m * 2048 + k * 1024); } while (0)
; #define PG8_LDB(dst, b, h) do { _Pragma("unroll") for (int n = 0; n < 2; ++n) _Pragma("unroll") for (int k = 0; k < 2; ++k) dst[n][k] = *(const PG8_LAS bf16x8*)(lds + PG8_SB(b, h) + boff + n * 2048 + k * 1024); } while (0)
; #define PG8_MMA(ai, bj, At, Bt) do { __builtin_amdgcn_s_setprio(1); _Pragma("unroll") for (int m = 0; m < 4; ++m) _Pragma("unroll") for (int n = 0; n < 2; ++n) _Pragma("unroll") for (int k = 0; k < 2; ++k) \
;         acc[ai][bj][m][n] = __builtin_amdgcn_mfma_f32_16x16x32_bf16(Bt[n][k], At[m][k], acc[ai][bj][m][n], 0, 0, 0); __builtin_amdgcn_s_setprio(0); } while (0)
; #define PG8_WAIT_V(n) asm volatile("s_waitcnt vmcnt(" #n ")" ::: "memory")
; #define PG8_WAIT_L(n) asm volatile("s_waitcnt lgkmcnt(" #n ")" ::: "memory")
; #define PG8_BAR __builtin_amdgcn_s_barrier()
; #define PG8_SCHED __builtin_amdgcn_sched_barrier(0)
; template <class Epi, class Sched, bool ALIGN_EPI = false, bool SP2 = false>
; __device__ __forceinline__ void gemm_phase(PG8_LAS unsigned char* lds, const Gemm g, const Sched& S, const Epi& E) {
;     ...
;             PG8_WAIT_V(8); PG8_WAIT_L(0); PG8_BAR; PG8_MMA(0, 0, At, B0); PG8_MMA(0, 1, At, B1); PG8_BAR; PG8_SCHED;
;             PG8_LDA(At, 0, 1); PG8_STAGE(PG8_SB(0, 0), b2, voffB); PG8_STAGE(PG8_SB(0, 1), b2 + hstep, voffB); PG8_STAGE(PG8_SA(0, 0), a2, voffA);
;             PG8_WAIT_V(8); PG8_WAIT_L(0); PG8_BAR; PG8_MMA(1, 0, At, B0); PG8_MMA(1, 1, At, B1); PG8_BAR; PG8_SCHED;
;             PG8_LDB(B0, 1, 0); PG8_LDB(B1, 1, 1); PG8_SCHED; PG8_LDA(At, 1, 0); PG8_STAGE(PG8_SA(0, 1), a2 + hstep, voffA);
;             PG8_WAIT_V(8); PG8_WAIT_L(0); PG8_BAR; PG8_MMA(0, 0, At, B0); PG8_MMA(0, 1, At, B1); PG8_BAR; PG8_SCHED;
	s_setprio 1
	s_waitcnt lgkmcnt(0)
	v_mfma_f32_16x16x32_bf16 v[126:129], v[142:145], v[196:199], v[126:129]
	v_mfma_f32_16x16x32_bf16 v[118:121], v[172:175], v[196:199], v[118:121]
	v_mfma_f32_16x16x32_bf16 v[110:113], v[142:145], v[218:221], v[110:113]
	v_mfma_f32_16x16x32_bf16 v[102:105], v[172:175], v[218:221], v[102:105]
	v_mfma_f32_16x16x32_bf16 v[94:97], v[142:145], v[226:229], v[94:97]
	v_mfma_f32_16x16x32_bf16 v[86:89], v[172:175], v[226:229], v[86:89]
	v_mfma_f32_16x16x32_bf16 v[78:81], v[142:145], v[234:237], v[78:81]
	v_mfma_f32_16x16x32_bf16 v[70:73], v[172:175], v[234:237], v[70:73]
	v_mfma_f32_16x16x32_bf16 v[126:129], v[152:155], v[214:217], v[126:129]
	v_mfma_f32_16x16x32_bf16 v[118:121], v[176:179], v[214:217], v[118:121]
	v_mfma_f32_16x16x32_bf16 v[110:113], v[152:155], v[222:225], v[110:113]
	v_mfma_f32_16x16x32_bf16 v[102:105], v[176:179], v[222:225], v[102:105]
	v_mfma_f32_16x16x32_bf16 v[94:97], v[152:155], v[230:233], v[94:97]
	v_mfma_f32_16x16x32_bf16 v[86:89], v[176:179], v[230:233], v[86:89]
	v_mfma_f32_16x16x32_bf16 v[78:81], v[152:155], v[238:241], v[78:81]
	v_mfma_f32_16x16x32_bf16 v[70:73], v[176:179], v[238:241], v[70:73]
	v_mfma_f32_16x16x32_bf16 v[122:125], v[180:183], v[196:199], v[122:125]
	v_mfma_f32_16x16x32_bf16 v[114:117], v[188:191], v[196:199], v[114:117]
	v_mfma_f32_16x16x32_bf16 v[106:109], v[180:183], v[218:221], v[106:109]
	v_mfma_f32_16x16x32_bf16 v[98:101], v[188:191], v[218:221], v[98:101]
	v_mfma_f32_16x16x32_bf16 v[90:93], v[180:183], v[226:229], v[90:93]
	v_mfma_f32_16x16x32_bf16 v[82:85], v[188:191], v[226:229], v[82:85]
	v_mfma_f32_16x16x32_bf16 v[74:77], v[180:183], v[234:237], v[74:77]
	v_mfma_f32_16x16x32_bf16 v[66:69], v[188:191], v[234:237], v[66:69]
	v_mfma_f32_16x16x32_bf16 v[122:125], v[184:187], v[214:217], v[122:125]
	v_mfma_f32_16x16x32_bf16 v[114:117], v[192:195], v[214:217], v[114:117]
	v_mfma_f32_16x16x32_bf16 v[106:109], v[184:187], v[222:225], v[106:109]
	v_mfma_f32_16x16x32_bf16 v[98:101], v[192:195], v[222:225], v[98:101]
	v_mfma_f32_16x16x32_bf16 v[90:93], v[184:187], v[230:233], v[90:93]
	v_mfma_f32_16x16x32_bf16 v[82:85], v[192:195], v[230:233], v[82:85]
	v_mfma_f32_16x16x32_bf16 v[74:77], v[184:187], v[238:241], v[74:77]
	v_mfma_f32_16x16x32_bf16 v[66:69], v[192:195], v[238:241], v[66:69]
	s_setprio 0
	s_barrier
	s_add_i32 s51, s51, s2
	s_mov_b32 m0, s51
	ds_read_b128 v[196:199], v151 offset:16384
	ds_read_b128 v[214:217], v151 offset:17408
	ds_read_b128 v[218:221], v151 offset:18432
	ds_read_b128 v[222:225], v151 offset:19456
	ds_read_b128 v[226:229], v151 offset:20480
	ds_read_b128 v[230:233], v151 offset:21504
	ds_read_b128 v[234:237], v151 offset:22528
	ds_read_b128 v[238:241], v151 offset:23552
	global_load_lds_dwordx4 v0, s[24:25]
	s_add_i32 m0, s51, 0x2000
	s_add_u32 s52, s24, 0x40000
	s_addc_u32 s53, s25, 0
	s_add_i32 s51, s54, s2
	global_load_lds_dwordx4 v130, s[24:25]
	s_mov_b32 m0, s51
	s_nop 0
	global_load_lds_dwordx4 v0, s[52:53]
	s_add_i32 m0, s51, 0x2000
	s_nop 0
	global_load_lds_dwordx4 v130, s[52:53]
	s_mov_b32 m0, s30
	s_nop 0
	global_load_lds_dwordx4 v134, s[26:27]
	s_mov_b32 m0, s31
	s_nop 0
	global_load_lds_dwordx4 v132, s[26:27]
	s_waitcnt vmcnt(8)
	s_waitcnt lgkmcnt(0)
	s_barrier
	s_setprio 1
	s_waitcnt lgkmcnt(0)
	v_mfma_f32_16x16x32_bf16 v[62:65], v[142:145], v[196:199], v[62:65]
	v_mfma_f32_16x16x32_bf16 v[54:57], v[172:175], v[196:199], v[54:57]
	v_mfma_f32_16x16x32_bf16 v[46:49], v[142:145], v[218:221], v[46:49]
	v_mfma_f32_16x16x32_bf16 v[38:41], v[172:175], v[218:221], v[38:41]
	v_mfma_f32_16x16x32_bf16 v[30:33], v[142:145], v[226:229], v[30:33]
	v_mfma_f32_16x16x32_bf16 v[22:25], v[172:175], v[226:229], v[22:25]
	v_mfma_f32_16x16x32_bf16 v[14:17], v[142:145], v[234:237], v[14:17]
	v_mfma_f32_16x16x32_bf16 v[6:9], v[172:175], v[234:237], v[6:9]
	v_mfma_f32_16x16x32_bf16 v[62:65], v[152:155], v[214:217], v[62:65]
	v_mfma_f32_16x16x32_bf16 v[54:57], v[176:179], v[214:217], v[54:57]
	v_mfma_f32_16x16x32_bf16 v[46:49], v[152:155], v[222:225], v[46:49]
	v_mfma_f32_16x16x32_bf16 v[38:41], v[176:179], v[222:225], v[38:41]
	v_mfma_f32_16x16x32_bf16 v[30:33], v[152:155], v[230:233], v[30:33]
	v_mfma_f32_16x16x32_bf16 v[22:25], v[176:179], v[230:233], v[22:25]
	v_mfma_f32_16x16x32_bf16 v[14:17], v[152:155], v[238:241], v[14:17]
	v_mfma_f32_16x16x32_bf16 v[6:9], v[176:179], v[238:241], v[6:9]
	v_mfma_f32_16x16x32_bf16 v[58:61], v[180:183], v[196:199], v[58:61]
	v_mfma_f32_16x16x32_bf16 v[50:53], v[188:191], v[196:199], v[50:53]
	v_mfma_f32_16x16x32_bf16 v[42:45], v[180:183], v[218:221], v[42:45]
	v_mfma_f32_16x16x32_bf16 v[34:37], v[188:191], v[218:221], v[34:37]
	v_mfma_f32_16x16x32_bf16 v[26:29], v[180:183], v[226:229], v[26:29]
	v_mfma_f32_16x16x32_bf16 v[18:21], v[188:191], v[226:229], v[18:21]
	v_mfma_f32_16x16x32_bf16 v[10:13], v[180:183], v[234:237], v[10:13]
	v_mfma_f32_16x16x32_bf16 v[2:5], v[188:191], v[234:237], v[2:5]
	v_mfma_f32_16x16x32_bf16 v[58:61], v[184:187], v[214:217], v[58:61]
	v_mfma_f32_16x16x32_bf16 v[50:53], v[192:195], v[214:217], v[50:53]
	v_mfma_f32_16x16x32_bf16 v[42:45], v[184:187], v[222:225], v[42:45]
	v_mfma_f32_16x16x32_bf16 v[34:37], v[192:195], v[222:225], v[34:37]
	v_mfma_f32_16x16x32_bf16 v[26:29], v[184:187], v[230:233], v[26:29]
	v_mfma_f32_16x16x32_bf16 v[18:21], v[192:195], v[230:233], v[18:21]
	v_mfma_f32_16x16x32_bf16 v[10:13], v[184:187], v[238:241], v[10:13]
	v_mfma_f32_16x16x32_bf16 v[2:5], v[192:195], v[238:241], v[2:5]
	s_setprio 0
	s_barrier
; #define PG8_STAGE(bufoff, gbase, voff) do { _Pragma("unroll") for (int _i = 0; _i < 2; ++_i) \
;         __builtin_amdgcn_global_load_lds((const unsigned*)((const char*)(gbase) + (voff)[_i]), (PG8_LAS unsigned*)(lds + (bufoff) + ldsw + _i * 8192), 16, 0, 0); } while (0)
; #define PG8_LDA(dst, b, h) do { _Pragma("unroll") for (int m = 0; m < 4; ++m) _Pragma("unroll") for (int k = 0; k < 2; ++k) dst[m][k] = *(const PG8_LAS bf16x8*)(lds + PG8_SA(b, h) + aoff + m * 2048 + k * 1024); } while (0)
; #define PG8_LDB(dst, b, h) do { _Pragma("unroll") for (int n = 0; n < 2; ++n) _Pragma("unroll") for (int k = 0; k < 2; ++k) dst[n][k] = *(const PG8_LAS bf16x8*)(lds + PG8_SB(b, h) + boff + n * 2048 + k * 1024); } while (0)
; #define PG8_MMA(ai, bj, At, Bt) do { __builtin_amdgcn_s_setprio(1); _Pragma("unroll") for (int m = 0; m < 4; ++m) _Pragma("unroll") for (int n = 0; n < 2; ++n) _Pragma("unroll") for (int k = 0; k < 2; ++k) \
;         acc[ai][bj][m][n] = __builtin_amdgcn_mfma_f32_16x16x32_bf16(Bt[n][k], At[m][k], acc[ai][bj][m][n], 0, 0, 0); __builtin_amdgcn_s_setprio(0); } while (0)
; #define PG8_WAIT_V(n) asm volatile("s_waitcnt vmcnt(" #n ")" ::: "memory")
; #define PG8_WAIT_L(n) asm volatile("s_waitcnt lgkmcnt(" #n ")" ::: "memory")
; #define PG8_BAR __builtin_amdgcn_s_barrier()
; #define PG8_SCHED __builtin_amdgcn_sched_barrier(0)
; template <class Epi, class Sched, bool ALIGN_EPI = false, bool SP2 = false>
; __device__ __forceinline__ void gemm_phase(PG8_LAS unsigned char* lds, const Gemm g, const Sched& S, const Epi& E) {
;     ...
;             PG8_LDB(B0, 1, 0); PG8_LDB(B1, 1, 1); PG8_SCHED; PG8_LDA(At, 1, 0); PG8_STAGE(PG8_SA(0, 1), a2 + hstep, voffA);
;             PG8_WAIT_V(8); PG8_WAIT_L(0); PG8_BAR; PG8_MMA(0, 0, At, B0); PG8_MMA(0, 1, At, B1); PG8_BAR; PG8_SCHED;
;             PG8_LDA(At, 1, 1); PG8_STAGE(PG8_SB(1, 0), b3, voffB); PG8_STAGE(PG8_SB(1, 1), b3 + hstep, voffB); PG8_STAGE(PG8_SA(1, 0), a3, voffA);
;             PG8_WAIT_V(8); PG8_WAIT_L(0); PG8_BAR; PG8_MMA(1, 0, At, B0); PG8_MMA(1, 1, At, B1); PG8_BAR; PG8_SCHED;
	s_add_i32 s51, 0, 0x18000
	v_add_u32_e32 v158, s51, v149
	s_add_i32 s52, 0, 0x1c000
	ds_read_b128 v[142:145], v158
	ds_read_b128 v[152:155], v158 offset:1024
	ds_read_b128 v[172:175], v158 offset:2048
	ds_read_b128 v[176:179], v158 offset:3072
	v_add_u32_e32 v158, s52, v149
	ds_read_b128 v[180:183], v158
	ds_read_b128 v[184:187], v158 offset:1024
	ds_read_b128 v[188:191], v158 offset:2048
	ds_read_b128 v[192:195], v158 offset:3072
	s_add_u32 s26, s26, 0x40000
	s_addc_u32 s27, s27, 0
	s_mov_b32 m0, s34
	ds_read_b128 v[196:199], v151 offset:32768
	ds_read_b128 v[214:217], v151 offset:33792
	ds_read_b128 v[218:221], v151 offset:34816
	ds_read_b128 v[222:225], v151 offset:35840
	ds_read_b128 v[226:229], v151 offset:36864
	ds_read_b128 v[230:233], v151 offset:37888
	ds_read_b128 v[234:237], v151 offset:38912
	ds_read_b128 v[238:241], v151 offset:39936
	global_load_lds_dwordx4 v134, s[26:27]
	s_mov_b32 m0, s35
	s_nop 0
	global_load_lds_dwordx4 v132, s[26:27]
	s_waitcnt vmcnt(8)
	s_waitcnt lgkmcnt(0)
	s_barrier
	s_setprio 1
	s_waitcnt lgkmcnt(0)
	v_mfma_f32_16x16x32_bf16 v[126:129], v[142:145], v[196:199], v[126:129]
	v_mfma_f32_16x16x32_bf16 v[118:121], v[172:175], v[196:199], v[118:121]
	v_mfma_f32_16x16x32_bf16 v[110:113], v[142:145], v[218:221], v[110:113]
	v_mfma_f32_16x16x32_bf16 v[102:105], v[172:175], v[218:221], v[102:105]
	v_mfma_f32_16x16x32_bf16 v[94:97], v[142:145], v[226:229], v[94:97]
	v_mfma_f32_16x16x32_bf16 v[86:89], v[172:175], v[226:229], v[86:89]
	v_mfma_f32_16x16x32_bf16 v[78:81], v[142:145], v[234:237], v[78:81]
	v_mfma_f32_16x16x32_bf16 v[70:73], v[172:175], v[234:237], v[70:73]
	v_mfma_f32_16x16x32_bf16 v[126:129], v[152:155], v[214:217], v[126:129]
	v_mfma_f32_16x16x32_bf16 v[118:121], v[176:179], v[214:217], v[118:121]
	v_mfma_f32_16x16x32_bf16 v[110:113], v[152:155], v[222:225], v[110:113]
	v_mfma_f32_16x16x32_bf16 v[102:105], v[176:179], v[222:225], v[102:105]
	v_mfma_f32_16x16x32_bf16 v[94:97], v[152:155], v[230:233], v[94:97]
	v_mfma_f32_16x16x32_bf16 v[86:89], v[176:179], v[230:233], v[86:89]
	v_mfma_f32_16x16x32_bf16 v[78:81], v[152:155], v[238:241], v[78:81]
	v_mfma_f32_16x16x32_bf16 v[70:73], v[176:179], v[238:241], v[70:73]
	v_mfma_f32_16x16x32_bf16 v[122:125], v[180:183], v[196:199], v[122:125]
	v_mfma_f32_16x16x32_bf16 v[114:117], v[188:191], v[196:199], v[114:117]
	v_mfma_f32_16x16x32_bf16 v[106:109], v[180:183], v[218:221], v[106:109]
	v_mfma_f32_16x16x32_bf16 v[98:101], v[188:191], v[218:221], v[98:101]
	v_mfma_f32_16x16x32_bf16 v[90:93], v[180:183], v[226:229], v[90:93]
	v_mfma_f32_16x16x32_bf16 v[82:85], v[188:191], v[226:229], v[82:85]
	v_mfma_f32_16x16x32_bf16 v[74:77], v[180:183], v[234:237], v[74:77]
	v_mfma_f32_16x16x32_bf16 v[66:69], v[188:191], v[234:237], v[66:69]
	v_mfma_f32_16x16x32_bf16 v[122:125], v[184:187], v[214:217], v[122:125]
	v_mfma_f32_16x16x32_bf16 v[114:117], v[192:195], v[214:217], v[114:117]
	v_mfma_f32_16x16x32_bf16 v[106:109], v[184:187], v[222:225], v[106:109]
	v_mfma_f32_16x16x32_bf16 v[98:101], v[192:195], v[222:225], v[98:101]
	v_mfma_f32_16x16x32_bf16 v[90:93], v[184:187], v[230:233], v[90:93]
	v_mfma_f32_16x16x32_bf16 v[82:85], v[192:195], v[230:233], v[82:85]
	v_mfma_f32_16x16x32_bf16 v[74:77], v[184:187], v[238:241], v[74:77]
	v_mfma_f32_16x16x32_bf16 v[66:69], v[192:195], v[238:241], v[66:69]
	s_setprio 0
	s_barrier
	s_add_u32 s98, s26, 0xfffc0080
	s_addc_u32 s99, s27, -1
	s_add_i32 s26, s51, s2
	s_add_u32 s100, s24, 0x80
	s_addc_u32 s101, s25, 0
	s_mov_b32 m0, s26
	ds_read_b128 v[196:199], v151 offset:49152
	ds_read_b128 v[214:217], v151 offset:50176
	ds_read_b128 v[218:221], v151 offset:51200
	ds_read_b128 v[222:225], v151 offset:52224
	ds_read_b128 v[226:229], v151 offset:53248
	ds_read_b128 v[230:233], v151 offset:54272
	ds_read_b128 v[234:237], v151 offset:55296
	ds_read_b128 v[238:241], v151 offset:56320
	global_load_lds_dwordx4 v0, s[100:101]
	s_add_i32 m0, s26, 0x2000
	s_add_u32 s24, s24, 0x40080
	s_addc_u32 s25, s25, 0
	s_add_i32 s26, s52, s2
	global_load_lds_dwordx4 v130, s[100:101]
	s_mov_b32 m0, s26
	s_nop 0
	global_load_lds_dwordx4 v0, s[24:25]
	s_add_i32 m0, s26, 0x2000
	s_nop 0
	global_load_lds_dwordx4 v130, s[24:25]
	s_mov_b32 m0, s37
	s_nop 0
	global_load_lds_dwordx4 v134, s[98:99]
	s_mov_b32 m0, s38
	s_nop 0
	global_load_lds_dwordx4 v132, s[98:99]
	s_waitcnt vmcnt(8)
	s_waitcnt lgkmcnt(0)
	s_barrier
; #define PG8_MMA(ai, bj, At, Bt) do { __builtin_amdgcn_s_setprio(1); _Pragma("unroll") for (int m = 0; m < 4; ++m) _Pragma("unroll") for (int n = 0; n < 2; ++n) _Pragma("unroll") for (int k = 0; k < 2; ++k) \
;         acc[ai][bj][m][n] = __builtin_amdgcn_mfma_f32_16x16x32_bf16(Bt[n][k], At[m][k], acc[ai][bj][m][n], 0, 0, 0); __builtin_amdgcn_s_setprio(0); } while (0)
; #define PG8_WAIT_V(n) asm volatile("s_waitcnt vmcnt(" #n ")" ::: "memory")
; #define PG8_WAIT_L(n) asm volatile("s_waitcnt lgkmcnt(" #n ")" ::: "memory")
; #define PG8_BAR __builtin_amdgcn_s_barrier()
; #define PG8_SCHED __builtin_amdgcn_sched_barrier(0)
; template <class Epi, class Sched, bool ALIGN_EPI = false, bool SP2 = false>
; __device__ __forceinline__ void gemm_phase(PG8_LAS unsigned char* lds, const Gemm g, const Sched& S, const Epi& E) {
;     ...
;             PG8_WAIT_V(8); PG8_WAIT_L(0); PG8_BAR; PG8_MMA(1, 0, At, B0); PG8_MMA(1, 1, At, B1); PG8_BAR; PG8_SCHED;
; __device__ __forceinline__ float row_rstd(const float* rsp, int row, int fq) {
;     const f32x4 v = *(const f32x4*)(rsp + (size_t)row * 16 + 4 * fq);
;     float s = (v[0] + v[1]) + (v[2] + v[3]); s += __shfl_xor(s, 16); s += __shfl_xor(s, 32);
;     return rsqrtf(s * (1.0f / 1024.0f) + RMS_EPS);
; }
;     __device__ __forceinline__ void operator()(const f32x4 (&acc)[2][2][4][2], const Unit& u, int wr, int wc, int fr, int fq) const {
;         const int row0 = u.pm * BM + wr * 64 + fr, col0 = u.pn * HALF + wc * 32 + 8 * fq;
; #pragma unroll
;         for (int ai = 0; ai < 2; ++ai)
; #pragma unroll
;             for (int m = 0; m < 4; ++m) {
;                 const int row = row0 + ai * HALF + m * 16; const float rs = row_rstd(rsp, row, fq);
	s_setprio 1
	s_waitcnt lgkmcnt(0)
	v_mfma_f32_16x16x32_bf16 v[62:65], v[142:145], v[196:199], v[62:65]
	v_mfma_f32_16x16x32_bf16 v[54:57], v[172:175], v[196:199], v[54:57]
	v_mfma_f32_16x16x32_bf16 v[46:49], v[142:145], v[218:221], v[46:49]
	v_mfma_f32_16x16x32_bf16 v[38:41], v[172:175], v[218:221], v[38:41]
	v_mfma_f32_16x16x32_bf16 v[30:33], v[142:145], v[226:229], v[30:33]
	v_mfma_f32_16x16x32_bf16 v[22:25], v[172:175], v[226:229], v[22:25]
	v_mfma_f32_16x16x32_bf16 v[14:17], v[142:145], v[234:237], v[14:17]
	v_mfma_f32_16x16x32_bf16 v[6:9], v[172:175], v[234:237], v[6:9]
	v_mfma_f32_16x16x32_bf16 v[62:65], v[152:155], v[214:217], v[62:65]
	v_mfma_f32_16x16x32_bf16 v[54:57], v[176:179], v[214:217], v[54:57]
	v_mfma_f32_16x16x32_bf16 v[46:49], v[152:155], v[222:225], v[46:49]
	v_mfma_f32_16x16x32_bf16 v[38:41], v[176:179], v[222:225], v[38:41]
	v_mfma_f32_16x16x32_bf16 v[30:33], v[152:155], v[230:233], v[30:33]
	v_mfma_f32_16x16x32_bf16 v[22:25], v[176:179], v[230:233], v[22:25]
	v_mfma_f32_16x16x32_bf16 v[14:17], v[152:155], v[238:241], v[14:17]
	v_mfma_f32_16x16x32_bf16 v[6:9], v[176:179], v[238:241], v[6:9]
	v_mfma_f32_16x16x32_bf16 v[58:61], v[180:183], v[196:199], v[58:61]
	v_mfma_f32_16x16x32_bf16 v[50:53], v[188:191], v[196:199], v[50:53]
	v_mfma_f32_16x16x32_bf16 v[42:45], v[180:183], v[218:221], v[42:45]
	v_mfma_f32_16x16x32_bf16 v[34:37], v[188:191], v[218:221], v[34:37]
	v_mfma_f32_16x16x32_bf16 v[26:29], v[180:183], v[226:229], v[26:29]
	v_mfma_f32_16x16x32_bf16 v[18:21], v[188:191], v[226:229], v[18:21]
	v_mfma_f32_16x16x32_bf16 v[10:13], v[180:183], v[234:237], v[10:13]
	v_mfma_f32_16x16x32_bf16 v[2:5], v[188:191], v[234:237], v[2:5]
	v_mfma_f32_16x16x32_bf16 v[58:61], v[184:187], v[214:217], v[58:61]
	v_mfma_f32_16x16x32_bf16 v[50:53], v[192:195], v[214:217], v[50:53]
	v_mfma_f32_16x16x32_bf16 v[42:45], v[184:187], v[222:225], v[42:45]
	v_mfma_f32_16x16x32_bf16 v[34:37], v[192:195], v[222:225], v[34:37]
	v_mfma_f32_16x16x32_bf16 v[26:29], v[184:187], v[230:233], v[26:29]
	v_mfma_f32_16x16x32_bf16 v[18:21], v[192:195], v[230:233], v[18:21]
	v_mfma_f32_16x16x32_bf16 v[10:13], v[184:187], v[238:241], v[10:13]
	v_mfma_f32_16x16x32_bf16 v[2:5], v[192:195], v[238:241], v[2:5]
	s_setprio 0
	s_barrier
	s_add_i32 s50, s50, 2
	s_add_u32 s22, s22, 0x100
	s_addc_u32 s23, s23, 0
	s_add_u32 s48, s48, 0x100
	s_addc_u32 s49, s49, 0
	s_cmp_gt_u32 s50, 13
	s_cbranch_scc0 .LBB0_493
	v_lshl_add_u32 v142, s45, 8, v148
	v_mov_b32_e32 v143, 0
	s_mov_b32 s26, 0x2000
	s_mov_b32 s27, 0
	v_lshlrev_b64 v[146:147], 6, v[142:143]
	v_lshl_add_u64 v[146:147], v[136:137], 0, v[146:147]
	v_lshl_add_u64 v[156:157], v[146:147], 0, s[26:27]
	global_load_dwordx4 v[172:175], v[146:147], off
	global_load_dwordx4 v[176:179], v[146:147], off offset:1024
	global_load_dwordx4 v[180:183], v[146:147], off offset:2048
	global_load_dwordx4 v[184:187], v[146:147], off offset:3072
	global_load_dwordx4 v[188:191], v[156:157], off
	global_load_dwordx4 v[192:195], v[156:157], off offset:1024
	global_load_dwordx4 v[196:199], v[156:157], off offset:2048
	global_load_dwordx4 v[214:217], v[156:157], off offset:3072
	v_xor_b32_e32 v152, 16, v201
	v_xor_b32_e32 v153, 32, v201
	v_lshlrev_b32_e32 v152, 2, v152
	v_lshlrev_b32_e32 v153, 2, v153
	v_lshl_or_b32 v144, s44, 7, v150
	v_mov_b32_e32 v145, 0
	v_mov_b32_e32 v238, s0
	v_mov_b32_e32 v239, s1
	v_mad_i64_i32 v[236:237], s[22:23], v142, s93, v[238:239]
	v_lshlrev_b64 v[240:241], 1, v[144:145]
	v_mov_b32_e32 v234, 1.0
	v_mov_b32_e32 v235, 1.0
	v_lshl_add_u64 v[236:237], v[236:237], 0, v[240:241]
	s_mov_b32 s26, 0x16000
	s_mov_b32 s24, 0x6e000
	s_mov_b32 s25, 0
	s_and_b64 vcc, exec, s[12:13]
	s_cbranch_vccz .LBB0_496
	s_barrier
